# doc 7.11 on the nine GEMM K-loops: loop-carried updates and exit test moved in front of the loop-back barrier
# baseline (speedup 1.0000x reference)
; #define PG8_STAGE(bufoff, gbase, voff) do { _Pragma("unroll") for (int _i = 0; _i < 2; ++_i) \
;         __builtin_amdgcn_global_load_lds((const unsigned*)((const char*)(gbase) + (voff)[_i]), (PG8_LAS unsigned*)(lds + (bufoff) + ldsw + _i * 8192), 16, 0, 0); } while (0)
; #define PG8_LDA(dst, b, h) do { _Pragma("unroll") for (int m = 0; m < 4; ++m) _Pragma("unroll") for (int k = 0; k < 2; ++k) dst[m][k] = *(const PG8_LAS bf16x8*)(lds + PG8_SA(b, h) + aoff + m * 2048 + k * 1024); } while (0)
; #define PG8_LDB(dst, b, h) do { _Pragma("unroll") for (int n = 0; n < 2; ++n) _Pragma("unroll") for (int k = 0; k < 2; ++k) dst[n][k] = *(const PG8_LAS bf16x8*)(lds + PG8_SB(b, h) + boff + n * 2048 + k * 1024); } while (0)
; #define PG8_MMA(ai, bj, At, Bt) do { __builtin_amdgcn_s_setprio(1); _Pragma("unroll") for (int m = 0; m < 4; ++m) _Pragma("unroll") for (int n = 0; n < 2; ++n) _Pragma("unroll") for (int k = 0; k < 2; ++k) \
;         acc[ai][bj][m][n] = __builtin_amdgcn_mfma_f32_16x16x32_bf16(Bt[n][k], At[m][k], acc[ai][bj][m][n], 0, 0, 0); __builtin_amdgcn_s_setprio(0); } while (0)
; #define PG8_WAIT_V(n) asm volatile("s_waitcnt vmcnt(" #n ")" ::: "memory")
; #define PG8_WAIT_L(n) asm volatile("s_waitcnt lgkmcnt(" #n ")" ::: "memory")
; #define PG8_BAR __builtin_amdgcn_s_barrier()
; #define PG8_SCHED __builtin_amdgcn_sched_barrier(0)
; template <class Epi, class Sched, bool ALIGN_EPI = false, bool SP2 = false>
; __device__ __forceinline__ void gemm_phase(PG8_LAS unsigned char* lds, const Gemm g, const Sched& S, const Epi& E) {
;     ...
;         for (int t = 0; t < nt; t += 2) {
;             const bool last = (t == nt - 2);
;             const char* a1 = cA + (size_t)(t + 1) * kstep;
;             const char* a2 = last ? nA : cA + (size_t)(t + 2) * kstep; const char* b2 = last ? nB : cB + (size_t)(t + 2) * kstep;
;             const char* a3 = a2 + kstep; const char* b3 = b2 + kstep;
;             if (last && has_next) S.a_ready(nxt);
;             if constexpr (SP2) {
;             PG8_LDB(B0, 0, 0); PG8_LDB(B1, 0, 1); PG8_SCHED; PG8_LDA(At, 0, 0); PG8_STAGE(PG8_SA(1, 1), a1 + hstepA, voffA);
;             PG8_WAIT_V(8); PG8_WAIT_L(0); PG8_BAR; PG8_MMA(0, 0, At, B0); PG8_MMA(0, 1, At, B1); PG8_BAR; PG8_SCHED;
;             PG8_LDA(At, 0, 1); PG8_STAGE(PG8_SB(0, 0), b2, voffB); PG8_STAGE(PG8_SB(0, 1), b2 + hstepB, voffB); PG8_STAGE(PG8_SA(0, 0), a2, voffA);
.LBB0_197:
	ds_read_b128 v[130:133], v180
	ds_read_b128 v[134:137], v180 offset:1024
	ds_read_b128 v[138:141], v180 offset:2048
	ds_read_b128 v[142:145], v180 offset:3072
	ds_read_b128 v[168:171], v181
	ds_read_b128 v[188:191], v181 offset:1024
	ds_read_b128 v[192:195], v181 offset:2048
	ds_read_b128 v[196:199], v181 offset:3072
	s_add_u32 s8, s6, 0xfffc0080
	s_addc_u32 s9, s7, -1
	s_cmp_eq_u32 s41, 12
	s_cselect_b32 s47, s11, s9
	s_cselect_b32 s46, s13, s8
	s_cselect_b32 s9, s33, s39
	s_cselect_b32 s8, s37, s38
	v_lshl_add_u64 v[172:173], s[6:7], 0, v[158:159]
	s_add_i32 m0, s59, 0xc000
	ds_read_b128 v[200:203], v182
	ds_read_b128 v[204:207], v182 offset:1024
	ds_read_b128 v[208:211], v182 offset:2048
	ds_read_b128 v[212:215], v182 offset:3072
	ds_read_b128 v[220:223], v182 offset:4096
	ds_read_b128 v[224:227], v182 offset:5120
	ds_read_b128 v[228:231], v182 offset:6144
	ds_read_b128 v[232:235], v182 offset:7168
	global_load_lds_dwordx4 v[172:173], off
	v_lshl_add_u64 v[172:173], s[6:7], 0, v[160:161]
	s_add_i32 m0, s59, 0xe000
	s_nop 0
	global_load_lds_dwordx4 v[172:173], off
	s_waitcnt vmcnt(8)
	s_waitcnt lgkmcnt(0)
	s_barrier
	s_setprio 1
	s_waitcnt lgkmcnt(0)
	v_mfma_f32_16x16x32_bf16 v[126:129], v[130:133], v[200:203], v[126:129]
	v_mfma_f32_16x16x32_bf16 v[122:125], v[138:141], v[200:203], v[122:125]
	v_mfma_f32_16x16x32_bf16 v[110:113], v[130:133], v[208:211], v[110:113]
	v_mfma_f32_16x16x32_bf16 v[106:109], v[138:141], v[208:211], v[106:109]
	v_mfma_f32_16x16x32_bf16 v[94:97], v[130:133], v[220:223], v[94:97]
	v_mfma_f32_16x16x32_bf16 v[90:93], v[138:141], v[220:223], v[90:93]
	v_mfma_f32_16x16x32_bf16 v[78:81], v[130:133], v[228:231], v[78:81]
	v_mfma_f32_16x16x32_bf16 v[74:77], v[138:141], v[228:231], v[74:77]
	v_mfma_f32_16x16x32_bf16 v[126:129], v[134:137], v[204:207], v[126:129]
	v_mfma_f32_16x16x32_bf16 v[122:125], v[142:145], v[204:207], v[122:125]
	v_mfma_f32_16x16x32_bf16 v[110:113], v[134:137], v[212:215], v[110:113]
	v_mfma_f32_16x16x32_bf16 v[106:109], v[142:145], v[212:215], v[106:109]
	v_mfma_f32_16x16x32_bf16 v[94:97], v[134:137], v[224:227], v[94:97]
	v_mfma_f32_16x16x32_bf16 v[90:93], v[142:145], v[224:227], v[90:93]
	v_mfma_f32_16x16x32_bf16 v[78:81], v[134:137], v[232:235], v[78:81]
	v_mfma_f32_16x16x32_bf16 v[74:77], v[142:145], v[232:235], v[74:77]
	s_setprio 0
	s_setprio 1
	v_mfma_f32_16x16x32_bf16 v[118:121], v[168:171], v[200:203], v[118:121]
	v_mfma_f32_16x16x32_bf16 v[114:117], v[192:195], v[200:203], v[114:117]
	v_mfma_f32_16x16x32_bf16 v[102:105], v[168:171], v[208:211], v[102:105]
	v_mfma_f32_16x16x32_bf16 v[98:101], v[192:195], v[208:211], v[98:101]
	v_mfma_f32_16x16x32_bf16 v[86:89], v[168:171], v[220:223], v[86:89]
	v_mfma_f32_16x16x32_bf16 v[82:85], v[192:195], v[220:223], v[82:85]
	v_mfma_f32_16x16x32_bf16 v[70:73], v[168:171], v[228:231], v[70:73]
	v_mfma_f32_16x16x32_bf16 v[66:69], v[192:195], v[228:231], v[66:69]
	v_mfma_f32_16x16x32_bf16 v[118:121], v[188:191], v[204:207], v[118:121]
	v_mfma_f32_16x16x32_bf16 v[114:117], v[196:199], v[204:207], v[114:117]
	v_mfma_f32_16x16x32_bf16 v[102:105], v[188:191], v[212:215], v[102:105]
	v_mfma_f32_16x16x32_bf16 v[98:101], v[196:199], v[212:215], v[98:101]
	v_mfma_f32_16x16x32_bf16 v[86:89], v[188:191], v[224:227], v[86:89]
	v_mfma_f32_16x16x32_bf16 v[82:85], v[196:199], v[224:227], v[82:85]
	v_mfma_f32_16x16x32_bf16 v[70:73], v[188:191], v[232:235], v[70:73]
	v_mfma_f32_16x16x32_bf16 v[66:69], v[196:199], v[232:235], v[66:69]
	s_setprio 0
	s_barrier
	s_add_i32 s48, s78, s55
	v_lshl_add_u64 v[172:173], s[8:9], 0, v[148:149]
	s_mov_b32 m0, s48
	ds_read_b128 v[200:203], v182 offset:16384
	ds_read_b128 v[204:207], v182 offset:17408
	ds_read_b128 v[208:211], v182 offset:18432
	ds_read_b128 v[212:215], v182 offset:19456
	ds_read_b128 v[220:223], v182 offset:20480
	ds_read_b128 v[224:227], v182 offset:21504
	ds_read_b128 v[228:231], v182 offset:22528
	ds_read_b128 v[232:235], v182 offset:23552
	global_load_lds_dwordx4 v[172:173], off
	s_add_i32 m0, s48, 0x2000
	s_add_u32 s48, s8, 0x40000
	v_lshl_add_u64 v[178:179], s[8:9], 0, v[152:153]
	s_addc_u32 s49, s9, 0
	s_add_i32 s50, s79, s55
	global_load_lds_dwordx4 v[178:179], off
	v_lshl_add_u64 v[216:217], s[48:49], 0, v[148:149]
	s_mov_b32 m0, s50
	v_lshl_add_u64 v[236:237], s[46:47], 0, v[150:151]
	global_load_lds_dwordx4 v[216:217], off
	v_lshl_add_u64 v[216:217], s[48:49], 0, v[152:153]
	s_add_i32 m0, s50, 0x2000
	s_nop 0
	global_load_lds_dwordx4 v[216:217], off
	v_lshl_add_u64 v[216:217], s[46:47], 0, v[146:147]
	s_mov_b32 m0, s59
	s_nop 0
	global_load_lds_dwordx4 v[216:217], off
	s_mov_b32 m0, s60
	s_nop 0
	global_load_lds_dwordx4 v[236:237], off
	s_waitcnt vmcnt(8)
	s_waitcnt lgkmcnt(0)
	s_barrier
; #define PG8_STAGE(bufoff, gbase, voff) do { _Pragma("unroll") for (int _i = 0; _i < 2; ++_i) \
;         __builtin_amdgcn_global_load_lds((const unsigned*)((const char*)(gbase) + (voff)[_i]), (PG8_LAS unsigned*)(lds + (bufoff) + ldsw + _i * 8192), 16, 0, 0); } while (0)
; #define PG8_LDA(dst, b, h) do { _Pragma("unroll") for (int m = 0; m < 4; ++m) _Pragma("unroll") for (int k = 0; k < 2; ++k) dst[m][k] = *(const PG8_LAS bf16x8*)(lds + PG8_SA(b, h) + aoff + m * 2048 + k * 1024); } while (0)
; #define PG8_LDB(dst, b, h) do { _Pragma("unroll") for (int n = 0; n < 2; ++n) _Pragma("unroll") for (int k = 0; k < 2; ++k) dst[n][k] = *(const PG8_LAS bf16x8*)(lds + PG8_SB(b, h) + boff + n * 2048 + k * 1024); } while (0)
; #define PG8_MMA(ai, bj, At, Bt) do { __builtin_amdgcn_s_setprio(1); _Pragma("unroll") for (int m = 0; m < 4; ++m) _Pragma("unroll") for (int n = 0; n < 2; ++n) _Pragma("unroll") for (int k = 0; k < 2; ++k) \
;         acc[ai][bj][m][n] = __builtin_amdgcn_mfma_f32_16x16x32_bf16(Bt[n][k], At[m][k], acc[ai][bj][m][n], 0, 0, 0); __builtin_amdgcn_s_setprio(0); } while (0)
; #define PG8_WAIT_V(n) asm volatile("s_waitcnt vmcnt(" #n ")" ::: "memory")
; #define PG8_WAIT_L(n) asm volatile("s_waitcnt lgkmcnt(" #n ")" ::: "memory")
; #define PG8_BAR __builtin_amdgcn_s_barrier()
; #define PG8_SCHED __builtin_amdgcn_sched_barrier(0)
; template <class Epi, class Sched, bool ALIGN_EPI = false, bool SP2 = false>
; __device__ __forceinline__ void gemm_phase(PG8_LAS unsigned char* lds, const Gemm g, const Sched& S, const Epi& E) {
;     ...
;             PG8_WAIT_V(8); PG8_WAIT_L(0); PG8_BAR; PG8_MMA(1, 0, At, B0); PG8_MMA(1, 1, At, B1); PG8_BAR; PG8_SCHED;
;             PG8_LDB(B0, 1, 0); PG8_LDB(B1, 1, 1); PG8_SCHED; PG8_LDA(At, 1, 0); PG8_STAGE(PG8_SA(0, 1), a2 + hstepA, voffA);
;             PG8_WAIT_V(8); PG8_WAIT_L(0); PG8_BAR; PG8_MMA(0, 0, At, B0); PG8_MMA(0, 1, At, B1); PG8_BAR; PG8_SCHED;
	s_setprio 1
	s_waitcnt lgkmcnt(0)
	v_mfma_f32_16x16x32_bf16 v[62:65], v[130:133], v[200:203], v[62:65]
	v_mfma_f32_16x16x32_bf16 v[58:61], v[138:141], v[200:203], v[58:61]
	v_mfma_f32_16x16x32_bf16 v[46:49], v[130:133], v[208:211], v[46:49]
	v_mfma_f32_16x16x32_bf16 v[42:45], v[138:141], v[208:211], v[42:45]
	v_mfma_f32_16x16x32_bf16 v[30:33], v[130:133], v[220:223], v[30:33]
	v_mfma_f32_16x16x32_bf16 v[26:29], v[138:141], v[220:223], v[26:29]
	v_mfma_f32_16x16x32_bf16 v[14:17], v[130:133], v[228:231], v[14:17]
	v_mfma_f32_16x16x32_bf16 v[10:13], v[138:141], v[228:231], v[10:13]
	v_mfma_f32_16x16x32_bf16 v[62:65], v[134:137], v[204:207], v[62:65]
	v_mfma_f32_16x16x32_bf16 v[58:61], v[142:145], v[204:207], v[58:61]
	v_mfma_f32_16x16x32_bf16 v[46:49], v[134:137], v[212:215], v[46:49]
	v_mfma_f32_16x16x32_bf16 v[42:45], v[142:145], v[212:215], v[42:45]
	v_mfma_f32_16x16x32_bf16 v[30:33], v[134:137], v[224:227], v[30:33]
	v_mfma_f32_16x16x32_bf16 v[26:29], v[142:145], v[224:227], v[26:29]
	v_mfma_f32_16x16x32_bf16 v[14:17], v[134:137], v[232:235], v[14:17]
	v_mfma_f32_16x16x32_bf16 v[10:13], v[142:145], v[232:235], v[10:13]
	s_setprio 0
	s_setprio 1
	v_mfma_f32_16x16x32_bf16 v[54:57], v[168:171], v[200:203], v[54:57]
	v_mfma_f32_16x16x32_bf16 v[50:53], v[192:195], v[200:203], v[50:53]
	v_mfma_f32_16x16x32_bf16 v[38:41], v[168:171], v[208:211], v[38:41]
	v_mfma_f32_16x16x32_bf16 v[34:37], v[192:195], v[208:211], v[34:37]
	v_mfma_f32_16x16x32_bf16 v[22:25], v[168:171], v[220:223], v[22:25]
	v_mfma_f32_16x16x32_bf16 v[18:21], v[192:195], v[220:223], v[18:21]
	v_mfma_f32_16x16x32_bf16 v[6:9], v[168:171], v[228:231], v[6:9]
	v_mfma_f32_16x16x32_bf16 v[2:5], v[192:195], v[228:231], v[2:5]
	v_mfma_f32_16x16x32_bf16 v[54:57], v[188:191], v[204:207], v[54:57]
	v_mfma_f32_16x16x32_bf16 v[50:53], v[196:199], v[204:207], v[50:53]
	v_mfma_f32_16x16x32_bf16 v[38:41], v[188:191], v[212:215], v[38:41]
	v_mfma_f32_16x16x32_bf16 v[34:37], v[196:199], v[212:215], v[34:37]
	v_mfma_f32_16x16x32_bf16 v[22:25], v[188:191], v[224:227], v[22:25]
	v_mfma_f32_16x16x32_bf16 v[18:21], v[196:199], v[224:227], v[18:21]
	v_mfma_f32_16x16x32_bf16 v[6:9], v[188:191], v[232:235], v[6:9]
	v_mfma_f32_16x16x32_bf16 v[2:5], v[196:199], v[232:235], v[2:5]
	s_setprio 0
	s_barrier
	s_add_i32 s48, 0, 0x18000
	s_add_i32 s49, 0, 0x1c000
	v_add_u32_e32 v142, s48, v177
	v_add_u32_e32 v154, s49, v177
	ds_read_b128 v[130:133], v142
	ds_read_b128 v[134:137], v142 offset:1024
	ds_read_b128 v[138:141], v142 offset:2048
	ds_read_b128 v[142:145], v142 offset:3072
	ds_read_b128 v[168:171], v154
	ds_read_b128 v[188:191], v154 offset:1024
	ds_read_b128 v[192:195], v154 offset:2048
	ds_read_b128 v[196:199], v154 offset:3072
	s_add_u32 s46, s46, 0x40000
	s_addc_u32 s47, s47, 0
	s_mov_b32 m0, s61
	v_lshl_add_u64 v[238:239], s[46:47], 0, v[146:147]
	ds_read_b128 v[200:203], v182 offset:32768
	ds_read_b128 v[204:207], v182 offset:33792
	ds_read_b128 v[208:211], v182 offset:34816
	ds_read_b128 v[212:215], v182 offset:35840
	ds_read_b128 v[220:223], v182 offset:36864
	ds_read_b128 v[224:227], v182 offset:37888
	ds_read_b128 v[228:231], v182 offset:38912
	ds_read_b128 v[232:235], v182 offset:39936
	global_load_lds_dwordx4 v[238:239], off
	v_lshl_add_u64 v[238:239], s[46:47], 0, v[150:151]
	s_mov_b32 m0, s62
	s_nop 0
	global_load_lds_dwordx4 v[238:239], off
	s_waitcnt vmcnt(8)
	s_waitcnt lgkmcnt(0)
	s_barrier
	s_setprio 1
	s_waitcnt lgkmcnt(0)
	v_mfma_f32_16x16x32_bf16 v[126:129], v[130:133], v[200:203], v[126:129]
	v_mfma_f32_16x16x32_bf16 v[122:125], v[138:141], v[200:203], v[122:125]
	v_mfma_f32_16x16x32_bf16 v[110:113], v[130:133], v[208:211], v[110:113]
	v_mfma_f32_16x16x32_bf16 v[106:109], v[138:141], v[208:211], v[106:109]
	v_mfma_f32_16x16x32_bf16 v[94:97], v[130:133], v[220:223], v[94:97]
	v_mfma_f32_16x16x32_bf16 v[90:93], v[138:141], v[220:223], v[90:93]
	v_mfma_f32_16x16x32_bf16 v[78:81], v[130:133], v[228:231], v[78:81]
	v_mfma_f32_16x16x32_bf16 v[74:77], v[138:141], v[228:231], v[74:77]
	v_mfma_f32_16x16x32_bf16 v[126:129], v[134:137], v[204:207], v[126:129]
	v_mfma_f32_16x16x32_bf16 v[122:125], v[142:145], v[204:207], v[122:125]
	v_mfma_f32_16x16x32_bf16 v[110:113], v[134:137], v[212:215], v[110:113]
	v_mfma_f32_16x16x32_bf16 v[106:109], v[142:145], v[212:215], v[106:109]
	v_mfma_f32_16x16x32_bf16 v[94:97], v[134:137], v[224:227], v[94:97]
	v_mfma_f32_16x16x32_bf16 v[90:93], v[142:145], v[224:227], v[90:93]
	v_mfma_f32_16x16x32_bf16 v[78:81], v[134:137], v[232:235], v[78:81]
	v_mfma_f32_16x16x32_bf16 v[74:77], v[142:145], v[232:235], v[74:77]
	s_setprio 0
	s_setprio 1
	v_mfma_f32_16x16x32_bf16 v[118:121], v[168:171], v[200:203], v[118:121]
	v_mfma_f32_16x16x32_bf16 v[114:117], v[192:195], v[200:203], v[114:117]
	v_mfma_f32_16x16x32_bf16 v[102:105], v[168:171], v[208:211], v[102:105]
	v_mfma_f32_16x16x32_bf16 v[98:101], v[192:195], v[208:211], v[98:101]
	v_mfma_f32_16x16x32_bf16 v[86:89], v[168:171], v[220:223], v[86:89]
	v_mfma_f32_16x16x32_bf16 v[82:85], v[192:195], v[220:223], v[82:85]
	v_mfma_f32_16x16x32_bf16 v[70:73], v[168:171], v[228:231], v[70:73]
	v_mfma_f32_16x16x32_bf16 v[66:69], v[192:195], v[228:231], v[66:69]
	v_mfma_f32_16x16x32_bf16 v[118:121], v[188:191], v[204:207], v[118:121]
	v_mfma_f32_16x16x32_bf16 v[114:117], v[196:199], v[204:207], v[114:117]
	v_mfma_f32_16x16x32_bf16 v[102:105], v[188:191], v[212:215], v[102:105]
	v_mfma_f32_16x16x32_bf16 v[98:101], v[196:199], v[212:215], v[98:101]
	v_mfma_f32_16x16x32_bf16 v[86:89], v[188:191], v[224:227], v[86:89]
	v_mfma_f32_16x16x32_bf16 v[82:85], v[196:199], v[224:227], v[82:85]
	v_mfma_f32_16x16x32_bf16 v[70:73], v[188:191], v[232:235], v[70:73]
	v_mfma_f32_16x16x32_bf16 v[66:69], v[196:199], v[232:235], v[66:69]
	s_setprio 0
	s_barrier
; #define PG8_STAGE(bufoff, gbase, voff) do { _Pragma("unroll") for (int _i = 0; _i < 2; ++_i) \
;         __builtin_amdgcn_global_load_lds((const unsigned*)((const char*)(gbase) + (voff)[_i]), (PG8_LAS unsigned*)(lds + (bufoff) + ldsw + _i * 8192), 16, 0, 0); } while (0)
; #define PG8_LDA(dst, b, h) do { _Pragma("unroll") for (int m = 0; m < 4; ++m) _Pragma("unroll") for (int k = 0; k < 2; ++k) dst[m][k] = *(const PG8_LAS bf16x8*)(lds + PG8_SA(b, h) + aoff + m * 2048 + k * 1024); } while (0)
; #define PG8_MMA(ai, bj, At, Bt) do { __builtin_amdgcn_s_setprio(1); _Pragma("unroll") for (int m = 0; m < 4; ++m) _Pragma("unroll") for (int n = 0; n < 2; ++n) _Pragma("unroll") for (int k = 0; k < 2; ++k) \
;         acc[ai][bj][m][n] = __builtin_amdgcn_mfma_f32_16x16x32_bf16(Bt[n][k], At[m][k], acc[ai][bj][m][n], 0, 0, 0); __builtin_amdgcn_s_setprio(0); } while (0)
; #define PG8_WAIT_V(n) asm volatile("s_waitcnt vmcnt(" #n ")" ::: "memory")
; #define PG8_WAIT_L(n) asm volatile("s_waitcnt lgkmcnt(" #n ")" ::: "memory")
; #define PG8_BAR __builtin_amdgcn_s_barrier()
; #define PG8_SCHED __builtin_amdgcn_sched_barrier(0)
; template <class Epi, class Sched, bool ALIGN_EPI = false, bool SP2 = false>
; __device__ __forceinline__ void gemm_phase(PG8_LAS unsigned char* lds, const Gemm g, const Sched& S, const Epi& E) {
;     ...
;         for (int t = 0; t < nt; t += 2) {
;             const bool last = (t == nt - 2);
;     ...
;             PG8_LDA(At, 1, 1); PG8_STAGE(PG8_SB(1, 0), b3, voffB); PG8_STAGE(PG8_SB(1, 1), b3 + hstepB, voffB); PG8_STAGE(PG8_SA(1, 0), a3, voffA);
;             PG8_WAIT_V(8); PG8_WAIT_L(0); PG8_BAR; PG8_MMA(1, 0, At, B0); PG8_MMA(1, 1, At, B1); PG8_BAR; PG8_SCHED;
	s_add_i32 s46, s48, s55
	v_lshl_add_u64 v[172:173], v[172:173], 0, s[24:25]
	s_mov_b32 m0, s46
	ds_read_b128 v[200:203], v182 offset:49152
	ds_read_b128 v[204:207], v182 offset:50176
	ds_read_b128 v[208:211], v182 offset:51200
	ds_read_b128 v[212:215], v182 offset:52224
	ds_read_b128 v[220:223], v182 offset:53248
	ds_read_b128 v[224:227], v182 offset:54272
	ds_read_b128 v[228:231], v182 offset:55296
	ds_read_b128 v[232:235], v182 offset:56320
	global_load_lds_dwordx4 v[172:173], off
	s_add_i32 m0, s46, 0x2000
	s_add_u32 s8, s8, 0x40080
	v_lshl_add_u64 v[172:173], v[178:179], 0, s[24:25]
	s_addc_u32 s9, s9, 0
	s_add_i32 s46, s49, s55
	global_load_lds_dwordx4 v[172:173], off
	v_lshl_add_u64 v[172:173], s[8:9], 0, v[148:149]
	s_mov_b32 m0, s46
	s_nop 0
	global_load_lds_dwordx4 v[172:173], off
	v_lshl_add_u64 v[172:173], s[8:9], 0, v[152:153]
	s_add_i32 m0, s46, 0x2000
	s_nop 0
	global_load_lds_dwordx4 v[172:173], off
	v_lshl_add_u64 v[172:173], v[216:217], 0, s[24:25]
	s_mov_b32 m0, s66
	s_nop 0
	global_load_lds_dwordx4 v[172:173], off
	v_lshl_add_u64 v[172:173], v[236:237], 0, s[24:25]
	s_mov_b32 m0, s67
	s_nop 0
	global_load_lds_dwordx4 v[172:173], off
	s_waitcnt vmcnt(8)
	s_waitcnt lgkmcnt(0)
	s_barrier
	s_setprio 1
	s_waitcnt lgkmcnt(0)
	v_mfma_f32_16x16x32_bf16 v[62:65], v[130:133], v[200:203], v[62:65]
	v_mfma_f32_16x16x32_bf16 v[58:61], v[138:141], v[200:203], v[58:61]
	v_mfma_f32_16x16x32_bf16 v[46:49], v[130:133], v[208:211], v[46:49]
	v_mfma_f32_16x16x32_bf16 v[42:45], v[138:141], v[208:211], v[42:45]
	v_mfma_f32_16x16x32_bf16 v[30:33], v[130:133], v[220:223], v[30:33]
	v_mfma_f32_16x16x32_bf16 v[26:29], v[138:141], v[220:223], v[26:29]
	v_mfma_f32_16x16x32_bf16 v[14:17], v[130:133], v[228:231], v[14:17]
	v_mfma_f32_16x16x32_bf16 v[10:13], v[138:141], v[228:231], v[10:13]
	v_mfma_f32_16x16x32_bf16 v[62:65], v[134:137], v[204:207], v[62:65]
	v_mfma_f32_16x16x32_bf16 v[58:61], v[142:145], v[204:207], v[58:61]
	v_mfma_f32_16x16x32_bf16 v[46:49], v[134:137], v[212:215], v[46:49]
	v_mfma_f32_16x16x32_bf16 v[42:45], v[142:145], v[212:215], v[42:45]
	v_mfma_f32_16x16x32_bf16 v[30:33], v[134:137], v[224:227], v[30:33]
	v_mfma_f32_16x16x32_bf16 v[26:29], v[142:145], v[224:227], v[26:29]
	v_mfma_f32_16x16x32_bf16 v[14:17], v[134:137], v[232:235], v[14:17]
	v_mfma_f32_16x16x32_bf16 v[10:13], v[142:145], v[232:235], v[10:13]
	s_setprio 0
	s_setprio 1
	v_mfma_f32_16x16x32_bf16 v[54:57], v[168:171], v[200:203], v[54:57]
	v_mfma_f32_16x16x32_bf16 v[50:53], v[192:195], v[200:203], v[50:53]
	v_mfma_f32_16x16x32_bf16 v[38:41], v[168:171], v[208:211], v[38:41]
	v_mfma_f32_16x16x32_bf16 v[34:37], v[192:195], v[208:211], v[34:37]
	v_mfma_f32_16x16x32_bf16 v[22:25], v[168:171], v[220:223], v[22:25]
	v_mfma_f32_16x16x32_bf16 v[18:21], v[192:195], v[220:223], v[18:21]
	v_mfma_f32_16x16x32_bf16 v[6:9], v[168:171], v[228:231], v[6:9]
	v_mfma_f32_16x16x32_bf16 v[2:5], v[192:195], v[228:231], v[2:5]
	v_mfma_f32_16x16x32_bf16 v[54:57], v[188:191], v[204:207], v[54:57]
	v_mfma_f32_16x16x32_bf16 v[50:53], v[196:199], v[204:207], v[50:53]
	v_mfma_f32_16x16x32_bf16 v[38:41], v[188:191], v[212:215], v[38:41]
	v_mfma_f32_16x16x32_bf16 v[34:37], v[196:199], v[212:215], v[34:37]
	v_mfma_f32_16x16x32_bf16 v[22:25], v[188:191], v[224:227], v[22:25]
	v_mfma_f32_16x16x32_bf16 v[18:21], v[196:199], v[224:227], v[18:21]
	v_mfma_f32_16x16x32_bf16 v[6:9], v[188:191], v[232:235], v[6:9]
	v_mfma_f32_16x16x32_bf16 v[2:5], v[196:199], v[232:235], v[2:5]
	s_setprio 0
	s_add_i32 s41, s41, 2
	s_add_u32 s6, s6, 0x100
	s_addc_u32 s7, s7, 0
	s_add_u32 s38, s38, 0x100
	s_addc_u32 s39, s39, 0
	s_cmp_gt_u32 s41, 13
	s_barrier
	s_cbranch_scc0 .LBB0_197
	s_and_b64 vcc, exec, s[26:27]
	s_cbranch_vccz .LBB0_200
	s_barrier

; #define PG8_STAGE(bufoff, gbase, voff) do { _Pragma("unroll") for (int _i = 0; _i < 2; ++_i) \
;         __builtin_amdgcn_global_load_lds((const unsigned*)((const char*)(gbase) + (voff)[_i]), (PG8_LAS unsigned*)(lds + (bufoff) + ldsw + _i * 8192), 16, 0, 0); } while (0)
; #define PG8_LDA(dst, b, h) do { _Pragma("unroll") for (int m = 0; m < 4; ++m) _Pragma("unroll") for (int k = 0; k < 2; ++k) dst[m][k] = *(const PG8_LAS bf16x8*)(lds + PG8_SA(b, h) + aoff + m * 2048 + k * 1024); } while (0)
; #define PG8_LDB(dst, b, h) do { _Pragma("unroll") for (int n = 0; n < 2; ++n) _Pragma("unroll") for (int k = 0; k < 2; ++k) dst[n][k] = *(const PG8_LAS bf16x8*)(lds + PG8_SB(b, h) + boff + n * 2048 + k * 1024); } while (0)
; #define PG8_MMA(ai, bj, At, Bt) do { __builtin_amdgcn_s_setprio(1); _Pragma("unroll") for (int m = 0; m < 4; ++m) _Pragma("unroll") for (int n = 0; n < 2; ++n) _Pragma("unroll") for (int k = 0; k < 2; ++k) \
;         acc[ai][bj][m][n] = __builtin_amdgcn_mfma_f32_16x16x32_bf16(Bt[n][k], At[m][k], acc[ai][bj][m][n], 0, 0, 0); __builtin_amdgcn_s_setprio(0); } while (0)
; #define PG8_WAIT_V(n) asm volatile("s_waitcnt vmcnt(" #n ")" ::: "memory")
; #define PG8_WAIT_L(n) asm volatile("s_waitcnt lgkmcnt(" #n ")" ::: "memory")
; #define PG8_BAR __builtin_amdgcn_s_barrier()
; #define PG8_SCHED __builtin_amdgcn_sched_barrier(0)
; template <class Epi, class Sched, bool ALIGN_EPI = false, bool SP2 = false>
; __device__ __forceinline__ void gemm_phase(PG8_LAS unsigned char* lds, const Gemm g, const Sched& S, const Epi& E) {
;     ...
;         for (int t = 0; t < nt; t += 2) {
;             const bool last = (t == nt - 2);
;             const char* a1 = cA + (size_t)(t + 1) * kstep;
;             const char* a2 = last ? nA : cA + (size_t)(t + 2) * kstep; const char* b2 = last ? nB : cB + (size_t)(t + 2) * kstep;
;             const char* a3 = a2 + kstep; const char* b3 = b2 + kstep;
;             if (last && has_next) S.a_ready(nxt);
;             if constexpr (SP2) {
;             PG8_LDB(B0, 0, 0); PG8_LDB(B1, 0, 1); PG8_SCHED; PG8_LDA(At, 0, 0); PG8_STAGE(PG8_SA(1, 1), a1 + hstepA, voffA);
;             PG8_WAIT_V(8); PG8_WAIT_L(0); PG8_BAR; PG8_MMA(0, 0, At, B0); PG8_MMA(0, 1, At, B1); PG8_BAR; PG8_SCHED;
;             PG8_LDA(At, 0, 1); PG8_STAGE(PG8_SB(0, 0), b2, voffB); PG8_STAGE(PG8_SB(0, 1), b2 + hstepB, voffB); PG8_STAGE(PG8_SA(0, 0), a2, voffA);
.LBB0_417:
	s_add_u32 s44, s24, s40
	s_addc_u32 s45, s25, s41
	s_add_u32 s46, s44, 0x100
	s_addc_u32 s47, s45, 0
	s_and_b64 s[42:43], s[36:37], exec
	s_cselect_b32 s43, s27, s47
	s_cselect_b32 s42, s26, s46
	s_add_u32 s40, s12, s40
	s_addc_u32 s41, s13, s41
	ds_read_b128 v[146:149], v140
	ds_read_b128 v[150:153], v140 offset:1024
	ds_read_b128 v[154:157], v140 offset:2048
	ds_read_b128 v[158:161], v140 offset:3072
	ds_read_b128 v[162:165], v141
	ds_read_b128 v[166:169], v141 offset:1024
	ds_read_b128 v[170:173], v141 offset:2048
	ds_read_b128 v[176:179], v141 offset:3072
	s_add_u32 s40, s40, 0x100
	s_addc_u32 s41, s41, 0
	s_and_b64 s[36:37], s[36:37], exec
	s_cselect_b32 s41, s76, s41
	s_cselect_b32 s40, s77, s40
	s_add_u32 s48, s44, 0x18080
	s_addc_u32 s49, s45, 0
	s_add_u32 s44, s40, 0x10000
	s_addc_u32 s45, s41, 0
	s_add_u32 s36, s42, 0x18000
	s_addc_u32 s37, s43, 0
	s_add_u32 s46, s40, 0x10080
	s_addc_u32 s47, s41, 0
	s_mov_b32 m0, s64
	v_lshl_add_u64 v[212:213], s[48:49], 0, v[136:137]
	ds_read_b128 v[180:183], v142
	ds_read_b128 v[184:187], v142 offset:1024
	ds_read_b128 v[188:191], v142 offset:2048
	ds_read_b128 v[192:195], v142 offset:3072
	ds_read_b128 v[196:199], v142 offset:4096
	ds_read_b128 v[200:203], v142 offset:5120
	ds_read_b128 v[204:207], v142 offset:6144
	ds_read_b128 v[208:211], v142 offset:7168
	global_load_lds_dwordx4 v[212:213], off
	v_lshl_add_u64 v[212:213], s[48:49], 0, v[132:133]
	s_mov_b32 m0, s65
	s_nop 0
	global_load_lds_dwordx4 v[212:213], off
	s_waitcnt vmcnt(8)
	s_waitcnt lgkmcnt(0)
	s_barrier
	s_setprio 1
	s_waitcnt lgkmcnt(0)
	v_mfma_f32_16x16x32_bf16 v[126:129], v[146:149], v[180:183], v[126:129]
	v_mfma_f32_16x16x32_bf16 v[122:125], v[154:157], v[180:183], v[122:125]
	v_mfma_f32_16x16x32_bf16 v[118:121], v[146:149], v[188:191], v[118:121]
	v_mfma_f32_16x16x32_bf16 v[114:117], v[154:157], v[188:191], v[114:117]
	v_mfma_f32_16x16x32_bf16 v[106:109], v[146:149], v[196:199], v[106:109]
	v_mfma_f32_16x16x32_bf16 v[98:101], v[154:157], v[196:199], v[98:101]
	v_mfma_f32_16x16x32_bf16 v[90:93], v[146:149], v[204:207], v[90:93]
	v_mfma_f32_16x16x32_bf16 v[82:85], v[154:157], v[204:207], v[82:85]
	v_mfma_f32_16x16x32_bf16 v[126:129], v[150:153], v[184:187], v[126:129]
	v_mfma_f32_16x16x32_bf16 v[122:125], v[158:161], v[184:187], v[122:125]
	v_mfma_f32_16x16x32_bf16 v[118:121], v[150:153], v[192:195], v[118:121]
	v_mfma_f32_16x16x32_bf16 v[114:117], v[158:161], v[192:195], v[114:117]
	v_mfma_f32_16x16x32_bf16 v[106:109], v[150:153], v[200:203], v[106:109]
	v_mfma_f32_16x16x32_bf16 v[98:101], v[158:161], v[200:203], v[98:101]
	v_mfma_f32_16x16x32_bf16 v[90:93], v[150:153], v[208:211], v[90:93]
	v_mfma_f32_16x16x32_bf16 v[82:85], v[158:161], v[208:211], v[82:85]
	s_setprio 0
	s_setprio 1
	v_mfma_f32_16x16x32_bf16 v[110:113], v[162:165], v[180:183], v[110:113]
	v_mfma_f32_16x16x32_bf16 v[102:105], v[170:173], v[180:183], v[102:105]
	v_mfma_f32_16x16x32_bf16 v[94:97], v[162:165], v[188:191], v[94:97]
	v_mfma_f32_16x16x32_bf16 v[86:89], v[170:173], v[188:191], v[86:89]
	v_mfma_f32_16x16x32_bf16 v[78:81], v[162:165], v[196:199], v[78:81]
	v_mfma_f32_16x16x32_bf16 v[74:77], v[170:173], v[196:199], v[74:77]
	v_mfma_f32_16x16x32_bf16 v[70:73], v[162:165], v[204:207], v[70:73]
	v_mfma_f32_16x16x32_bf16 v[66:69], v[170:173], v[204:207], v[66:69]
	v_mfma_f32_16x16x32_bf16 v[110:113], v[166:169], v[184:187], v[110:113]
	v_mfma_f32_16x16x32_bf16 v[102:105], v[176:179], v[184:187], v[102:105]
	v_mfma_f32_16x16x32_bf16 v[94:97], v[166:169], v[192:195], v[94:97]
	v_mfma_f32_16x16x32_bf16 v[86:89], v[176:179], v[192:195], v[86:89]
	v_mfma_f32_16x16x32_bf16 v[78:81], v[166:169], v[200:203], v[78:81]
	v_mfma_f32_16x16x32_bf16 v[74:77], v[176:179], v[200:203], v[74:77]
	v_mfma_f32_16x16x32_bf16 v[70:73], v[166:169], v[208:211], v[70:73]
	v_mfma_f32_16x16x32_bf16 v[66:69], v[176:179], v[208:211], v[66:69]
	s_setprio 0
	s_barrier
	s_mov_b32 m0, s66
	v_lshl_add_u64 v[212:213], s[40:41], 0, v[134:135]
	ds_read_b128 v[180:183], v142 offset:16384
	ds_read_b128 v[184:187], v142 offset:17408
	ds_read_b128 v[188:191], v142 offset:18432
	ds_read_b128 v[192:195], v142 offset:19456
	ds_read_b128 v[196:199], v142 offset:20480
	ds_read_b128 v[200:203], v142 offset:21504
	ds_read_b128 v[204:207], v142 offset:22528
	ds_read_b128 v[208:211], v142 offset:23552
	global_load_lds_dwordx4 v[212:213], off
	v_lshl_add_u64 v[214:215], s[40:41], 0, v[130:131]
	s_mov_b32 m0, s67
	v_lshl_add_u64 v[216:217], s[44:45], 0, v[134:135]
	global_load_lds_dwordx4 v[214:215], off
	s_mov_b32 m0, s68
	v_lshl_add_u64 v[220:221], s[42:43], 0, v[132:133]
	global_load_lds_dwordx4 v[216:217], off
	v_lshl_add_u64 v[216:217], s[44:45], 0, v[130:131]
	s_mov_b32 m0, s69
	s_nop 0
	global_load_lds_dwordx4 v[216:217], off
	v_lshl_add_u64 v[216:217], s[42:43], 0, v[136:137]
	s_mov_b32 m0, s51
	s_nop 0
	global_load_lds_dwordx4 v[216:217], off
	s_mov_b32 m0, s53
	s_nop 0
	global_load_lds_dwordx4 v[220:221], off
	s_waitcnt vmcnt(8)
	s_waitcnt lgkmcnt(0)
	s_barrier
; #define PG8_STAGE(bufoff, gbase, voff) do { _Pragma("unroll") for (int _i = 0; _i < 2; ++_i) \
;         __builtin_amdgcn_global_load_lds((const unsigned*)((const char*)(gbase) + (voff)[_i]), (PG8_LAS unsigned*)(lds + (bufoff) + ldsw + _i * 8192), 16, 0, 0); } while (0)
; #define PG8_LDA(dst, b, h) do { _Pragma("unroll") for (int m = 0; m < 4; ++m) _Pragma("unroll") for (int k = 0; k < 2; ++k) dst[m][k] = *(const PG8_LAS bf16x8*)(lds + PG8_SA(b, h) + aoff + m * 2048 + k * 1024); } while (0)
; #define PG8_LDB(dst, b, h) do { _Pragma("unroll") for (int n = 0; n < 2; ++n) _Pragma("unroll") for (int k = 0; k < 2; ++k) dst[n][k] = *(const PG8_LAS bf16x8*)(lds + PG8_SB(b, h) + boff + n * 2048 + k * 1024); } while (0)
; #define PG8_MMA(ai, bj, At, Bt) do { __builtin_amdgcn_s_setprio(1); _Pragma("unroll") for (int m = 0; m < 4; ++m) _Pragma("unroll") for (int n = 0; n < 2; ++n) _Pragma("unroll") for (int k = 0; k < 2; ++k) \
;         acc[ai][bj][m][n] = __builtin_amdgcn_mfma_f32_16x16x32_bf16(Bt[n][k], At[m][k], acc[ai][bj][m][n], 0, 0, 0); __builtin_amdgcn_s_setprio(0); } while (0)
; #define PG8_WAIT_V(n) asm volatile("s_waitcnt vmcnt(" #n ")" ::: "memory")
; #define PG8_WAIT_L(n) asm volatile("s_waitcnt lgkmcnt(" #n ")" ::: "memory")
; #define PG8_BAR __builtin_amdgcn_s_barrier()
; #define PG8_SCHED __builtin_amdgcn_sched_barrier(0)
; template <class Epi, class Sched, bool ALIGN_EPI = false, bool SP2 = false>
; __device__ __forceinline__ void gemm_phase(PG8_LAS unsigned char* lds, const Gemm g, const Sched& S, const Epi& E) {
;     ...
;             PG8_WAIT_V(8); PG8_WAIT_L(0); PG8_BAR; PG8_MMA(1, 0, At, B0); PG8_MMA(1, 1, At, B1); PG8_BAR; PG8_SCHED;
;             PG8_LDB(B0, 1, 0); PG8_LDB(B1, 1, 1); PG8_SCHED; PG8_LDA(At, 1, 0); PG8_STAGE(PG8_SA(0, 1), a2 + hstepA, voffA);
;             PG8_WAIT_V(8); PG8_WAIT_L(0); PG8_BAR; PG8_MMA(0, 0, At, B0); PG8_MMA(0, 1, At, B1); PG8_BAR; PG8_SCHED;
	s_setprio 1
	s_waitcnt lgkmcnt(0)
	v_mfma_f32_16x16x32_bf16 v[62:65], v[146:149], v[180:183], v[62:65]
	v_mfma_f32_16x16x32_bf16 v[58:61], v[154:157], v[180:183], v[58:61]
	v_mfma_f32_16x16x32_bf16 v[54:57], v[146:149], v[188:191], v[54:57]
	v_mfma_f32_16x16x32_bf16 v[50:53], v[154:157], v[188:191], v[50:53]
	v_mfma_f32_16x16x32_bf16 v[42:45], v[146:149], v[196:199], v[42:45]
	v_mfma_f32_16x16x32_bf16 v[34:37], v[154:157], v[196:199], v[34:37]
	v_mfma_f32_16x16x32_bf16 v[26:29], v[146:149], v[204:207], v[26:29]
	v_mfma_f32_16x16x32_bf16 v[18:21], v[154:157], v[204:207], v[18:21]
	v_mfma_f32_16x16x32_bf16 v[62:65], v[150:153], v[184:187], v[62:65]
	v_mfma_f32_16x16x32_bf16 v[58:61], v[158:161], v[184:187], v[58:61]
	v_mfma_f32_16x16x32_bf16 v[54:57], v[150:153], v[192:195], v[54:57]
	v_mfma_f32_16x16x32_bf16 v[50:53], v[158:161], v[192:195], v[50:53]
	v_mfma_f32_16x16x32_bf16 v[42:45], v[150:153], v[200:203], v[42:45]
	v_mfma_f32_16x16x32_bf16 v[34:37], v[158:161], v[200:203], v[34:37]
	v_mfma_f32_16x16x32_bf16 v[26:29], v[150:153], v[208:211], v[26:29]
	v_mfma_f32_16x16x32_bf16 v[18:21], v[158:161], v[208:211], v[18:21]
	s_setprio 0
	s_setprio 1
	v_mfma_f32_16x16x32_bf16 v[46:49], v[162:165], v[180:183], v[46:49]
	v_mfma_f32_16x16x32_bf16 v[38:41], v[170:173], v[180:183], v[38:41]
	v_mfma_f32_16x16x32_bf16 v[30:33], v[162:165], v[188:191], v[30:33]
	v_mfma_f32_16x16x32_bf16 v[22:25], v[170:173], v[188:191], v[22:25]
	v_mfma_f32_16x16x32_bf16 v[14:17], v[162:165], v[196:199], v[14:17]
	v_mfma_f32_16x16x32_bf16 v[10:13], v[170:173], v[196:199], v[10:13]
	v_mfma_f32_16x16x32_bf16 v[6:9], v[162:165], v[204:207], v[6:9]
	v_mfma_f32_16x16x32_bf16 v[2:5], v[170:173], v[204:207], v[2:5]
	v_mfma_f32_16x16x32_bf16 v[46:49], v[166:169], v[184:187], v[46:49]
	v_mfma_f32_16x16x32_bf16 v[38:41], v[176:179], v[184:187], v[38:41]
	v_mfma_f32_16x16x32_bf16 v[30:33], v[166:169], v[192:195], v[30:33]
	v_mfma_f32_16x16x32_bf16 v[22:25], v[176:179], v[192:195], v[22:25]
	v_mfma_f32_16x16x32_bf16 v[14:17], v[166:169], v[200:203], v[14:17]
	v_mfma_f32_16x16x32_bf16 v[10:13], v[176:179], v[200:203], v[10:13]
	v_mfma_f32_16x16x32_bf16 v[6:9], v[166:169], v[208:211], v[6:9]
	v_mfma_f32_16x16x32_bf16 v[2:5], v[176:179], v[208:211], v[2:5]
	s_setprio 0
	s_barrier
	ds_read_b128 v[146:149], v143
	ds_read_b128 v[150:153], v143 offset:1024
	ds_read_b128 v[154:157], v143 offset:2048
	ds_read_b128 v[158:161], v143 offset:3072
	ds_read_b128 v[162:165], v144
	ds_read_b128 v[166:169], v144 offset:1024
	ds_read_b128 v[170:173], v144 offset:2048
	ds_read_b128 v[176:179], v144 offset:3072
	s_mov_b32 m0, s54
	v_lshl_add_u64 v[222:223], s[36:37], 0, v[136:137]
	ds_read_b128 v[180:183], v142 offset:32768
	ds_read_b128 v[184:187], v142 offset:33792
	ds_read_b128 v[188:191], v142 offset:34816
	ds_read_b128 v[192:195], v142 offset:35840
	ds_read_b128 v[196:199], v142 offset:36864
	ds_read_b128 v[200:203], v142 offset:37888
	ds_read_b128 v[204:207], v142 offset:38912
	ds_read_b128 v[208:211], v142 offset:39936
	global_load_lds_dwordx4 v[222:223], off
	v_lshl_add_u64 v[222:223], s[36:37], 0, v[132:133]
	s_mov_b32 m0, s55
	s_nop 0
	global_load_lds_dwordx4 v[222:223], off
	s_waitcnt vmcnt(8)
	s_waitcnt lgkmcnt(0)
	s_barrier
	s_setprio 1
	s_waitcnt lgkmcnt(0)
	v_mfma_f32_16x16x32_bf16 v[126:129], v[146:149], v[180:183], v[126:129]
	v_mfma_f32_16x16x32_bf16 v[122:125], v[154:157], v[180:183], v[122:125]
	v_mfma_f32_16x16x32_bf16 v[118:121], v[146:149], v[188:191], v[118:121]
	v_mfma_f32_16x16x32_bf16 v[114:117], v[154:157], v[188:191], v[114:117]
	v_mfma_f32_16x16x32_bf16 v[106:109], v[146:149], v[196:199], v[106:109]
	v_mfma_f32_16x16x32_bf16 v[98:101], v[154:157], v[196:199], v[98:101]
	v_mfma_f32_16x16x32_bf16 v[90:93], v[146:149], v[204:207], v[90:93]
	v_mfma_f32_16x16x32_bf16 v[82:85], v[154:157], v[204:207], v[82:85]
	v_mfma_f32_16x16x32_bf16 v[126:129], v[150:153], v[184:187], v[126:129]
	v_mfma_f32_16x16x32_bf16 v[122:125], v[158:161], v[184:187], v[122:125]
	v_mfma_f32_16x16x32_bf16 v[118:121], v[150:153], v[192:195], v[118:121]
	v_mfma_f32_16x16x32_bf16 v[114:117], v[158:161], v[192:195], v[114:117]
	v_mfma_f32_16x16x32_bf16 v[106:109], v[150:153], v[200:203], v[106:109]
	v_mfma_f32_16x16x32_bf16 v[98:101], v[158:161], v[200:203], v[98:101]
	v_mfma_f32_16x16x32_bf16 v[90:93], v[150:153], v[208:211], v[90:93]
	v_mfma_f32_16x16x32_bf16 v[82:85], v[158:161], v[208:211], v[82:85]
	s_setprio 0
	s_setprio 1
	v_mfma_f32_16x16x32_bf16 v[110:113], v[162:165], v[180:183], v[110:113]
	v_mfma_f32_16x16x32_bf16 v[102:105], v[170:173], v[180:183], v[102:105]
	v_mfma_f32_16x16x32_bf16 v[94:97], v[162:165], v[188:191], v[94:97]
	v_mfma_f32_16x16x32_bf16 v[86:89], v[170:173], v[188:191], v[86:89]
	v_mfma_f32_16x16x32_bf16 v[78:81], v[162:165], v[196:199], v[78:81]
	v_mfma_f32_16x16x32_bf16 v[74:77], v[170:173], v[196:199], v[74:77]
	v_mfma_f32_16x16x32_bf16 v[70:73], v[162:165], v[204:207], v[70:73]
	v_mfma_f32_16x16x32_bf16 v[66:69], v[170:173], v[204:207], v[66:69]
	v_mfma_f32_16x16x32_bf16 v[110:113], v[166:169], v[184:187], v[110:113]
	v_mfma_f32_16x16x32_bf16 v[102:105], v[176:179], v[184:187], v[102:105]
	v_mfma_f32_16x16x32_bf16 v[94:97], v[166:169], v[192:195], v[94:97]
	v_mfma_f32_16x16x32_bf16 v[86:89], v[176:179], v[192:195], v[86:89]
	v_mfma_f32_16x16x32_bf16 v[78:81], v[166:169], v[200:203], v[78:81]
	v_mfma_f32_16x16x32_bf16 v[74:77], v[176:179], v[200:203], v[74:77]
	v_mfma_f32_16x16x32_bf16 v[70:73], v[166:169], v[208:211], v[70:73]
	v_mfma_f32_16x16x32_bf16 v[66:69], v[176:179], v[208:211], v[66:69]
	s_setprio 0
	s_barrier
; #define PG8_STAGE(bufoff, gbase, voff) do { _Pragma("unroll") for (int _i = 0; _i < 2; ++_i) \
;         __builtin_amdgcn_global_load_lds((const unsigned*)((const char*)(gbase) + (voff)[_i]), (PG8_LAS unsigned*)(lds + (bufoff) + ldsw + _i * 8192), 16, 0, 0); } while (0)
; #define PG8_LDA(dst, b, h) do { _Pragma("unroll") for (int m = 0; m < 4; ++m) _Pragma("unroll") for (int k = 0; k < 2; ++k) dst[m][k] = *(const PG8_LAS bf16x8*)(lds + PG8_SA(b, h) + aoff + m * 2048 + k * 1024); } while (0)
; #define PG8_MMA(ai, bj, At, Bt) do { __builtin_amdgcn_s_setprio(1); _Pragma("unroll") for (int m = 0; m < 4; ++m) _Pragma("unroll") for (int n = 0; n < 2; ++n) _Pragma("unroll") for (int k = 0; k < 2; ++k) \
;         acc[ai][bj][m][n] = __builtin_amdgcn_mfma_f32_16x16x32_bf16(Bt[n][k], At[m][k], acc[ai][bj][m][n], 0, 0, 0); __builtin_amdgcn_s_setprio(0); } while (0)
; #define PG8_WAIT_V(n) asm volatile("s_waitcnt vmcnt(" #n ")" ::: "memory")
; #define PG8_WAIT_L(n) asm volatile("s_waitcnt lgkmcnt(" #n ")" ::: "memory")
; #define PG8_BAR __builtin_amdgcn_s_barrier()
; #define PG8_SCHED __builtin_amdgcn_sched_barrier(0)
; template <class Epi, class Sched, bool ALIGN_EPI = false, bool SP2 = false>
; __device__ __forceinline__ void gemm_phase(PG8_LAS unsigned char* lds, const Gemm g, const Sched& S, const Epi& E) {
;     ...
;         for (int t = 0; t < nt; t += 2) {
;             const bool last = (t == nt - 2);
;     ...
;             PG8_LDA(At, 1, 1); PG8_STAGE(PG8_SB(1, 0), b3, voffB); PG8_STAGE(PG8_SB(1, 1), b3 + hstepB, voffB); PG8_STAGE(PG8_SA(1, 0), a3, voffA);
;             PG8_WAIT_V(8); PG8_WAIT_L(0); PG8_BAR; PG8_MMA(1, 0, At, B0); PG8_MMA(1, 1, At, B1); PG8_BAR; PG8_SCHED;
	s_mov_b32 m0, s70
	v_lshl_add_u64 v[212:213], v[212:213], 0, s[10:11]
	ds_read_b128 v[180:183], v142 offset:49152
	ds_read_b128 v[184:187], v142 offset:50176
	ds_read_b128 v[188:191], v142 offset:51200
	ds_read_b128 v[192:195], v142 offset:52224
	ds_read_b128 v[196:199], v142 offset:53248
	ds_read_b128 v[200:203], v142 offset:54272
	ds_read_b128 v[204:207], v142 offset:55296
	ds_read_b128 v[208:211], v142 offset:56320
	global_load_lds_dwordx4 v[212:213], off
	v_lshl_add_u64 v[212:213], v[214:215], 0, s[10:11]
	s_mov_b32 m0, s71
	s_nop 0
	global_load_lds_dwordx4 v[212:213], off
	v_lshl_add_u64 v[212:213], s[46:47], 0, v[134:135]
	s_mov_b32 m0, s72
	s_nop 0
	global_load_lds_dwordx4 v[212:213], off
	v_lshl_add_u64 v[212:213], s[46:47], 0, v[130:131]
	s_mov_b32 m0, s73
	s_nop 0
	global_load_lds_dwordx4 v[212:213], off
	v_lshl_add_u64 v[212:213], v[216:217], 0, s[10:11]
	s_mov_b32 m0, s62
	s_nop 0
	global_load_lds_dwordx4 v[212:213], off
	v_lshl_add_u64 v[212:213], v[220:221], 0, s[10:11]
	s_mov_b32 m0, s63
	s_nop 0
	global_load_lds_dwordx4 v[212:213], off
	s_waitcnt vmcnt(8)
	s_waitcnt lgkmcnt(0)
	s_barrier
	s_setprio 1
	s_waitcnt lgkmcnt(0)
	v_mfma_f32_16x16x32_bf16 v[62:65], v[146:149], v[180:183], v[62:65]
	v_mfma_f32_16x16x32_bf16 v[58:61], v[154:157], v[180:183], v[58:61]
	v_mfma_f32_16x16x32_bf16 v[54:57], v[146:149], v[188:191], v[54:57]
	v_mfma_f32_16x16x32_bf16 v[50:53], v[154:157], v[188:191], v[50:53]
	v_mfma_f32_16x16x32_bf16 v[42:45], v[146:149], v[196:199], v[42:45]
	v_mfma_f32_16x16x32_bf16 v[34:37], v[154:157], v[196:199], v[34:37]
	v_mfma_f32_16x16x32_bf16 v[26:29], v[146:149], v[204:207], v[26:29]
	v_mfma_f32_16x16x32_bf16 v[18:21], v[154:157], v[204:207], v[18:21]
	v_mfma_f32_16x16x32_bf16 v[62:65], v[150:153], v[184:187], v[62:65]
	v_mfma_f32_16x16x32_bf16 v[58:61], v[158:161], v[184:187], v[58:61]
	v_mfma_f32_16x16x32_bf16 v[54:57], v[150:153], v[192:195], v[54:57]
	v_mfma_f32_16x16x32_bf16 v[50:53], v[158:161], v[192:195], v[50:53]
	v_mfma_f32_16x16x32_bf16 v[42:45], v[150:153], v[200:203], v[42:45]
	v_mfma_f32_16x16x32_bf16 v[34:37], v[158:161], v[200:203], v[34:37]
	v_mfma_f32_16x16x32_bf16 v[26:29], v[150:153], v[208:211], v[26:29]
	v_mfma_f32_16x16x32_bf16 v[18:21], v[158:161], v[208:211], v[18:21]
	s_setprio 0
	s_setprio 1
	v_mfma_f32_16x16x32_bf16 v[46:49], v[162:165], v[180:183], v[46:49]
	v_mfma_f32_16x16x32_bf16 v[38:41], v[170:173], v[180:183], v[38:41]
	v_mfma_f32_16x16x32_bf16 v[30:33], v[162:165], v[188:191], v[30:33]
	v_mfma_f32_16x16x32_bf16 v[22:25], v[170:173], v[188:191], v[22:25]
	v_mfma_f32_16x16x32_bf16 v[14:17], v[162:165], v[196:199], v[14:17]
	v_mfma_f32_16x16x32_bf16 v[10:13], v[170:173], v[196:199], v[10:13]
	v_mfma_f32_16x16x32_bf16 v[6:9], v[162:165], v[204:207], v[6:9]
	v_mfma_f32_16x16x32_bf16 v[2:5], v[170:173], v[204:207], v[2:5]
	v_mfma_f32_16x16x32_bf16 v[46:49], v[166:169], v[184:187], v[46:49]
	v_mfma_f32_16x16x32_bf16 v[38:41], v[176:179], v[184:187], v[38:41]
	v_mfma_f32_16x16x32_bf16 v[30:33], v[166:169], v[192:195], v[30:33]
	v_mfma_f32_16x16x32_bf16 v[22:25], v[176:179], v[192:195], v[22:25]
	v_mfma_f32_16x16x32_bf16 v[14:17], v[166:169], v[200:203], v[14:17]
	v_mfma_f32_16x16x32_bf16 v[10:13], v[176:179], v[200:203], v[10:13]
	v_mfma_f32_16x16x32_bf16 v[6:9], v[166:169], v[208:211], v[6:9]
	v_mfma_f32_16x16x32_bf16 v[2:5], v[176:179], v[208:211], v[2:5]
	s_setprio 0
	s_andn2_b64 vcc, exec, s[34:35]
	s_mov_b64 s[36:37], -1
	s_mov_b64 s[34:35], 0
	s_mov_b64 s[40:41], 0x100
	s_barrier
	s_cbranch_vccz .LBB0_417
	s_and_b64 vcc, exec, s[14:15]
	s_cbranch_vccnz .LBB0_421
	s_andn2_b64 vcc, exec, s[16:17]
	s_cbranch_vccz .LBB0_422

; #define PG8_STAGE(bufoff, gbase, voff) do { _Pragma("unroll") for (int _i = 0; _i < 2; ++_i) \
;         __builtin_amdgcn_global_load_lds((const unsigned*)((const char*)(gbase) + (voff)[_i]), (PG8_LAS unsigned*)(lds + (bufoff) + ldsw + _i * 8192), 16, 0, 0); } while (0)
; #define PG8_LDA(dst, b, h) do { _Pragma("unroll") for (int m = 0; m < 4; ++m) _Pragma("unroll") for (int k = 0; k < 2; ++k) dst[m][k] = *(const PG8_LAS bf16x8*)(lds + PG8_SA(b, h) + aoff + m * 2048 + k * 1024); } while (0)
; #define PG8_LDB(dst, b, h) do { _Pragma("unroll") for (int n = 0; n < 2; ++n) _Pragma("unroll") for (int k = 0; k < 2; ++k) dst[n][k] = *(const PG8_LAS bf16x8*)(lds + PG8_SB(b, h) + boff + n * 2048 + k * 1024); } while (0)
; #define PG8_MMA(ai, bj, At, Bt) do { __builtin_amdgcn_s_setprio(1); _Pragma("unroll") for (int m = 0; m < 4; ++m) _Pragma("unroll") for (int n = 0; n < 2; ++n) _Pragma("unroll") for (int k = 0; k < 2; ++k) \
;         acc[ai][bj][m][n] = __builtin_amdgcn_mfma_f32_16x16x32_bf16(Bt[n][k], At[m][k], acc[ai][bj][m][n], 0, 0, 0); __builtin_amdgcn_s_setprio(0); } while (0)
; #define PG8_WAIT_V(n) asm volatile("s_waitcnt vmcnt(" #n ")" ::: "memory")
; #define PG8_WAIT_L(n) asm volatile("s_waitcnt lgkmcnt(" #n ")" ::: "memory")
; #define PG8_BAR __builtin_amdgcn_s_barrier()
; #define PG8_SCHED __builtin_amdgcn_sched_barrier(0)
; template <class Epi, class Sched, bool ALIGN_EPI = false, bool SP2 = false>
; __device__ __forceinline__ void gemm_phase(PG8_LAS unsigned char* lds, const Gemm g, const Sched& S, const Epi& E) {
;     ...
;         for (int t = 0; t < nt; t += 2) {
;             const bool last = (t == nt - 2);
;             const char* a1 = cA + (size_t)(t + 1) * kstep;
;             const char* a2 = last ? nA : cA + (size_t)(t + 2) * kstep; const char* b2 = last ? nB : cB + (size_t)(t + 2) * kstep;
;             const char* a3 = a2 + kstep; const char* b3 = b2 + kstep;
;             if (last && has_next) S.a_ready(nxt);
;             if constexpr (SP2) {
;             PG8_LDB(B0, 0, 0); PG8_LDB(B1, 0, 1); PG8_SCHED; PG8_LDA(At, 0, 0); PG8_STAGE(PG8_SA(1, 1), a1 + hstepA, voffA);
;             PG8_WAIT_V(8); PG8_WAIT_L(0); PG8_BAR; PG8_MMA(0, 0, At, B0); PG8_MMA(0, 1, At, B1); PG8_BAR; PG8_SCHED;
;             PG8_LDA(At, 0, 1); PG8_STAGE(PG8_SB(0, 0), b2, voffB); PG8_STAGE(PG8_SB(0, 1), b2 + hstepB, voffB); PG8_STAGE(PG8_SA(0, 0), a2, voffA);
.LBB0_686:
	ds_read_b128 v[146:149], v152
	ds_read_b128 v[158:161], v152 offset:1024
	ds_read_b128 v[162:165], v152 offset:2048
	ds_read_b128 v[166:169], v152 offset:3072
	ds_read_b128 v[170:173], v153
	ds_read_b128 v[176:179], v153 offset:1024
	ds_read_b128 v[180:183], v153 offset:2048
	ds_read_b128 v[184:187], v153 offset:3072
	s_add_u32 s22, s20, 0x100
	s_addc_u32 s23, s21, 0
	s_cmp_eq_u32 s61, 2
	s_cselect_b32 s27, s17, s23
	s_cselect_b32 s26, s16, s22
	s_cselect_b32 s25, s19, s39
	s_cselect_b32 s24, s18, s38
	s_mov_b32 m0, s43
	v_lshl_add_u64 v[216:217], s[20:21], 0, v[142:143]
	ds_read_b128 v[188:191], v154
	ds_read_b128 v[192:195], v154 offset:1024
	ds_read_b128 v[196:199], v154 offset:2048
	ds_read_b128 v[200:203], v154 offset:3072
	ds_read_b128 v[204:207], v154 offset:4096
	ds_read_b128 v[208:211], v154 offset:5120
	ds_read_b128 v[212:215], v154 offset:6144
	ds_read_b128 v[220:223], v154 offset:7168
	global_load_lds_dwordx4 v[216:217], off
	v_lshl_add_u64 v[216:217], s[20:21], 0, v[144:145]
	s_mov_b32 m0, s44
	s_nop 0
	global_load_lds_dwordx4 v[216:217], off
	s_waitcnt vmcnt(8)
	s_waitcnt lgkmcnt(0)
	s_barrier
	s_setprio 1
	s_waitcnt lgkmcnt(0)
	v_mfma_f32_16x16x32_bf16 v[126:129], v[146:149], v[188:191], v[126:129]
	v_mfma_f32_16x16x32_bf16 v[122:125], v[162:165], v[188:191], v[122:125]
	v_mfma_f32_16x16x32_bf16 v[110:113], v[146:149], v[196:199], v[110:113]
	v_mfma_f32_16x16x32_bf16 v[106:109], v[162:165], v[196:199], v[106:109]
	v_mfma_f32_16x16x32_bf16 v[94:97], v[146:149], v[204:207], v[94:97]
	v_mfma_f32_16x16x32_bf16 v[90:93], v[162:165], v[204:207], v[90:93]
	v_mfma_f32_16x16x32_bf16 v[78:81], v[146:149], v[212:215], v[78:81]
	v_mfma_f32_16x16x32_bf16 v[74:77], v[162:165], v[212:215], v[74:77]
	v_mfma_f32_16x16x32_bf16 v[126:129], v[158:161], v[192:195], v[126:129]
	v_mfma_f32_16x16x32_bf16 v[122:125], v[166:169], v[192:195], v[122:125]
	v_mfma_f32_16x16x32_bf16 v[110:113], v[158:161], v[200:203], v[110:113]
	v_mfma_f32_16x16x32_bf16 v[106:109], v[166:169], v[200:203], v[106:109]
	v_mfma_f32_16x16x32_bf16 v[94:97], v[158:161], v[208:211], v[94:97]
	v_mfma_f32_16x16x32_bf16 v[90:93], v[166:169], v[208:211], v[90:93]
	v_mfma_f32_16x16x32_bf16 v[78:81], v[158:161], v[220:223], v[78:81]
	v_mfma_f32_16x16x32_bf16 v[74:77], v[166:169], v[220:223], v[74:77]
	s_setprio 0
	s_setprio 1
	v_mfma_f32_16x16x32_bf16 v[118:121], v[170:173], v[188:191], v[118:121]
	v_mfma_f32_16x16x32_bf16 v[114:117], v[180:183], v[188:191], v[114:117]
	v_mfma_f32_16x16x32_bf16 v[102:105], v[170:173], v[196:199], v[102:105]
	v_mfma_f32_16x16x32_bf16 v[98:101], v[180:183], v[196:199], v[98:101]
	v_mfma_f32_16x16x32_bf16 v[86:89], v[170:173], v[204:207], v[86:89]
	v_mfma_f32_16x16x32_bf16 v[82:85], v[180:183], v[204:207], v[82:85]
	v_mfma_f32_16x16x32_bf16 v[70:73], v[170:173], v[212:215], v[70:73]
	v_mfma_f32_16x16x32_bf16 v[66:69], v[180:183], v[212:215], v[66:69]
	v_mfma_f32_16x16x32_bf16 v[118:121], v[176:179], v[192:195], v[118:121]
	v_mfma_f32_16x16x32_bf16 v[114:117], v[184:187], v[192:195], v[114:117]
	v_mfma_f32_16x16x32_bf16 v[102:105], v[176:179], v[200:203], v[102:105]
	v_mfma_f32_16x16x32_bf16 v[98:101], v[184:187], v[200:203], v[98:101]
	v_mfma_f32_16x16x32_bf16 v[86:89], v[176:179], v[208:211], v[86:89]
	v_mfma_f32_16x16x32_bf16 v[82:85], v[184:187], v[208:211], v[82:85]
	v_mfma_f32_16x16x32_bf16 v[70:73], v[176:179], v[220:223], v[70:73]
	v_mfma_f32_16x16x32_bf16 v[66:69], v[184:187], v[220:223], v[66:69]
	s_setprio 0
	s_barrier
	s_mov_b32 m0, s45
	v_lshl_add_u64 v[216:217], s[24:25], 0, v[134:135]
	s_add_u32 s20, s24, 0x18000
	ds_read_b128 v[188:191], v154 offset:16384
	ds_read_b128 v[192:195], v154 offset:17408
	ds_read_b128 v[196:199], v154 offset:18432
	ds_read_b128 v[200:203], v154 offset:19456
	ds_read_b128 v[204:207], v154 offset:20480
	ds_read_b128 v[208:211], v154 offset:21504
	ds_read_b128 v[212:215], v154 offset:22528
	ds_read_b128 v[220:223], v154 offset:23552
	global_load_lds_dwordx4 v[216:217], off
	v_lshl_add_u64 v[224:225], s[24:25], 0, v[130:131]
	s_mov_b32 m0, s46
	s_addc_u32 s21, s25, 0
	global_load_lds_dwordx4 v[224:225], off
	v_lshl_add_u64 v[226:227], s[20:21], 0, v[134:135]
	s_mov_b32 m0, s47
	v_lshl_add_u64 v[228:229], s[26:27], 0, v[132:133]
	global_load_lds_dwordx4 v[226:227], off
	v_lshl_add_u64 v[226:227], s[20:21], 0, v[130:131]
	s_mov_b32 m0, s48
	s_nop 0
	global_load_lds_dwordx4 v[226:227], off
	v_lshl_add_u64 v[226:227], s[26:27], 0, v[136:137]
	s_mov_b32 m0, s34
	s_nop 0
	global_load_lds_dwordx4 v[226:227], off
	s_mov_b32 m0, s35
	s_nop 0
	global_load_lds_dwordx4 v[228:229], off
	s_waitcnt vmcnt(8)
	s_waitcnt lgkmcnt(0)
	s_barrier
; #define PG8_STAGE(bufoff, gbase, voff) do { _Pragma("unroll") for (int _i = 0; _i < 2; ++_i) \
;         __builtin_amdgcn_global_load_lds((const unsigned*)((const char*)(gbase) + (voff)[_i]), (PG8_LAS unsigned*)(lds + (bufoff) + ldsw + _i * 8192), 16, 0, 0); } while (0)
; #define PG8_LDA(dst, b, h) do { _Pragma("unroll") for (int m = 0; m < 4; ++m) _Pragma("unroll") for (int k = 0; k < 2; ++k) dst[m][k] = *(const PG8_LAS bf16x8*)(lds + PG8_SA(b, h) + aoff + m * 2048 + k * 1024); } while (0)
; #define PG8_LDB(dst, b, h) do { _Pragma("unroll") for (int n = 0; n < 2; ++n) _Pragma("unroll") for (int k = 0; k < 2; ++k) dst[n][k] = *(const PG8_LAS bf16x8*)(lds + PG8_SB(b, h) + boff + n * 2048 + k * 1024); } while (0)
; #define PG8_MMA(ai, bj, At, Bt) do { __builtin_amdgcn_s_setprio(1); _Pragma("unroll") for (int m = 0; m < 4; ++m) _Pragma("unroll") for (int n = 0; n < 2; ++n) _Pragma("unroll") for (int k = 0; k < 2; ++k) \
;         acc[ai][bj][m][n] = __builtin_amdgcn_mfma_f32_16x16x32_bf16(Bt[n][k], At[m][k], acc[ai][bj][m][n], 0, 0, 0); __builtin_amdgcn_s_setprio(0); } while (0)
; #define PG8_WAIT_V(n) asm volatile("s_waitcnt vmcnt(" #n ")" ::: "memory")
; #define PG8_WAIT_L(n) asm volatile("s_waitcnt lgkmcnt(" #n ")" ::: "memory")
; #define PG8_BAR __builtin_amdgcn_s_barrier()
; #define PG8_SCHED __builtin_amdgcn_sched_barrier(0)
; template <class Epi, class Sched, bool ALIGN_EPI = false, bool SP2 = false>
; __device__ __forceinline__ void gemm_phase(PG8_LAS unsigned char* lds, const Gemm g, const Sched& S, const Epi& E) {
;     ...
;             PG8_WAIT_V(8); PG8_WAIT_L(0); PG8_BAR; PG8_MMA(1, 0, At, B0); PG8_MMA(1, 1, At, B1); PG8_BAR; PG8_SCHED;
;             PG8_LDB(B0, 1, 0); PG8_LDB(B1, 1, 1); PG8_SCHED; PG8_LDA(At, 1, 0); PG8_STAGE(PG8_SA(0, 1), a2 + hstepA, voffA);
;             PG8_WAIT_V(8); PG8_WAIT_L(0); PG8_BAR; PG8_MMA(0, 0, At, B0); PG8_MMA(0, 1, At, B1); PG8_BAR; PG8_SCHED;
	s_setprio 1
	s_waitcnt lgkmcnt(0)
	v_mfma_f32_16x16x32_bf16 v[62:65], v[146:149], v[188:191], v[62:65]
	v_mfma_f32_16x16x32_bf16 v[58:61], v[162:165], v[188:191], v[58:61]
	v_mfma_f32_16x16x32_bf16 v[46:49], v[146:149], v[196:199], v[46:49]
	v_mfma_f32_16x16x32_bf16 v[42:45], v[162:165], v[196:199], v[42:45]
	v_mfma_f32_16x16x32_bf16 v[30:33], v[146:149], v[204:207], v[30:33]
	v_mfma_f32_16x16x32_bf16 v[26:29], v[162:165], v[204:207], v[26:29]
	v_mfma_f32_16x16x32_bf16 v[14:17], v[146:149], v[212:215], v[14:17]
	v_mfma_f32_16x16x32_bf16 v[10:13], v[162:165], v[212:215], v[10:13]
	v_mfma_f32_16x16x32_bf16 v[62:65], v[158:161], v[192:195], v[62:65]
	v_mfma_f32_16x16x32_bf16 v[58:61], v[166:169], v[192:195], v[58:61]
	v_mfma_f32_16x16x32_bf16 v[46:49], v[158:161], v[200:203], v[46:49]
	v_mfma_f32_16x16x32_bf16 v[42:45], v[166:169], v[200:203], v[42:45]
	v_mfma_f32_16x16x32_bf16 v[30:33], v[158:161], v[208:211], v[30:33]
	v_mfma_f32_16x16x32_bf16 v[26:29], v[166:169], v[208:211], v[26:29]
	v_mfma_f32_16x16x32_bf16 v[14:17], v[158:161], v[220:223], v[14:17]
	v_mfma_f32_16x16x32_bf16 v[10:13], v[166:169], v[220:223], v[10:13]
	s_setprio 0
	s_setprio 1
	v_mfma_f32_16x16x32_bf16 v[54:57], v[170:173], v[188:191], v[54:57]
	v_mfma_f32_16x16x32_bf16 v[50:53], v[180:183], v[188:191], v[50:53]
	v_mfma_f32_16x16x32_bf16 v[38:41], v[170:173], v[196:199], v[38:41]
	v_mfma_f32_16x16x32_bf16 v[34:37], v[180:183], v[196:199], v[34:37]
	v_mfma_f32_16x16x32_bf16 v[22:25], v[170:173], v[204:207], v[22:25]
	v_mfma_f32_16x16x32_bf16 v[18:21], v[180:183], v[204:207], v[18:21]
	v_mfma_f32_16x16x32_bf16 v[6:9], v[170:173], v[212:215], v[6:9]
	v_mfma_f32_16x16x32_bf16 v[2:5], v[180:183], v[212:215], v[2:5]
	v_mfma_f32_16x16x32_bf16 v[54:57], v[176:179], v[192:195], v[54:57]
	v_mfma_f32_16x16x32_bf16 v[50:53], v[184:187], v[192:195], v[50:53]
	v_mfma_f32_16x16x32_bf16 v[38:41], v[176:179], v[200:203], v[38:41]
	v_mfma_f32_16x16x32_bf16 v[34:37], v[184:187], v[200:203], v[34:37]
	v_mfma_f32_16x16x32_bf16 v[22:25], v[176:179], v[208:211], v[22:25]
	v_mfma_f32_16x16x32_bf16 v[18:21], v[184:187], v[208:211], v[18:21]
	v_mfma_f32_16x16x32_bf16 v[6:9], v[176:179], v[220:223], v[6:9]
	v_mfma_f32_16x16x32_bf16 v[2:5], v[184:187], v[220:223], v[2:5]
	s_setprio 0
	s_barrier
	ds_read_b128 v[146:149], v155
	ds_read_b128 v[158:161], v155 offset:1024
	ds_read_b128 v[162:165], v155 offset:2048
	ds_read_b128 v[166:169], v155 offset:3072
	ds_read_b128 v[170:173], v156
	ds_read_b128 v[176:179], v156 offset:1024
	ds_read_b128 v[180:183], v156 offset:2048
	ds_read_b128 v[184:187], v156 offset:3072
	s_add_u32 s20, s26, 0x18000
	s_addc_u32 s21, s27, 0
	s_mov_b32 m0, s36
	v_lshl_add_u64 v[230:231], s[20:21], 0, v[136:137]
	ds_read_b128 v[188:191], v154 offset:32768
	ds_read_b128 v[192:195], v154 offset:33792
	ds_read_b128 v[196:199], v154 offset:34816
	ds_read_b128 v[200:203], v154 offset:35840
	ds_read_b128 v[204:207], v154 offset:36864
	ds_read_b128 v[208:211], v154 offset:37888
	ds_read_b128 v[212:215], v154 offset:38912
	ds_read_b128 v[220:223], v154 offset:39936
	global_load_lds_dwordx4 v[230:231], off
	v_lshl_add_u64 v[230:231], s[20:21], 0, v[132:133]
	s_mov_b32 m0, s37
	s_nop 0
	global_load_lds_dwordx4 v[230:231], off
	s_waitcnt vmcnt(8)
	s_waitcnt lgkmcnt(0)
	s_barrier
	s_setprio 1
	s_waitcnt lgkmcnt(0)
	v_mfma_f32_16x16x32_bf16 v[126:129], v[146:149], v[188:191], v[126:129]
	v_mfma_f32_16x16x32_bf16 v[122:125], v[162:165], v[188:191], v[122:125]
	v_mfma_f32_16x16x32_bf16 v[110:113], v[146:149], v[196:199], v[110:113]
	v_mfma_f32_16x16x32_bf16 v[106:109], v[162:165], v[196:199], v[106:109]
	v_mfma_f32_16x16x32_bf16 v[94:97], v[146:149], v[204:207], v[94:97]
	v_mfma_f32_16x16x32_bf16 v[90:93], v[162:165], v[204:207], v[90:93]
	v_mfma_f32_16x16x32_bf16 v[78:81], v[146:149], v[212:215], v[78:81]
	v_mfma_f32_16x16x32_bf16 v[74:77], v[162:165], v[212:215], v[74:77]
	v_mfma_f32_16x16x32_bf16 v[126:129], v[158:161], v[192:195], v[126:129]
	v_mfma_f32_16x16x32_bf16 v[122:125], v[166:169], v[192:195], v[122:125]
	v_mfma_f32_16x16x32_bf16 v[110:113], v[158:161], v[200:203], v[110:113]
	v_mfma_f32_16x16x32_bf16 v[106:109], v[166:169], v[200:203], v[106:109]
	v_mfma_f32_16x16x32_bf16 v[94:97], v[158:161], v[208:211], v[94:97]
	v_mfma_f32_16x16x32_bf16 v[90:93], v[166:169], v[208:211], v[90:93]
	v_mfma_f32_16x16x32_bf16 v[78:81], v[158:161], v[220:223], v[78:81]
	v_mfma_f32_16x16x32_bf16 v[74:77], v[166:169], v[220:223], v[74:77]
	s_setprio 0
	s_setprio 1
	v_mfma_f32_16x16x32_bf16 v[118:121], v[170:173], v[188:191], v[118:121]
	v_mfma_f32_16x16x32_bf16 v[114:117], v[180:183], v[188:191], v[114:117]
	v_mfma_f32_16x16x32_bf16 v[102:105], v[170:173], v[196:199], v[102:105]
	v_mfma_f32_16x16x32_bf16 v[98:101], v[180:183], v[196:199], v[98:101]
	v_mfma_f32_16x16x32_bf16 v[86:89], v[170:173], v[204:207], v[86:89]
	v_mfma_f32_16x16x32_bf16 v[82:85], v[180:183], v[204:207], v[82:85]
	v_mfma_f32_16x16x32_bf16 v[70:73], v[170:173], v[212:215], v[70:73]
	v_mfma_f32_16x16x32_bf16 v[66:69], v[180:183], v[212:215], v[66:69]
	v_mfma_f32_16x16x32_bf16 v[118:121], v[176:179], v[192:195], v[118:121]
	v_mfma_f32_16x16x32_bf16 v[114:117], v[184:187], v[192:195], v[114:117]
	v_mfma_f32_16x16x32_bf16 v[102:105], v[176:179], v[200:203], v[102:105]
	v_mfma_f32_16x16x32_bf16 v[98:101], v[184:187], v[200:203], v[98:101]
	v_mfma_f32_16x16x32_bf16 v[86:89], v[176:179], v[208:211], v[86:89]
	v_mfma_f32_16x16x32_bf16 v[82:85], v[184:187], v[208:211], v[82:85]
	v_mfma_f32_16x16x32_bf16 v[70:73], v[176:179], v[220:223], v[70:73]
	v_mfma_f32_16x16x32_bf16 v[66:69], v[184:187], v[220:223], v[66:69]
	s_setprio 0
	s_barrier
; #define PG8_STAGE(bufoff, gbase, voff) do { _Pragma("unroll") for (int _i = 0; _i < 2; ++_i) \
;         __builtin_amdgcn_global_load_lds((const unsigned*)((const char*)(gbase) + (voff)[_i]), (PG8_LAS unsigned*)(lds + (bufoff) + ldsw + _i * 8192), 16, 0, 0); } while (0)
; #define PG8_LDA(dst, b, h) do { _Pragma("unroll") for (int m = 0; m < 4; ++m) _Pragma("unroll") for (int k = 0; k < 2; ++k) dst[m][k] = *(const PG8_LAS bf16x8*)(lds + PG8_SA(b, h) + aoff + m * 2048 + k * 1024); } while (0)
; #define PG8_MMA(ai, bj, At, Bt) do { __builtin_amdgcn_s_setprio(1); _Pragma("unroll") for (int m = 0; m < 4; ++m) _Pragma("unroll") for (int n = 0; n < 2; ++n) _Pragma("unroll") for (int k = 0; k < 2; ++k) \
;         acc[ai][bj][m][n] = __builtin_amdgcn_mfma_f32_16x16x32_bf16(Bt[n][k], At[m][k], acc[ai][bj][m][n], 0, 0, 0); __builtin_amdgcn_s_setprio(0); } while (0)
; #define PG8_WAIT_V(n) asm volatile("s_waitcnt vmcnt(" #n ")" ::: "memory")
; #define PG8_WAIT_L(n) asm volatile("s_waitcnt lgkmcnt(" #n ")" ::: "memory")
; #define PG8_BAR __builtin_amdgcn_s_barrier()
; #define PG8_SCHED __builtin_amdgcn_sched_barrier(0)
; template <class Epi, class Sched, bool ALIGN_EPI = false, bool SP2 = false>
; __device__ __forceinline__ void gemm_phase(PG8_LAS unsigned char* lds, const Gemm g, const Sched& S, const Epi& E) {
;     ...
;         for (int t = 0; t < nt; t += 2) {
;             const bool last = (t == nt - 2);
;     ...
;             PG8_LDA(At, 1, 1); PG8_STAGE(PG8_SB(1, 0), b3, voffB); PG8_STAGE(PG8_SB(1, 1), b3 + hstepB, voffB); PG8_STAGE(PG8_SA(1, 0), a3, voffA);
;             PG8_WAIT_V(8); PG8_WAIT_L(0); PG8_BAR; PG8_MMA(1, 0, At, B0); PG8_MMA(1, 1, At, B1); PG8_BAR; PG8_SCHED;
	s_mov_b32 m0, s56
	v_lshl_add_u64 v[216:217], v[216:217], 0, s[12:13]
	s_add_u32 s20, s24, 0x18080
	ds_read_b128 v[188:191], v154 offset:49152
	ds_read_b128 v[192:195], v154 offset:50176
	ds_read_b128 v[196:199], v154 offset:51200
	ds_read_b128 v[200:203], v154 offset:52224
	ds_read_b128 v[204:207], v154 offset:53248
	ds_read_b128 v[208:211], v154 offset:54272
	ds_read_b128 v[212:215], v154 offset:55296
	ds_read_b128 v[220:223], v154 offset:56320
	global_load_lds_dwordx4 v[216:217], off
	v_lshl_add_u64 v[216:217], v[224:225], 0, s[12:13]
	s_mov_b32 m0, s57
	s_addc_u32 s21, s25, 0
	global_load_lds_dwordx4 v[216:217], off
	v_lshl_add_u64 v[216:217], s[20:21], 0, v[134:135]
	s_mov_b32 m0, s58
	s_nop 0
	global_load_lds_dwordx4 v[216:217], off
	v_lshl_add_u64 v[216:217], s[20:21], 0, v[130:131]
	s_mov_b32 m0, s59
	s_nop 0
	global_load_lds_dwordx4 v[216:217], off
	v_lshl_add_u64 v[216:217], v[226:227], 0, s[12:13]
	s_mov_b32 m0, s41
	s_nop 0
	global_load_lds_dwordx4 v[216:217], off
	v_lshl_add_u64 v[216:217], v[228:229], 0, s[12:13]
	s_mov_b32 m0, s42
	s_nop 0
	global_load_lds_dwordx4 v[216:217], off
	s_waitcnt vmcnt(8)
	s_waitcnt lgkmcnt(0)
	s_barrier
	s_setprio 1
	s_waitcnt lgkmcnt(0)
	v_mfma_f32_16x16x32_bf16 v[62:65], v[146:149], v[188:191], v[62:65]
	v_mfma_f32_16x16x32_bf16 v[58:61], v[162:165], v[188:191], v[58:61]
	v_mfma_f32_16x16x32_bf16 v[46:49], v[146:149], v[196:199], v[46:49]
	v_mfma_f32_16x16x32_bf16 v[42:45], v[162:165], v[196:199], v[42:45]
	v_mfma_f32_16x16x32_bf16 v[30:33], v[146:149], v[204:207], v[30:33]
	v_mfma_f32_16x16x32_bf16 v[26:29], v[162:165], v[204:207], v[26:29]
	v_mfma_f32_16x16x32_bf16 v[14:17], v[146:149], v[212:215], v[14:17]
	v_mfma_f32_16x16x32_bf16 v[10:13], v[162:165], v[212:215], v[10:13]
	v_mfma_f32_16x16x32_bf16 v[62:65], v[158:161], v[192:195], v[62:65]
	v_mfma_f32_16x16x32_bf16 v[58:61], v[166:169], v[192:195], v[58:61]
	v_mfma_f32_16x16x32_bf16 v[46:49], v[158:161], v[200:203], v[46:49]
	v_mfma_f32_16x16x32_bf16 v[42:45], v[166:169], v[200:203], v[42:45]
	v_mfma_f32_16x16x32_bf16 v[30:33], v[158:161], v[208:211], v[30:33]
	v_mfma_f32_16x16x32_bf16 v[26:29], v[166:169], v[208:211], v[26:29]
	v_mfma_f32_16x16x32_bf16 v[14:17], v[158:161], v[220:223], v[14:17]
	v_mfma_f32_16x16x32_bf16 v[10:13], v[166:169], v[220:223], v[10:13]
	s_setprio 0
	s_setprio 1
	v_mfma_f32_16x16x32_bf16 v[54:57], v[170:173], v[188:191], v[54:57]
	v_mfma_f32_16x16x32_bf16 v[50:53], v[180:183], v[188:191], v[50:53]
	v_mfma_f32_16x16x32_bf16 v[38:41], v[170:173], v[196:199], v[38:41]
	v_mfma_f32_16x16x32_bf16 v[34:37], v[180:183], v[196:199], v[34:37]
	v_mfma_f32_16x16x32_bf16 v[22:25], v[170:173], v[204:207], v[22:25]
	v_mfma_f32_16x16x32_bf16 v[18:21], v[180:183], v[204:207], v[18:21]
	v_mfma_f32_16x16x32_bf16 v[6:9], v[170:173], v[212:215], v[6:9]
	v_mfma_f32_16x16x32_bf16 v[2:5], v[180:183], v[212:215], v[2:5]
	v_mfma_f32_16x16x32_bf16 v[54:57], v[176:179], v[192:195], v[54:57]
	v_mfma_f32_16x16x32_bf16 v[50:53], v[184:187], v[192:195], v[50:53]
	v_mfma_f32_16x16x32_bf16 v[38:41], v[176:179], v[200:203], v[38:41]
	v_mfma_f32_16x16x32_bf16 v[34:37], v[184:187], v[200:203], v[34:37]
	v_mfma_f32_16x16x32_bf16 v[22:25], v[176:179], v[208:211], v[22:25]
	v_mfma_f32_16x16x32_bf16 v[18:21], v[184:187], v[208:211], v[18:21]
	v_mfma_f32_16x16x32_bf16 v[6:9], v[176:179], v[220:223], v[6:9]
	v_mfma_f32_16x16x32_bf16 v[2:5], v[184:187], v[220:223], v[2:5]
	s_setprio 0
	s_add_i32 s61, s61, 2
	s_add_u32 s38, s38, 0x100
	s_addc_u32 s39, s39, 0
	s_cmp_gt_u32 s61, 3
	s_mov_b64 s[20:21], s[22:23]
	s_barrier
	s_cbranch_scc0 .LBB0_686
	s_and_b64 vcc, exec, s[14:15]
	s_cbranch_vccz .LBB0_689
	s_barrier

; #define PG8_STAGE(bufoff, gbase, voff) do { _Pragma("unroll") for (int _i = 0; _i < 2; ++_i) \
;         __builtin_amdgcn_global_load_lds((const unsigned*)((const char*)(gbase) + (voff)[_i]), (PG8_LAS unsigned*)(lds + (bufoff) + ldsw + _i * 8192), 16, 0, 0); } while (0)
; #define PG8_LDA(dst, b, h) do { _Pragma("unroll") for (int m = 0; m < 4; ++m) _Pragma("unroll") for (int k = 0; k < 2; ++k) dst[m][k] = *(const PG8_LAS bf16x8*)(lds + PG8_SA(b, h) + aoff + m * 2048 + k * 1024); } while (0)
; #define PG8_LDB(dst, b, h) do { _Pragma("unroll") for (int n = 0; n < 2; ++n) _Pragma("unroll") for (int k = 0; k < 2; ++k) dst[n][k] = *(const PG8_LAS bf16x8*)(lds + PG8_SB(b, h) + boff + n * 2048 + k * 1024); } while (0)
; #define PG8_MMA(ai, bj, At, Bt) do { __builtin_amdgcn_s_setprio(1); _Pragma("unroll") for (int m = 0; m < 4; ++m) _Pragma("unroll") for (int n = 0; n < 2; ++n) _Pragma("unroll") for (int k = 0; k < 2; ++k) \
;         acc[ai][bj][m][n] = __builtin_amdgcn_mfma_f32_16x16x32_bf16(Bt[n][k], At[m][k], acc[ai][bj][m][n], 0, 0, 0); __builtin_amdgcn_s_setprio(0); } while (0)
; #define PG8_WAIT_V(n) asm volatile("s_waitcnt vmcnt(" #n ")" ::: "memory")
; #define PG8_WAIT_L(n) asm volatile("s_waitcnt lgkmcnt(" #n ")" ::: "memory")
; #define PG8_BAR __builtin_amdgcn_s_barrier()
; #define PG8_SCHED __builtin_amdgcn_sched_barrier(0)
; template <class Epi, class Sched, bool ALIGN_EPI = false, bool SP2 = false>
; __device__ __forceinline__ void gemm_phase(PG8_LAS unsigned char* lds, const Gemm g, const Sched& S, const Epi& E) {
;     ...
;         for (int t = 0; t < nt; t += 2) {
;             const bool last = (t == nt - 2);
;             const char* a1 = cA + (size_t)(t + 1) * kstep;
;             const char* a2 = last ? nA : cA + (size_t)(t + 2) * kstep; const char* b2 = last ? nB : cB + (size_t)(t + 2) * kstep;
;             const char* a3 = a2 + kstep; const char* b3 = b2 + kstep;
;             if (last && has_next) S.a_ready(nxt);
;             if constexpr (SP2) {
;             PG8_LDB(B0, 0, 0); PG8_LDB(B1, 0, 1); PG8_SCHED; PG8_LDA(At, 0, 0); PG8_STAGE(PG8_SA(1, 1), a1 + hstepA, voffA);
;             PG8_WAIT_V(8); PG8_WAIT_L(0); PG8_BAR; PG8_MMA(0, 0, At, B0); PG8_MMA(0, 1, At, B1); PG8_BAR; PG8_SCHED;
;             PG8_LDA(At, 0, 1); PG8_STAGE(PG8_SB(0, 0), b2, voffB); PG8_STAGE(PG8_SB(0, 1), b2 + hstepB, voffB); PG8_STAGE(PG8_SA(0, 0), a2, voffA);
.LBB0_851:
	ds_read_b128 v[130:133], v166
	ds_read_b128 v[134:137], v166 offset:1024
	ds_read_b128 v[154:157], v166 offset:2048
	ds_read_b128 v[158:161], v166 offset:3072
	ds_read_b128 v[170:173], v167
	ds_read_b128 v[176:179], v167 offset:1024
	ds_read_b128 v[180:183], v167 offset:2048
	ds_read_b128 v[184:187], v167 offset:3072
	s_add_u32 s42, s40, 0xfffe0080
	s_addc_u32 s43, s41, -1
	s_cmp_eq_u32 s63, 4
	s_cselect_b32 s45, s29, s43
	s_cselect_b32 s44, s38, s42
	s_cselect_b32 s43, s27, s62
	s_cselect_b32 s42, s39, s61
	v_lshl_add_u64 v[162:163], s[40:41], 0, v[146:147]
	s_add_i32 m0, s37, 0xc000
	ds_read_b128 v[188:191], v168
	ds_read_b128 v[192:195], v168 offset:1024
	ds_read_b128 v[196:199], v168 offset:2048
	ds_read_b128 v[200:203], v168 offset:3072
	ds_read_b128 v[204:207], v168 offset:4096
	ds_read_b128 v[208:211], v168 offset:5120
	ds_read_b128 v[212:215], v168 offset:6144
	ds_read_b128 v[220:223], v168 offset:7168
	global_load_lds_dwordx4 v[162:163], off
	v_lshl_add_u64 v[162:163], s[40:41], 0, v[148:149]
	s_add_i32 m0, s37, 0xe000
	s_nop 0
	global_load_lds_dwordx4 v[162:163], off
	s_waitcnt vmcnt(8)
	s_waitcnt lgkmcnt(0)
	s_barrier
	s_setprio 1
	s_waitcnt lgkmcnt(0)
	v_mfma_f32_16x16x32_bf16 v[126:129], v[130:133], v[188:191], v[126:129]
	v_mfma_f32_16x16x32_bf16 v[122:125], v[154:157], v[188:191], v[122:125]
	v_mfma_f32_16x16x32_bf16 v[110:113], v[130:133], v[196:199], v[110:113]
	v_mfma_f32_16x16x32_bf16 v[106:109], v[154:157], v[196:199], v[106:109]
	v_mfma_f32_16x16x32_bf16 v[94:97], v[130:133], v[204:207], v[94:97]
	v_mfma_f32_16x16x32_bf16 v[90:93], v[154:157], v[204:207], v[90:93]
	v_mfma_f32_16x16x32_bf16 v[78:81], v[130:133], v[212:215], v[78:81]
	v_mfma_f32_16x16x32_bf16 v[74:77], v[154:157], v[212:215], v[74:77]
	v_mfma_f32_16x16x32_bf16 v[126:129], v[134:137], v[192:195], v[126:129]
	v_mfma_f32_16x16x32_bf16 v[122:125], v[158:161], v[192:195], v[122:125]
	v_mfma_f32_16x16x32_bf16 v[110:113], v[134:137], v[200:203], v[110:113]
	v_mfma_f32_16x16x32_bf16 v[106:109], v[158:161], v[200:203], v[106:109]
	v_mfma_f32_16x16x32_bf16 v[94:97], v[134:137], v[208:211], v[94:97]
	v_mfma_f32_16x16x32_bf16 v[90:93], v[158:161], v[208:211], v[90:93]
	v_mfma_f32_16x16x32_bf16 v[78:81], v[134:137], v[220:223], v[78:81]
	v_mfma_f32_16x16x32_bf16 v[74:77], v[158:161], v[220:223], v[74:77]
	s_setprio 0
	s_setprio 1
	v_mfma_f32_16x16x32_bf16 v[118:121], v[170:173], v[188:191], v[118:121]
	v_mfma_f32_16x16x32_bf16 v[114:117], v[180:183], v[188:191], v[114:117]
	v_mfma_f32_16x16x32_bf16 v[102:105], v[170:173], v[196:199], v[102:105]
	v_mfma_f32_16x16x32_bf16 v[98:101], v[180:183], v[196:199], v[98:101]
	v_mfma_f32_16x16x32_bf16 v[86:89], v[170:173], v[204:207], v[86:89]
	v_mfma_f32_16x16x32_bf16 v[82:85], v[180:183], v[204:207], v[82:85]
	v_mfma_f32_16x16x32_bf16 v[70:73], v[170:173], v[212:215], v[70:73]
	v_mfma_f32_16x16x32_bf16 v[66:69], v[180:183], v[212:215], v[66:69]
	v_mfma_f32_16x16x32_bf16 v[118:121], v[176:179], v[192:195], v[118:121]
	v_mfma_f32_16x16x32_bf16 v[114:117], v[184:187], v[192:195], v[114:117]
	v_mfma_f32_16x16x32_bf16 v[102:105], v[176:179], v[200:203], v[102:105]
	v_mfma_f32_16x16x32_bf16 v[98:101], v[184:187], v[200:203], v[98:101]
	v_mfma_f32_16x16x32_bf16 v[86:89], v[176:179], v[208:211], v[86:89]
	v_mfma_f32_16x16x32_bf16 v[82:85], v[184:187], v[208:211], v[82:85]
	v_mfma_f32_16x16x32_bf16 v[70:73], v[176:179], v[220:223], v[70:73]
	v_mfma_f32_16x16x32_bf16 v[66:69], v[184:187], v[220:223], v[66:69]
	s_setprio 0
	s_barrier
	s_add_i32 s64, s59, s51
	v_lshl_add_u64 v[162:163], s[42:43], 0, v[140:141]
	s_mov_b32 m0, s64
	ds_read_b128 v[188:191], v168 offset:16384
	ds_read_b128 v[192:195], v168 offset:17408
	ds_read_b128 v[196:199], v168 offset:18432
	ds_read_b128 v[200:203], v168 offset:19456
	ds_read_b128 v[204:207], v168 offset:20480
	ds_read_b128 v[208:211], v168 offset:21504
	ds_read_b128 v[212:215], v168 offset:22528
	ds_read_b128 v[220:223], v168 offset:23552
	global_load_lds_dwordx4 v[162:163], off
	s_add_i32 m0, s64, 0x2000
	s_add_u32 s64, s42, 0x20000
	v_lshl_add_u64 v[216:217], s[42:43], 0, v[144:145]
	s_addc_u32 s65, s43, 0
	s_add_i32 s66, s60, s51
	global_load_lds_dwordx4 v[216:217], off
	v_lshl_add_u64 v[224:225], s[64:65], 0, v[140:141]
	s_mov_b32 m0, s66
	v_lshl_add_u64 v[226:227], s[44:45], 0, v[142:143]
	global_load_lds_dwordx4 v[224:225], off
	v_lshl_add_u64 v[224:225], s[64:65], 0, v[144:145]
	s_add_i32 m0, s66, 0x2000
	s_nop 0
	global_load_lds_dwordx4 v[224:225], off
	v_lshl_add_u64 v[224:225], s[44:45], 0, v[138:139]
	s_mov_b32 m0, s37
	s_nop 0
	global_load_lds_dwordx4 v[224:225], off
	s_mov_b32 m0, s52
	s_nop 0
	global_load_lds_dwordx4 v[226:227], off
	s_waitcnt vmcnt(8)
	s_waitcnt lgkmcnt(0)
	s_barrier
; #define PG8_STAGE(bufoff, gbase, voff) do { _Pragma("unroll") for (int _i = 0; _i < 2; ++_i) \
;         __builtin_amdgcn_global_load_lds((const unsigned*)((const char*)(gbase) + (voff)[_i]), (PG8_LAS unsigned*)(lds + (bufoff) + ldsw + _i * 8192), 16, 0, 0); } while (0)
; #define PG8_LDA(dst, b, h) do { _Pragma("unroll") for (int m = 0; m < 4; ++m) _Pragma("unroll") for (int k = 0; k < 2; ++k) dst[m][k] = *(const PG8_LAS bf16x8*)(lds + PG8_SA(b, h) + aoff + m * 2048 + k * 1024); } while (0)
; #define PG8_LDB(dst, b, h) do { _Pragma("unroll") for (int n = 0; n < 2; ++n) _Pragma("unroll") for (int k = 0; k < 2; ++k) dst[n][k] = *(const PG8_LAS bf16x8*)(lds + PG8_SB(b, h) + boff + n * 2048 + k * 1024); } while (0)
; #define PG8_MMA(ai, bj, At, Bt) do { __builtin_amdgcn_s_setprio(1); _Pragma("unroll") for (int m = 0; m < 4; ++m) _Pragma("unroll") for (int n = 0; n < 2; ++n) _Pragma("unroll") for (int k = 0; k < 2; ++k) \
;         acc[ai][bj][m][n] = __builtin_amdgcn_mfma_f32_16x16x32_bf16(Bt[n][k], At[m][k], acc[ai][bj][m][n], 0, 0, 0); __builtin_amdgcn_s_setprio(0); } while (0)
; #define PG8_WAIT_V(n) asm volatile("s_waitcnt vmcnt(" #n ")" ::: "memory")
; #define PG8_WAIT_L(n) asm volatile("s_waitcnt lgkmcnt(" #n ")" ::: "memory")
; #define PG8_BAR __builtin_amdgcn_s_barrier()
; #define PG8_SCHED __builtin_amdgcn_sched_barrier(0)
; template <class Epi, class Sched, bool ALIGN_EPI = false, bool SP2 = false>
; __device__ __forceinline__ void gemm_phase(PG8_LAS unsigned char* lds, const Gemm g, const Sched& S, const Epi& E) {
;     ...
;             PG8_WAIT_V(8); PG8_WAIT_L(0); PG8_BAR; PG8_MMA(1, 0, At, B0); PG8_MMA(1, 1, At, B1); PG8_BAR; PG8_SCHED;
;             PG8_LDB(B0, 1, 0); PG8_LDB(B1, 1, 1); PG8_SCHED; PG8_LDA(At, 1, 0); PG8_STAGE(PG8_SA(0, 1), a2 + hstepA, voffA);
;             PG8_WAIT_V(8); PG8_WAIT_L(0); PG8_BAR; PG8_MMA(0, 0, At, B0); PG8_MMA(0, 1, At, B1); PG8_BAR; PG8_SCHED;
	s_setprio 1
	s_waitcnt lgkmcnt(0)
	v_mfma_f32_16x16x32_bf16 v[62:65], v[130:133], v[188:191], v[62:65]
	v_mfma_f32_16x16x32_bf16 v[58:61], v[154:157], v[188:191], v[58:61]
	v_mfma_f32_16x16x32_bf16 v[46:49], v[130:133], v[196:199], v[46:49]
	v_mfma_f32_16x16x32_bf16 v[42:45], v[154:157], v[196:199], v[42:45]
	v_mfma_f32_16x16x32_bf16 v[30:33], v[130:133], v[204:207], v[30:33]
	v_mfma_f32_16x16x32_bf16 v[26:29], v[154:157], v[204:207], v[26:29]
	v_mfma_f32_16x16x32_bf16 v[14:17], v[130:133], v[212:215], v[14:17]
	v_mfma_f32_16x16x32_bf16 v[10:13], v[154:157], v[212:215], v[10:13]
	v_mfma_f32_16x16x32_bf16 v[62:65], v[134:137], v[192:195], v[62:65]
	v_mfma_f32_16x16x32_bf16 v[58:61], v[158:161], v[192:195], v[58:61]
	v_mfma_f32_16x16x32_bf16 v[46:49], v[134:137], v[200:203], v[46:49]
	v_mfma_f32_16x16x32_bf16 v[42:45], v[158:161], v[200:203], v[42:45]
	v_mfma_f32_16x16x32_bf16 v[30:33], v[134:137], v[208:211], v[30:33]
	v_mfma_f32_16x16x32_bf16 v[26:29], v[158:161], v[208:211], v[26:29]
	v_mfma_f32_16x16x32_bf16 v[14:17], v[134:137], v[220:223], v[14:17]
	v_mfma_f32_16x16x32_bf16 v[10:13], v[158:161], v[220:223], v[10:13]
	s_setprio 0
	s_setprio 1
	v_mfma_f32_16x16x32_bf16 v[54:57], v[170:173], v[188:191], v[54:57]
	v_mfma_f32_16x16x32_bf16 v[50:53], v[180:183], v[188:191], v[50:53]
	v_mfma_f32_16x16x32_bf16 v[38:41], v[170:173], v[196:199], v[38:41]
	v_mfma_f32_16x16x32_bf16 v[34:37], v[180:183], v[196:199], v[34:37]
	v_mfma_f32_16x16x32_bf16 v[22:25], v[170:173], v[204:207], v[22:25]
	v_mfma_f32_16x16x32_bf16 v[18:21], v[180:183], v[204:207], v[18:21]
	v_mfma_f32_16x16x32_bf16 v[6:9], v[170:173], v[212:215], v[6:9]
	v_mfma_f32_16x16x32_bf16 v[2:5], v[180:183], v[212:215], v[2:5]
	v_mfma_f32_16x16x32_bf16 v[54:57], v[176:179], v[192:195], v[54:57]
	v_mfma_f32_16x16x32_bf16 v[50:53], v[184:187], v[192:195], v[50:53]
	v_mfma_f32_16x16x32_bf16 v[38:41], v[176:179], v[200:203], v[38:41]
	v_mfma_f32_16x16x32_bf16 v[34:37], v[184:187], v[200:203], v[34:37]
	v_mfma_f32_16x16x32_bf16 v[22:25], v[176:179], v[208:211], v[22:25]
	v_mfma_f32_16x16x32_bf16 v[18:21], v[184:187], v[208:211], v[18:21]
	v_mfma_f32_16x16x32_bf16 v[6:9], v[176:179], v[220:223], v[6:9]
	v_mfma_f32_16x16x32_bf16 v[2:5], v[184:187], v[220:223], v[2:5]
	s_setprio 0
	s_barrier
	s_add_i32 s64, 0, 0x18000
	s_add_i32 s65, 0, 0x1c000
	v_add_u32_e32 v158, s64, v164
	v_add_u32_e32 v169, s65, v164
	ds_read_b128 v[130:133], v158
	ds_read_b128 v[134:137], v158 offset:1024
	ds_read_b128 v[154:157], v158 offset:2048
	ds_read_b128 v[158:161], v158 offset:3072
	ds_read_b128 v[170:173], v169
	ds_read_b128 v[176:179], v169 offset:1024
	ds_read_b128 v[180:183], v169 offset:2048
	ds_read_b128 v[184:187], v169 offset:3072
	s_add_u32 s44, s44, 0x20000
	s_addc_u32 s45, s45, 0
	s_mov_b32 m0, s53
	v_lshl_add_u64 v[228:229], s[44:45], 0, v[138:139]
	ds_read_b128 v[188:191], v168 offset:32768
	ds_read_b128 v[192:195], v168 offset:33792
	ds_read_b128 v[196:199], v168 offset:34816
	ds_read_b128 v[200:203], v168 offset:35840
	ds_read_b128 v[204:207], v168 offset:36864
	ds_read_b128 v[208:211], v168 offset:37888
	ds_read_b128 v[212:215], v168 offset:38912
	ds_read_b128 v[220:223], v168 offset:39936
	global_load_lds_dwordx4 v[228:229], off
	v_lshl_add_u64 v[228:229], s[44:45], 0, v[142:143]
	s_mov_b32 m0, s54
	s_nop 0
	global_load_lds_dwordx4 v[228:229], off
	s_waitcnt vmcnt(8)
	s_waitcnt lgkmcnt(0)
	s_barrier
	s_setprio 1
	s_waitcnt lgkmcnt(0)
	v_mfma_f32_16x16x32_bf16 v[126:129], v[130:133], v[188:191], v[126:129]
	v_mfma_f32_16x16x32_bf16 v[122:125], v[154:157], v[188:191], v[122:125]
	v_mfma_f32_16x16x32_bf16 v[110:113], v[130:133], v[196:199], v[110:113]
	v_mfma_f32_16x16x32_bf16 v[106:109], v[154:157], v[196:199], v[106:109]
	v_mfma_f32_16x16x32_bf16 v[94:97], v[130:133], v[204:207], v[94:97]
	v_mfma_f32_16x16x32_bf16 v[90:93], v[154:157], v[204:207], v[90:93]
	v_mfma_f32_16x16x32_bf16 v[78:81], v[130:133], v[212:215], v[78:81]
	v_mfma_f32_16x16x32_bf16 v[74:77], v[154:157], v[212:215], v[74:77]
	v_mfma_f32_16x16x32_bf16 v[126:129], v[134:137], v[192:195], v[126:129]
	v_mfma_f32_16x16x32_bf16 v[122:125], v[158:161], v[192:195], v[122:125]
	v_mfma_f32_16x16x32_bf16 v[110:113], v[134:137], v[200:203], v[110:113]
	v_mfma_f32_16x16x32_bf16 v[106:109], v[158:161], v[200:203], v[106:109]
	v_mfma_f32_16x16x32_bf16 v[94:97], v[134:137], v[208:211], v[94:97]
	v_mfma_f32_16x16x32_bf16 v[90:93], v[158:161], v[208:211], v[90:93]
	v_mfma_f32_16x16x32_bf16 v[78:81], v[134:137], v[220:223], v[78:81]
	v_mfma_f32_16x16x32_bf16 v[74:77], v[158:161], v[220:223], v[74:77]
	s_setprio 0
	s_setprio 1
	v_mfma_f32_16x16x32_bf16 v[118:121], v[170:173], v[188:191], v[118:121]
	v_mfma_f32_16x16x32_bf16 v[114:117], v[180:183], v[188:191], v[114:117]
	v_mfma_f32_16x16x32_bf16 v[102:105], v[170:173], v[196:199], v[102:105]
	v_mfma_f32_16x16x32_bf16 v[98:101], v[180:183], v[196:199], v[98:101]
	v_mfma_f32_16x16x32_bf16 v[86:89], v[170:173], v[204:207], v[86:89]
	v_mfma_f32_16x16x32_bf16 v[82:85], v[180:183], v[204:207], v[82:85]
	v_mfma_f32_16x16x32_bf16 v[70:73], v[170:173], v[212:215], v[70:73]
	v_mfma_f32_16x16x32_bf16 v[66:69], v[180:183], v[212:215], v[66:69]
	v_mfma_f32_16x16x32_bf16 v[118:121], v[176:179], v[192:195], v[118:121]
	v_mfma_f32_16x16x32_bf16 v[114:117], v[184:187], v[192:195], v[114:117]
	v_mfma_f32_16x16x32_bf16 v[102:105], v[176:179], v[200:203], v[102:105]
	v_mfma_f32_16x16x32_bf16 v[98:101], v[184:187], v[200:203], v[98:101]
	v_mfma_f32_16x16x32_bf16 v[86:89], v[176:179], v[208:211], v[86:89]
	v_mfma_f32_16x16x32_bf16 v[82:85], v[184:187], v[208:211], v[82:85]
	v_mfma_f32_16x16x32_bf16 v[70:73], v[176:179], v[220:223], v[70:73]
	v_mfma_f32_16x16x32_bf16 v[66:69], v[184:187], v[220:223], v[66:69]
	s_setprio 0
	s_barrier
; #define PG8_STAGE(bufoff, gbase, voff) do { _Pragma("unroll") for (int _i = 0; _i < 2; ++_i) \
;         __builtin_amdgcn_global_load_lds((const unsigned*)((const char*)(gbase) + (voff)[_i]), (PG8_LAS unsigned*)(lds + (bufoff) + ldsw + _i * 8192), 16, 0, 0); } while (0)
; #define PG8_LDA(dst, b, h) do { _Pragma("unroll") for (int m = 0; m < 4; ++m) _Pragma("unroll") for (int k = 0; k < 2; ++k) dst[m][k] = *(const PG8_LAS bf16x8*)(lds + PG8_SA(b, h) + aoff + m * 2048 + k * 1024); } while (0)
; #define PG8_MMA(ai, bj, At, Bt) do { __builtin_amdgcn_s_setprio(1); _Pragma("unroll") for (int m = 0; m < 4; ++m) _Pragma("unroll") for (int n = 0; n < 2; ++n) _Pragma("unroll") for (int k = 0; k < 2; ++k) \
;         acc[ai][bj][m][n] = __builtin_amdgcn_mfma_f32_16x16x32_bf16(Bt[n][k], At[m][k], acc[ai][bj][m][n], 0, 0, 0); __builtin_amdgcn_s_setprio(0); } while (0)
; #define PG8_WAIT_V(n) asm volatile("s_waitcnt vmcnt(" #n ")" ::: "memory")
; #define PG8_WAIT_L(n) asm volatile("s_waitcnt lgkmcnt(" #n ")" ::: "memory")
; #define PG8_BAR __builtin_amdgcn_s_barrier()
; #define PG8_SCHED __builtin_amdgcn_sched_barrier(0)
; template <class Epi, class Sched, bool ALIGN_EPI = false, bool SP2 = false>
; __device__ __forceinline__ void gemm_phase(PG8_LAS unsigned char* lds, const Gemm g, const Sched& S, const Epi& E) {
;     ...
;         for (int t = 0; t < nt; t += 2) {
;             const bool last = (t == nt - 2);
;     ...
;             PG8_LDA(At, 1, 1); PG8_STAGE(PG8_SB(1, 0), b3, voffB); PG8_STAGE(PG8_SB(1, 1), b3 + hstepB, voffB); PG8_STAGE(PG8_SA(1, 0), a3, voffA);
;             PG8_WAIT_V(8); PG8_WAIT_L(0); PG8_BAR; PG8_MMA(1, 0, At, B0); PG8_MMA(1, 1, At, B1); PG8_BAR; PG8_SCHED;
	s_add_i32 s44, s64, s51
	v_lshl_add_u64 v[162:163], v[162:163], 0, s[22:23]
	s_mov_b32 m0, s44
	ds_read_b128 v[188:191], v168 offset:49152
	ds_read_b128 v[192:195], v168 offset:50176
	ds_read_b128 v[196:199], v168 offset:51200
	ds_read_b128 v[200:203], v168 offset:52224
	ds_read_b128 v[204:207], v168 offset:53248
	ds_read_b128 v[208:211], v168 offset:54272
	ds_read_b128 v[212:215], v168 offset:55296
	ds_read_b128 v[220:223], v168 offset:56320
	global_load_lds_dwordx4 v[162:163], off
	s_add_i32 m0, s44, 0x2000
	s_add_u32 s42, s42, 0x20080
	v_lshl_add_u64 v[162:163], v[216:217], 0, s[22:23]
	s_addc_u32 s43, s43, 0
	s_add_i32 s44, s65, s51
	global_load_lds_dwordx4 v[162:163], off
	v_lshl_add_u64 v[162:163], s[42:43], 0, v[140:141]
	s_mov_b32 m0, s44
	s_nop 0
	global_load_lds_dwordx4 v[162:163], off
	v_lshl_add_u64 v[162:163], s[42:43], 0, v[144:145]
	s_add_i32 m0, s44, 0x2000
	s_nop 0
	global_load_lds_dwordx4 v[162:163], off
	v_lshl_add_u64 v[162:163], v[224:225], 0, s[22:23]
	s_mov_b32 m0, s56
	s_nop 0
	global_load_lds_dwordx4 v[162:163], off
	v_lshl_add_u64 v[162:163], v[226:227], 0, s[22:23]
	s_mov_b32 m0, s57
	s_nop 0
	global_load_lds_dwordx4 v[162:163], off
	s_waitcnt vmcnt(8)
	s_waitcnt lgkmcnt(0)
	s_barrier
	s_setprio 1
	s_waitcnt lgkmcnt(0)
	v_mfma_f32_16x16x32_bf16 v[62:65], v[130:133], v[188:191], v[62:65]
	v_mfma_f32_16x16x32_bf16 v[58:61], v[154:157], v[188:191], v[58:61]
	v_mfma_f32_16x16x32_bf16 v[46:49], v[130:133], v[196:199], v[46:49]
	v_mfma_f32_16x16x32_bf16 v[42:45], v[154:157], v[196:199], v[42:45]
	v_mfma_f32_16x16x32_bf16 v[30:33], v[130:133], v[204:207], v[30:33]
	v_mfma_f32_16x16x32_bf16 v[26:29], v[154:157], v[204:207], v[26:29]
	v_mfma_f32_16x16x32_bf16 v[14:17], v[130:133], v[212:215], v[14:17]
	v_mfma_f32_16x16x32_bf16 v[10:13], v[154:157], v[212:215], v[10:13]
	v_mfma_f32_16x16x32_bf16 v[62:65], v[134:137], v[192:195], v[62:65]
	v_mfma_f32_16x16x32_bf16 v[58:61], v[158:161], v[192:195], v[58:61]
	v_mfma_f32_16x16x32_bf16 v[46:49], v[134:137], v[200:203], v[46:49]
	v_mfma_f32_16x16x32_bf16 v[42:45], v[158:161], v[200:203], v[42:45]
	v_mfma_f32_16x16x32_bf16 v[30:33], v[134:137], v[208:211], v[30:33]
	v_mfma_f32_16x16x32_bf16 v[26:29], v[158:161], v[208:211], v[26:29]
	v_mfma_f32_16x16x32_bf16 v[14:17], v[134:137], v[220:223], v[14:17]
	v_mfma_f32_16x16x32_bf16 v[10:13], v[158:161], v[220:223], v[10:13]
	s_setprio 0
	s_setprio 1
	v_mfma_f32_16x16x32_bf16 v[54:57], v[170:173], v[188:191], v[54:57]
	v_mfma_f32_16x16x32_bf16 v[50:53], v[180:183], v[188:191], v[50:53]
	v_mfma_f32_16x16x32_bf16 v[38:41], v[170:173], v[196:199], v[38:41]
	v_mfma_f32_16x16x32_bf16 v[34:37], v[180:183], v[196:199], v[34:37]
	v_mfma_f32_16x16x32_bf16 v[22:25], v[170:173], v[204:207], v[22:25]
	v_mfma_f32_16x16x32_bf16 v[18:21], v[180:183], v[204:207], v[18:21]
	v_mfma_f32_16x16x32_bf16 v[6:9], v[170:173], v[212:215], v[6:9]
	v_mfma_f32_16x16x32_bf16 v[2:5], v[180:183], v[212:215], v[2:5]
	v_mfma_f32_16x16x32_bf16 v[54:57], v[176:179], v[192:195], v[54:57]
	v_mfma_f32_16x16x32_bf16 v[50:53], v[184:187], v[192:195], v[50:53]
	v_mfma_f32_16x16x32_bf16 v[38:41], v[176:179], v[200:203], v[38:41]
	v_mfma_f32_16x16x32_bf16 v[34:37], v[184:187], v[200:203], v[34:37]
	v_mfma_f32_16x16x32_bf16 v[22:25], v[176:179], v[208:211], v[22:25]
	v_mfma_f32_16x16x32_bf16 v[18:21], v[184:187], v[208:211], v[18:21]
	v_mfma_f32_16x16x32_bf16 v[6:9], v[176:179], v[220:223], v[6:9]
	v_mfma_f32_16x16x32_bf16 v[2:5], v[184:187], v[220:223], v[2:5]
	s_setprio 0
	s_add_i32 s63, s63, 2
	s_add_u32 s40, s40, 0x100
	s_addc_u32 s41, s41, 0
	s_add_u32 s61, s61, 0x100
	s_addc_u32 s62, s62, 0
	s_cmp_gt_u32 s63, 5
	s_barrier
	s_cbranch_scc0 .LBB0_851
	s_and_b64 vcc, exec, s[24:25]
	s_cbranch_vccz .LBB0_854
	s_barrier

; #define PG8_STAGE(bufoff, gbase, voff) do { _Pragma("unroll") for (int _i = 0; _i < 2; ++_i) \
;         __builtin_amdgcn_global_load_lds((const unsigned*)((const char*)(gbase) + (voff)[_i]), (PG8_LAS unsigned*)(lds + (bufoff) + ldsw + _i * 8192), 16, 0, 0); } while (0)
; #define PG8_LDA(dst, b, h) do { _Pragma("unroll") for (int m = 0; m < 4; ++m) _Pragma("unroll") for (int k = 0; k < 2; ++k) dst[m][k] = *(const PG8_LAS bf16x8*)(lds + PG8_SA(b, h) + aoff + m * 2048 + k * 1024); } while (0)
; #define PG8_LDB(dst, b, h) do { _Pragma("unroll") for (int n = 0; n < 2; ++n) _Pragma("unroll") for (int k = 0; k < 2; ++k) dst[n][k] = *(const PG8_LAS bf16x8*)(lds + PG8_SB(b, h) + boff + n * 2048 + k * 1024); } while (0)
; #define PG8_MMA(ai, bj, At, Bt) do { __builtin_amdgcn_s_setprio(1); _Pragma("unroll") for (int m = 0; m < 4; ++m) _Pragma("unroll") for (int n = 0; n < 2; ++n) _Pragma("unroll") for (int k = 0; k < 2; ++k) \
;         acc[ai][bj][m][n] = __builtin_amdgcn_mfma_f32_16x16x32_bf16(Bt[n][k], At[m][k], acc[ai][bj][m][n], 0, 0, 0); __builtin_amdgcn_s_setprio(0); } while (0)
; #define PG8_WAIT_V(n) asm volatile("s_waitcnt vmcnt(" #n ")" ::: "memory")
; #define PG8_WAIT_L(n) asm volatile("s_waitcnt lgkmcnt(" #n ")" ::: "memory")
; #define PG8_BAR __builtin_amdgcn_s_barrier()
; #define PG8_SCHED __builtin_amdgcn_sched_barrier(0)
; template <class Epi, class Sched, bool ALIGN_EPI = false, bool SP2 = false>
; __device__ __forceinline__ void gemm_phase(PG8_LAS unsigned char* lds, const Gemm g, const Sched& S, const Epi& E) {
;     ...
;         for (int t = 0; t < nt; t += 2) {
;             const bool last = (t == nt - 2);
;             const char* a1 = cA + (size_t)(t + 1) * kstep;
;             const char* a2 = last ? nA : cA + (size_t)(t + 2) * kstep; const char* b2 = last ? nB : cB + (size_t)(t + 2) * kstep;
;             const char* a3 = a2 + kstep; const char* b3 = b2 + kstep;
;             if (last && has_next) S.a_ready(nxt);
;             if constexpr (SP2) {
;             PG8_LDB(B0, 0, 0); PG8_LDB(B1, 0, 1); PG8_SCHED; PG8_LDA(At, 0, 0); PG8_STAGE(PG8_SA(1, 1), a1 + hstepA, voffA);
;             PG8_WAIT_V(8); PG8_WAIT_L(0); PG8_BAR; PG8_MMA(0, 0, At, B0); PG8_MMA(0, 1, At, B1); PG8_BAR; PG8_SCHED;
;             PG8_LDA(At, 0, 1); PG8_STAGE(PG8_SB(0, 0), b2, voffB); PG8_STAGE(PG8_SB(0, 1), b2 + hstepB, voffB); PG8_STAGE(PG8_SA(0, 0), a2, voffA);
.LBB0_875:
	ds_read_b128 v[146:149], v160
	ds_read_b128 v[150:153], v160 offset:1024
	ds_read_b128 v[154:157], v160 offset:2048
	ds_read_b128 v[164:167], v160 offset:3072
	ds_read_b128 v[168:171], v161
	ds_read_b128 v[176:179], v161 offset:1024
	ds_read_b128 v[180:183], v161 offset:2048
	ds_read_b128 v[184:187], v161 offset:3072
	s_add_u32 s36, s34, 0xfffe0080
	s_addc_u32 s37, s35, -1
	s_cmp_eq_u32 s58, 4
	s_cselect_b32 s41, s25, s37
	s_cselect_b32 s40, s39, s36
	s_cselect_b32 s37, s23, s57
	s_cselect_b32 s36, s55, s56
	v_lshl_add_u64 v[172:173], s[34:35], 0, v[138:139]
	s_add_i32 m0, s31, 0xc000
	ds_read_b128 v[188:191], v162
	ds_read_b128 v[192:195], v162 offset:1024
	ds_read_b128 v[196:199], v162 offset:2048
	ds_read_b128 v[200:203], v162 offset:3072
	ds_read_b128 v[204:207], v162 offset:4096
	ds_read_b128 v[208:211], v162 offset:5120
	ds_read_b128 v[212:215], v162 offset:6144
	ds_read_b128 v[220:223], v162 offset:7168
	global_load_lds_dwordx4 v[172:173], off
	v_lshl_add_u64 v[172:173], s[34:35], 0, v[140:141]
	s_add_i32 m0, s31, 0xe000
	s_nop 0
	global_load_lds_dwordx4 v[172:173], off
	s_waitcnt vmcnt(8)
	s_waitcnt lgkmcnt(0)
	s_barrier
	s_setprio 1
	s_waitcnt lgkmcnt(0)
	v_mfma_f32_16x16x32_bf16 v[126:129], v[146:149], v[188:191], v[126:129]
	v_mfma_f32_16x16x32_bf16 v[122:125], v[154:157], v[188:191], v[122:125]
	v_mfma_f32_16x16x32_bf16 v[110:113], v[146:149], v[196:199], v[110:113]
	v_mfma_f32_16x16x32_bf16 v[106:109], v[154:157], v[196:199], v[106:109]
	v_mfma_f32_16x16x32_bf16 v[94:97], v[146:149], v[204:207], v[94:97]
	v_mfma_f32_16x16x32_bf16 v[90:93], v[154:157], v[204:207], v[90:93]
	v_mfma_f32_16x16x32_bf16 v[78:81], v[146:149], v[212:215], v[78:81]
	v_mfma_f32_16x16x32_bf16 v[74:77], v[154:157], v[212:215], v[74:77]
	v_mfma_f32_16x16x32_bf16 v[126:129], v[150:153], v[192:195], v[126:129]
	v_mfma_f32_16x16x32_bf16 v[122:125], v[164:167], v[192:195], v[122:125]
	v_mfma_f32_16x16x32_bf16 v[110:113], v[150:153], v[200:203], v[110:113]
	v_mfma_f32_16x16x32_bf16 v[106:109], v[164:167], v[200:203], v[106:109]
	v_mfma_f32_16x16x32_bf16 v[94:97], v[150:153], v[208:211], v[94:97]
	v_mfma_f32_16x16x32_bf16 v[90:93], v[164:167], v[208:211], v[90:93]
	v_mfma_f32_16x16x32_bf16 v[78:81], v[150:153], v[220:223], v[78:81]
	v_mfma_f32_16x16x32_bf16 v[74:77], v[164:167], v[220:223], v[74:77]
	s_setprio 0
	s_setprio 1
	v_mfma_f32_16x16x32_bf16 v[118:121], v[168:171], v[188:191], v[118:121]
	v_mfma_f32_16x16x32_bf16 v[114:117], v[180:183], v[188:191], v[114:117]
	v_mfma_f32_16x16x32_bf16 v[102:105], v[168:171], v[196:199], v[102:105]
	v_mfma_f32_16x16x32_bf16 v[98:101], v[180:183], v[196:199], v[98:101]
	v_mfma_f32_16x16x32_bf16 v[86:89], v[168:171], v[204:207], v[86:89]
	v_mfma_f32_16x16x32_bf16 v[82:85], v[180:183], v[204:207], v[82:85]
	v_mfma_f32_16x16x32_bf16 v[70:73], v[168:171], v[212:215], v[70:73]
	v_mfma_f32_16x16x32_bf16 v[66:69], v[180:183], v[212:215], v[66:69]
	v_mfma_f32_16x16x32_bf16 v[118:121], v[176:179], v[192:195], v[118:121]
	v_mfma_f32_16x16x32_bf16 v[114:117], v[184:187], v[192:195], v[114:117]
	v_mfma_f32_16x16x32_bf16 v[102:105], v[176:179], v[200:203], v[102:105]
	v_mfma_f32_16x16x32_bf16 v[98:101], v[184:187], v[200:203], v[98:101]
	v_mfma_f32_16x16x32_bf16 v[86:89], v[176:179], v[208:211], v[86:89]
	v_mfma_f32_16x16x32_bf16 v[82:85], v[184:187], v[208:211], v[82:85]
	v_mfma_f32_16x16x32_bf16 v[70:73], v[176:179], v[220:223], v[70:73]
	v_mfma_f32_16x16x32_bf16 v[66:69], v[184:187], v[220:223], v[66:69]
	s_setprio 0
	s_barrier
	s_add_i32 s59, s53, s45
	v_lshl_add_u64 v[172:173], s[36:37], 0, v[132:133]
	s_mov_b32 m0, s59
	ds_read_b128 v[188:191], v162 offset:16384
	ds_read_b128 v[192:195], v162 offset:17408
	ds_read_b128 v[196:199], v162 offset:18432
	ds_read_b128 v[200:203], v162 offset:19456
	ds_read_b128 v[204:207], v162 offset:20480
	ds_read_b128 v[208:211], v162 offset:21504
	ds_read_b128 v[212:215], v162 offset:22528
	ds_read_b128 v[220:223], v162 offset:23552
	global_load_lds_dwordx4 v[172:173], off
	s_add_i32 m0, s59, 0x2000
	s_add_u32 s60, s36, 0x20000
	v_lshl_add_u64 v[216:217], s[36:37], 0, v[136:137]
	s_addc_u32 s61, s37, 0
	s_add_i32 s59, s54, s45
	global_load_lds_dwordx4 v[216:217], off
	v_lshl_add_u64 v[224:225], s[60:61], 0, v[132:133]
	s_mov_b32 m0, s59
	v_lshl_add_u64 v[226:227], s[40:41], 0, v[134:135]
	global_load_lds_dwordx4 v[224:225], off
	v_lshl_add_u64 v[224:225], s[60:61], 0, v[136:137]
	s_add_i32 m0, s59, 0x2000
	s_nop 0
	global_load_lds_dwordx4 v[224:225], off
	v_lshl_add_u64 v[224:225], s[40:41], 0, v[130:131]
	s_mov_b32 m0, s31
	s_nop 0
	global_load_lds_dwordx4 v[224:225], off
	s_mov_b32 m0, s46
	s_nop 0
	global_load_lds_dwordx4 v[226:227], off
	s_waitcnt vmcnt(8)
	s_waitcnt lgkmcnt(0)
	s_barrier
; #define PG8_STAGE(bufoff, gbase, voff) do { _Pragma("unroll") for (int _i = 0; _i < 2; ++_i) \
;         __builtin_amdgcn_global_load_lds((const unsigned*)((const char*)(gbase) + (voff)[_i]), (PG8_LAS unsigned*)(lds + (bufoff) + ldsw + _i * 8192), 16, 0, 0); } while (0)
; #define PG8_LDA(dst, b, h) do { _Pragma("unroll") for (int m = 0; m < 4; ++m) _Pragma("unroll") for (int k = 0; k < 2; ++k) dst[m][k] = *(const PG8_LAS bf16x8*)(lds + PG8_SA(b, h) + aoff + m * 2048 + k * 1024); } while (0)
; #define PG8_LDB(dst, b, h) do { _Pragma("unroll") for (int n = 0; n < 2; ++n) _Pragma("unroll") for (int k = 0; k < 2; ++k) dst[n][k] = *(const PG8_LAS bf16x8*)(lds + PG8_SB(b, h) + boff + n * 2048 + k * 1024); } while (0)
; #define PG8_MMA(ai, bj, At, Bt) do { __builtin_amdgcn_s_setprio(1); _Pragma("unroll") for (int m = 0; m < 4; ++m) _Pragma("unroll") for (int n = 0; n < 2; ++n) _Pragma("unroll") for (int k = 0; k < 2; ++k) \
;         acc[ai][bj][m][n] = __builtin_amdgcn_mfma_f32_16x16x32_bf16(Bt[n][k], At[m][k], acc[ai][bj][m][n], 0, 0, 0); __builtin_amdgcn_s_setprio(0); } while (0)
; #define PG8_WAIT_V(n) asm volatile("s_waitcnt vmcnt(" #n ")" ::: "memory")
; #define PG8_WAIT_L(n) asm volatile("s_waitcnt lgkmcnt(" #n ")" ::: "memory")
; #define PG8_BAR __builtin_amdgcn_s_barrier()
; #define PG8_SCHED __builtin_amdgcn_sched_barrier(0)
; template <class Epi, class Sched, bool ALIGN_EPI = false, bool SP2 = false>
; __device__ __forceinline__ void gemm_phase(PG8_LAS unsigned char* lds, const Gemm g, const Sched& S, const Epi& E) {
;     ...
;             PG8_WAIT_V(8); PG8_WAIT_L(0); PG8_BAR; PG8_MMA(1, 0, At, B0); PG8_MMA(1, 1, At, B1); PG8_BAR; PG8_SCHED;
;             PG8_LDB(B0, 1, 0); PG8_LDB(B1, 1, 1); PG8_SCHED; PG8_LDA(At, 1, 0); PG8_STAGE(PG8_SA(0, 1), a2 + hstepA, voffA);
;             PG8_WAIT_V(8); PG8_WAIT_L(0); PG8_BAR; PG8_MMA(0, 0, At, B0); PG8_MMA(0, 1, At, B1); PG8_BAR; PG8_SCHED;
	s_setprio 1
	s_waitcnt lgkmcnt(0)
	v_mfma_f32_16x16x32_bf16 v[62:65], v[146:149], v[188:191], v[62:65]
	v_mfma_f32_16x16x32_bf16 v[58:61], v[154:157], v[188:191], v[58:61]
	v_mfma_f32_16x16x32_bf16 v[46:49], v[146:149], v[196:199], v[46:49]
	v_mfma_f32_16x16x32_bf16 v[42:45], v[154:157], v[196:199], v[42:45]
	v_mfma_f32_16x16x32_bf16 v[30:33], v[146:149], v[204:207], v[30:33]
	v_mfma_f32_16x16x32_bf16 v[26:29], v[154:157], v[204:207], v[26:29]
	v_mfma_f32_16x16x32_bf16 v[14:17], v[146:149], v[212:215], v[14:17]
	v_mfma_f32_16x16x32_bf16 v[10:13], v[154:157], v[212:215], v[10:13]
	v_mfma_f32_16x16x32_bf16 v[62:65], v[150:153], v[192:195], v[62:65]
	v_mfma_f32_16x16x32_bf16 v[58:61], v[164:167], v[192:195], v[58:61]
	v_mfma_f32_16x16x32_bf16 v[46:49], v[150:153], v[200:203], v[46:49]
	v_mfma_f32_16x16x32_bf16 v[42:45], v[164:167], v[200:203], v[42:45]
	v_mfma_f32_16x16x32_bf16 v[30:33], v[150:153], v[208:211], v[30:33]
	v_mfma_f32_16x16x32_bf16 v[26:29], v[164:167], v[208:211], v[26:29]
	v_mfma_f32_16x16x32_bf16 v[14:17], v[150:153], v[220:223], v[14:17]
	v_mfma_f32_16x16x32_bf16 v[10:13], v[164:167], v[220:223], v[10:13]
	s_setprio 0
	s_setprio 1
	v_mfma_f32_16x16x32_bf16 v[54:57], v[168:171], v[188:191], v[54:57]
	v_mfma_f32_16x16x32_bf16 v[50:53], v[180:183], v[188:191], v[50:53]
	v_mfma_f32_16x16x32_bf16 v[38:41], v[168:171], v[196:199], v[38:41]
	v_mfma_f32_16x16x32_bf16 v[34:37], v[180:183], v[196:199], v[34:37]
	v_mfma_f32_16x16x32_bf16 v[22:25], v[168:171], v[204:207], v[22:25]
	v_mfma_f32_16x16x32_bf16 v[18:21], v[180:183], v[204:207], v[18:21]
	v_mfma_f32_16x16x32_bf16 v[6:9], v[168:171], v[212:215], v[6:9]
	v_mfma_f32_16x16x32_bf16 v[2:5], v[180:183], v[212:215], v[2:5]
	v_mfma_f32_16x16x32_bf16 v[54:57], v[176:179], v[192:195], v[54:57]
	v_mfma_f32_16x16x32_bf16 v[50:53], v[184:187], v[192:195], v[50:53]
	v_mfma_f32_16x16x32_bf16 v[38:41], v[176:179], v[200:203], v[38:41]
	v_mfma_f32_16x16x32_bf16 v[34:37], v[184:187], v[200:203], v[34:37]
	v_mfma_f32_16x16x32_bf16 v[22:25], v[176:179], v[208:211], v[22:25]
	v_mfma_f32_16x16x32_bf16 v[18:21], v[184:187], v[208:211], v[18:21]
	v_mfma_f32_16x16x32_bf16 v[6:9], v[176:179], v[220:223], v[6:9]
	v_mfma_f32_16x16x32_bf16 v[2:5], v[184:187], v[220:223], v[2:5]
	s_setprio 0
	s_barrier
	s_add_i32 s59, 0, 0x18000
	v_add_u32_e32 v163, s59, v158
	s_add_i32 s60, 0, 0x1c000
	ds_read_b128 v[146:149], v163
	ds_read_b128 v[150:153], v163 offset:1024
	ds_read_b128 v[154:157], v163 offset:2048
	ds_read_b128 v[164:167], v163 offset:3072
	v_add_u32_e32 v163, s60, v158
	ds_read_b128 v[168:171], v163
	ds_read_b128 v[176:179], v163 offset:1024
	ds_read_b128 v[180:183], v163 offset:2048
	ds_read_b128 v[184:187], v163 offset:3072
	s_add_u32 s40, s40, 0x20000
	s_addc_u32 s41, s41, 0
	s_mov_b32 m0, s47
	v_lshl_add_u64 v[228:229], s[40:41], 0, v[130:131]
	ds_read_b128 v[188:191], v162 offset:32768
	ds_read_b128 v[192:195], v162 offset:33792
	ds_read_b128 v[196:199], v162 offset:34816
	ds_read_b128 v[200:203], v162 offset:35840
	ds_read_b128 v[204:207], v162 offset:36864
	ds_read_b128 v[208:211], v162 offset:37888
	ds_read_b128 v[212:215], v162 offset:38912
	ds_read_b128 v[220:223], v162 offset:39936
	global_load_lds_dwordx4 v[228:229], off
	v_lshl_add_u64 v[228:229], s[40:41], 0, v[134:135]
	s_mov_b32 m0, s48
	s_nop 0
	global_load_lds_dwordx4 v[228:229], off
	s_waitcnt vmcnt(8)
	s_waitcnt lgkmcnt(0)
	s_barrier
	s_setprio 1
	s_waitcnt lgkmcnt(0)
	v_mfma_f32_16x16x32_bf16 v[126:129], v[146:149], v[188:191], v[126:129]
	v_mfma_f32_16x16x32_bf16 v[122:125], v[154:157], v[188:191], v[122:125]
	v_mfma_f32_16x16x32_bf16 v[110:113], v[146:149], v[196:199], v[110:113]
	v_mfma_f32_16x16x32_bf16 v[106:109], v[154:157], v[196:199], v[106:109]
	v_mfma_f32_16x16x32_bf16 v[94:97], v[146:149], v[204:207], v[94:97]
	v_mfma_f32_16x16x32_bf16 v[90:93], v[154:157], v[204:207], v[90:93]
	v_mfma_f32_16x16x32_bf16 v[78:81], v[146:149], v[212:215], v[78:81]
	v_mfma_f32_16x16x32_bf16 v[74:77], v[154:157], v[212:215], v[74:77]
	v_mfma_f32_16x16x32_bf16 v[126:129], v[150:153], v[192:195], v[126:129]
	v_mfma_f32_16x16x32_bf16 v[122:125], v[164:167], v[192:195], v[122:125]
	v_mfma_f32_16x16x32_bf16 v[110:113], v[150:153], v[200:203], v[110:113]
	v_mfma_f32_16x16x32_bf16 v[106:109], v[164:167], v[200:203], v[106:109]
	v_mfma_f32_16x16x32_bf16 v[94:97], v[150:153], v[208:211], v[94:97]
	v_mfma_f32_16x16x32_bf16 v[90:93], v[164:167], v[208:211], v[90:93]
	v_mfma_f32_16x16x32_bf16 v[78:81], v[150:153], v[220:223], v[78:81]
	v_mfma_f32_16x16x32_bf16 v[74:77], v[164:167], v[220:223], v[74:77]
	s_setprio 0
	s_setprio 1
	v_mfma_f32_16x16x32_bf16 v[118:121], v[168:171], v[188:191], v[118:121]
	v_mfma_f32_16x16x32_bf16 v[114:117], v[180:183], v[188:191], v[114:117]
	v_mfma_f32_16x16x32_bf16 v[102:105], v[168:171], v[196:199], v[102:105]
	v_mfma_f32_16x16x32_bf16 v[98:101], v[180:183], v[196:199], v[98:101]
	v_mfma_f32_16x16x32_bf16 v[86:89], v[168:171], v[204:207], v[86:89]
	v_mfma_f32_16x16x32_bf16 v[82:85], v[180:183], v[204:207], v[82:85]
	v_mfma_f32_16x16x32_bf16 v[70:73], v[168:171], v[212:215], v[70:73]
	v_mfma_f32_16x16x32_bf16 v[66:69], v[180:183], v[212:215], v[66:69]
	v_mfma_f32_16x16x32_bf16 v[118:121], v[176:179], v[192:195], v[118:121]
	v_mfma_f32_16x16x32_bf16 v[114:117], v[184:187], v[192:195], v[114:117]
	v_mfma_f32_16x16x32_bf16 v[102:105], v[176:179], v[200:203], v[102:105]
	v_mfma_f32_16x16x32_bf16 v[98:101], v[184:187], v[200:203], v[98:101]
	v_mfma_f32_16x16x32_bf16 v[86:89], v[176:179], v[208:211], v[86:89]
	v_mfma_f32_16x16x32_bf16 v[82:85], v[184:187], v[208:211], v[82:85]
	v_mfma_f32_16x16x32_bf16 v[70:73], v[176:179], v[220:223], v[70:73]
	v_mfma_f32_16x16x32_bf16 v[66:69], v[184:187], v[220:223], v[66:69]
	s_setprio 0
	s_barrier
; #define PG8_STAGE(bufoff, gbase, voff) do { _Pragma("unroll") for (int _i = 0; _i < 2; ++_i) \
;         __builtin_amdgcn_global_load_lds((const unsigned*)((const char*)(gbase) + (voff)[_i]), (PG8_LAS unsigned*)(lds + (bufoff) + ldsw + _i * 8192), 16, 0, 0); } while (0)
; #define PG8_LDA(dst, b, h) do { _Pragma("unroll") for (int m = 0; m < 4; ++m) _Pragma("unroll") for (int k = 0; k < 2; ++k) dst[m][k] = *(const PG8_LAS bf16x8*)(lds + PG8_SA(b, h) + aoff + m * 2048 + k * 1024); } while (0)
; #define PG8_MMA(ai, bj, At, Bt) do { __builtin_amdgcn_s_setprio(1); _Pragma("unroll") for (int m = 0; m < 4; ++m) _Pragma("unroll") for (int n = 0; n < 2; ++n) _Pragma("unroll") for (int k = 0; k < 2; ++k) \
;         acc[ai][bj][m][n] = __builtin_amdgcn_mfma_f32_16x16x32_bf16(Bt[n][k], At[m][k], acc[ai][bj][m][n], 0, 0, 0); __builtin_amdgcn_s_setprio(0); } while (0)
; #define PG8_WAIT_V(n) asm volatile("s_waitcnt vmcnt(" #n ")" ::: "memory")
; #define PG8_WAIT_L(n) asm volatile("s_waitcnt lgkmcnt(" #n ")" ::: "memory")
; #define PG8_BAR __builtin_amdgcn_s_barrier()
; #define PG8_SCHED __builtin_amdgcn_sched_barrier(0)
; template <class Epi, class Sched, bool ALIGN_EPI = false, bool SP2 = false>
; __device__ __forceinline__ void gemm_phase(PG8_LAS unsigned char* lds, const Gemm g, const Sched& S, const Epi& E) {
;     ...
;         for (int t = 0; t < nt; t += 2) {
;             const bool last = (t == nt - 2);
;     ...
;             PG8_LDA(At, 1, 1); PG8_STAGE(PG8_SB(1, 0), b3, voffB); PG8_STAGE(PG8_SB(1, 1), b3 + hstepB, voffB); PG8_STAGE(PG8_SA(1, 0), a3, voffA);
;             PG8_WAIT_V(8); PG8_WAIT_L(0); PG8_BAR; PG8_MMA(1, 0, At, B0); PG8_MMA(1, 1, At, B1); PG8_BAR; PG8_SCHED;
	s_add_i32 s40, s59, s45
	v_lshl_add_u64 v[172:173], v[172:173], 0, s[14:15]
	s_mov_b32 m0, s40
	ds_read_b128 v[188:191], v162 offset:49152
	ds_read_b128 v[192:195], v162 offset:50176
	ds_read_b128 v[196:199], v162 offset:51200
	ds_read_b128 v[200:203], v162 offset:52224
	ds_read_b128 v[204:207], v162 offset:53248
	ds_read_b128 v[208:211], v162 offset:54272
	ds_read_b128 v[212:215], v162 offset:55296
	ds_read_b128 v[220:223], v162 offset:56320
	global_load_lds_dwordx4 v[172:173], off
	s_add_i32 m0, s40, 0x2000
	s_add_u32 s36, s36, 0x20080
	v_lshl_add_u64 v[172:173], v[216:217], 0, s[14:15]
	s_addc_u32 s37, s37, 0
	s_add_i32 s40, s60, s45
	global_load_lds_dwordx4 v[172:173], off
	v_lshl_add_u64 v[172:173], s[36:37], 0, v[132:133]
	s_mov_b32 m0, s40
	s_nop 0
	global_load_lds_dwordx4 v[172:173], off
	v_lshl_add_u64 v[172:173], s[36:37], 0, v[136:137]
	s_add_i32 m0, s40, 0x2000
	s_nop 0
	global_load_lds_dwordx4 v[172:173], off
	v_lshl_add_u64 v[172:173], v[224:225], 0, s[14:15]
	s_mov_b32 m0, s50
	s_nop 0
	global_load_lds_dwordx4 v[172:173], off
	v_lshl_add_u64 v[172:173], v[226:227], 0, s[14:15]
	s_mov_b32 m0, s51
	s_nop 0
	global_load_lds_dwordx4 v[172:173], off
	s_waitcnt vmcnt(8)
	s_waitcnt lgkmcnt(0)
	s_barrier
	s_setprio 1
	s_waitcnt lgkmcnt(0)
	v_mfma_f32_16x16x32_bf16 v[62:65], v[146:149], v[188:191], v[62:65]
	v_mfma_f32_16x16x32_bf16 v[58:61], v[154:157], v[188:191], v[58:61]
	v_mfma_f32_16x16x32_bf16 v[46:49], v[146:149], v[196:199], v[46:49]
	v_mfma_f32_16x16x32_bf16 v[42:45], v[154:157], v[196:199], v[42:45]
	v_mfma_f32_16x16x32_bf16 v[30:33], v[146:149], v[204:207], v[30:33]
	v_mfma_f32_16x16x32_bf16 v[26:29], v[154:157], v[204:207], v[26:29]
	v_mfma_f32_16x16x32_bf16 v[14:17], v[146:149], v[212:215], v[14:17]
	v_mfma_f32_16x16x32_bf16 v[10:13], v[154:157], v[212:215], v[10:13]
	v_mfma_f32_16x16x32_bf16 v[62:65], v[150:153], v[192:195], v[62:65]
	v_mfma_f32_16x16x32_bf16 v[58:61], v[164:167], v[192:195], v[58:61]
	v_mfma_f32_16x16x32_bf16 v[46:49], v[150:153], v[200:203], v[46:49]
	v_mfma_f32_16x16x32_bf16 v[42:45], v[164:167], v[200:203], v[42:45]
	v_mfma_f32_16x16x32_bf16 v[30:33], v[150:153], v[208:211], v[30:33]
	v_mfma_f32_16x16x32_bf16 v[26:29], v[164:167], v[208:211], v[26:29]
	v_mfma_f32_16x16x32_bf16 v[14:17], v[150:153], v[220:223], v[14:17]
	v_mfma_f32_16x16x32_bf16 v[10:13], v[164:167], v[220:223], v[10:13]
	s_setprio 0
	s_setprio 1
	v_mfma_f32_16x16x32_bf16 v[54:57], v[168:171], v[188:191], v[54:57]
	v_mfma_f32_16x16x32_bf16 v[50:53], v[180:183], v[188:191], v[50:53]
	v_mfma_f32_16x16x32_bf16 v[38:41], v[168:171], v[196:199], v[38:41]
	v_mfma_f32_16x16x32_bf16 v[34:37], v[180:183], v[196:199], v[34:37]
	v_mfma_f32_16x16x32_bf16 v[22:25], v[168:171], v[204:207], v[22:25]
	v_mfma_f32_16x16x32_bf16 v[18:21], v[180:183], v[204:207], v[18:21]
	v_mfma_f32_16x16x32_bf16 v[6:9], v[168:171], v[212:215], v[6:9]
	v_mfma_f32_16x16x32_bf16 v[2:5], v[180:183], v[212:215], v[2:5]
	v_mfma_f32_16x16x32_bf16 v[54:57], v[176:179], v[192:195], v[54:57]
	v_mfma_f32_16x16x32_bf16 v[50:53], v[184:187], v[192:195], v[50:53]
	v_mfma_f32_16x16x32_bf16 v[38:41], v[176:179], v[200:203], v[38:41]
	v_mfma_f32_16x16x32_bf16 v[34:37], v[184:187], v[200:203], v[34:37]
	v_mfma_f32_16x16x32_bf16 v[22:25], v[176:179], v[208:211], v[22:25]
	v_mfma_f32_16x16x32_bf16 v[18:21], v[184:187], v[208:211], v[18:21]
	v_mfma_f32_16x16x32_bf16 v[6:9], v[176:179], v[220:223], v[6:9]
	v_mfma_f32_16x16x32_bf16 v[2:5], v[184:187], v[220:223], v[2:5]
	s_setprio 0
	s_add_i32 s58, s58, 2
	s_add_u32 s34, s34, 0x100
	s_addc_u32 s35, s35, 0
	s_add_u32 s56, s56, 0x100
	s_addc_u32 s57, s57, 0
	s_cmp_gt_u32 s58, 5
	s_barrier
	s_cbranch_scc0 .LBB0_875
	s_and_b64 vcc, exec, s[16:17]
	s_cbranch_vccz .LBB0_878
	s_barrier

; #define PG8_STAGE(bufoff, gbase, voff) do { _Pragma("unroll") for (int _i = 0; _i < 2; ++_i) \
;         __builtin_amdgcn_global_load_lds((const unsigned*)((const char*)(gbase) + (voff)[_i]), (PG8_LAS unsigned*)(lds + (bufoff) + ldsw + _i * 8192), 16, 0, 0); } while (0)
; #define PG8_LDA(dst, b, h) do { _Pragma("unroll") for (int m = 0; m < 4; ++m) _Pragma("unroll") for (int k = 0; k < 2; ++k) dst[m][k] = *(const PG8_LAS bf16x8*)(lds + PG8_SA(b, h) + aoff + m * 2048 + k * 1024); } while (0)
; #define PG8_LDB(dst, b, h) do { _Pragma("unroll") for (int n = 0; n < 2; ++n) _Pragma("unroll") for (int k = 0; k < 2; ++k) dst[n][k] = *(const PG8_LAS bf16x8*)(lds + PG8_SB(b, h) + boff + n * 2048 + k * 1024); } while (0)
; #define PG8_MMA(ai, bj, At, Bt) do { __builtin_amdgcn_s_setprio(1); _Pragma("unroll") for (int m = 0; m < 4; ++m) _Pragma("unroll") for (int n = 0; n < 2; ++n) _Pragma("unroll") for (int k = 0; k < 2; ++k) \
;         acc[ai][bj][m][n] = __builtin_amdgcn_mfma_f32_16x16x32_bf16(Bt[n][k], At[m][k], acc[ai][bj][m][n], 0, 0, 0); __builtin_amdgcn_s_setprio(0); } while (0)
; #define PG8_WAIT_V(n) asm volatile("s_waitcnt vmcnt(" #n ")" ::: "memory")
; #define PG8_WAIT_L(n) asm volatile("s_waitcnt lgkmcnt(" #n ")" ::: "memory")
; #define PG8_BAR __builtin_amdgcn_s_barrier()
; #define PG8_SCHED __builtin_amdgcn_sched_barrier(0)
; template <class Epi, class Sched, bool ALIGN_EPI = false, bool SP2 = false>
; __device__ __forceinline__ void gemm_phase(PG8_LAS unsigned char* lds, const Gemm g, const Sched& S, const Epi& E) {
;     ...
;         for (int t = 0; t < nt; t += 2) {
;             const bool last = (t == nt - 2);
;             const char* a1 = cA + (size_t)(t + 1) * kstep;
;             const char* a2 = last ? nA : cA + (size_t)(t + 2) * kstep; const char* b2 = last ? nB : cB + (size_t)(t + 2) * kstep;
;             const char* a3 = a2 + kstep; const char* b3 = b2 + kstep;
;             if (last && has_next) S.a_ready(nxt);
;             if constexpr (SP2) {
;             PG8_LDB(B0, 0, 0); PG8_LDB(B1, 0, 1); PG8_SCHED; PG8_LDA(At, 0, 0); PG8_STAGE(PG8_SA(1, 1), a1 + hstepA, voffA);
;             PG8_WAIT_V(8); PG8_WAIT_L(0); PG8_BAR; PG8_MMA(0, 0, At, B0); PG8_MMA(0, 1, At, B1); PG8_BAR; PG8_SCHED;
;             PG8_LDA(At, 0, 1); PG8_STAGE(PG8_SB(0, 0), b2, voffB); PG8_STAGE(PG8_SB(0, 1), b2 + hstepB, voffB); PG8_STAGE(PG8_SA(0, 0), a2, voffA);
.LBB0_976:
	ds_read_b128 v[146:149], v156
	ds_read_b128 v[150:153], v156 offset:1024
	ds_read_b128 v[160:163], v156 offset:2048
	ds_read_b128 v[164:167], v156 offset:3072
	ds_read_b128 v[168:171], v157
	ds_read_b128 v[176:179], v157 offset:1024
	ds_read_b128 v[180:183], v157 offset:2048
	ds_read_b128 v[184:187], v157 offset:3072
	s_add_u32 s40, s36, 0xfffe0080
	s_addc_u32 s41, s37, -1
	s_cmp_eq_u32 s60, 4
	s_cselect_b32 s43, s27, s41
	s_cselect_b32 s42, s39, s40
	s_cselect_b32 s41, s25, s59
	s_cselect_b32 s40, s57, s58
	v_lshl_add_u64 v[172:173], s[36:37], 0, v[138:139]
	s_add_i32 m0, s35, 0xc000
	ds_read_b128 v[188:191], v158
	ds_read_b128 v[192:195], v158 offset:1024
	ds_read_b128 v[196:199], v158 offset:2048
	ds_read_b128 v[200:203], v158 offset:3072
	ds_read_b128 v[204:207], v158 offset:4096
	ds_read_b128 v[208:211], v158 offset:5120
	ds_read_b128 v[212:215], v158 offset:6144
	ds_read_b128 v[220:223], v158 offset:7168
	global_load_lds_dwordx4 v[172:173], off
	v_lshl_add_u64 v[172:173], s[36:37], 0, v[140:141]
	s_add_i32 m0, s35, 0xe000
	s_nop 0
	global_load_lds_dwordx4 v[172:173], off
	s_waitcnt vmcnt(8)
	s_waitcnt lgkmcnt(0)
	s_barrier
	s_setprio 1
	s_waitcnt lgkmcnt(0)
	v_mfma_f32_16x16x32_bf16 v[126:129], v[146:149], v[188:191], v[126:129]
	v_mfma_f32_16x16x32_bf16 v[122:125], v[160:163], v[188:191], v[122:125]
	v_mfma_f32_16x16x32_bf16 v[110:113], v[146:149], v[196:199], v[110:113]
	v_mfma_f32_16x16x32_bf16 v[106:109], v[160:163], v[196:199], v[106:109]
	v_mfma_f32_16x16x32_bf16 v[94:97], v[146:149], v[204:207], v[94:97]
	v_mfma_f32_16x16x32_bf16 v[90:93], v[160:163], v[204:207], v[90:93]
	v_mfma_f32_16x16x32_bf16 v[78:81], v[146:149], v[212:215], v[78:81]
	v_mfma_f32_16x16x32_bf16 v[74:77], v[160:163], v[212:215], v[74:77]
	v_mfma_f32_16x16x32_bf16 v[126:129], v[150:153], v[192:195], v[126:129]
	v_mfma_f32_16x16x32_bf16 v[122:125], v[164:167], v[192:195], v[122:125]
	v_mfma_f32_16x16x32_bf16 v[110:113], v[150:153], v[200:203], v[110:113]
	v_mfma_f32_16x16x32_bf16 v[106:109], v[164:167], v[200:203], v[106:109]
	v_mfma_f32_16x16x32_bf16 v[94:97], v[150:153], v[208:211], v[94:97]
	v_mfma_f32_16x16x32_bf16 v[90:93], v[164:167], v[208:211], v[90:93]
	v_mfma_f32_16x16x32_bf16 v[78:81], v[150:153], v[220:223], v[78:81]
	v_mfma_f32_16x16x32_bf16 v[74:77], v[164:167], v[220:223], v[74:77]
	s_setprio 0
	s_setprio 1
	v_mfma_f32_16x16x32_bf16 v[118:121], v[168:171], v[188:191], v[118:121]
	v_mfma_f32_16x16x32_bf16 v[114:117], v[180:183], v[188:191], v[114:117]
	v_mfma_f32_16x16x32_bf16 v[102:105], v[168:171], v[196:199], v[102:105]
	v_mfma_f32_16x16x32_bf16 v[98:101], v[180:183], v[196:199], v[98:101]
	v_mfma_f32_16x16x32_bf16 v[86:89], v[168:171], v[204:207], v[86:89]
	v_mfma_f32_16x16x32_bf16 v[82:85], v[180:183], v[204:207], v[82:85]
	v_mfma_f32_16x16x32_bf16 v[70:73], v[168:171], v[212:215], v[70:73]
	v_mfma_f32_16x16x32_bf16 v[66:69], v[180:183], v[212:215], v[66:69]
	v_mfma_f32_16x16x32_bf16 v[118:121], v[176:179], v[192:195], v[118:121]
	v_mfma_f32_16x16x32_bf16 v[114:117], v[184:187], v[192:195], v[114:117]
	v_mfma_f32_16x16x32_bf16 v[102:105], v[176:179], v[200:203], v[102:105]
	v_mfma_f32_16x16x32_bf16 v[98:101], v[184:187], v[200:203], v[98:101]
	v_mfma_f32_16x16x32_bf16 v[86:89], v[176:179], v[208:211], v[86:89]
	v_mfma_f32_16x16x32_bf16 v[82:85], v[184:187], v[208:211], v[82:85]
	v_mfma_f32_16x16x32_bf16 v[70:73], v[176:179], v[220:223], v[70:73]
	v_mfma_f32_16x16x32_bf16 v[66:69], v[184:187], v[220:223], v[66:69]
	s_setprio 0
	s_barrier
	s_add_i32 s61, s55, s47
	v_lshl_add_u64 v[172:173], s[40:41], 0, v[132:133]
	s_mov_b32 m0, s61
	ds_read_b128 v[188:191], v158 offset:16384
	ds_read_b128 v[192:195], v158 offset:17408
	ds_read_b128 v[196:199], v158 offset:18432
	ds_read_b128 v[200:203], v158 offset:19456
	ds_read_b128 v[204:207], v158 offset:20480
	ds_read_b128 v[208:211], v158 offset:21504
	ds_read_b128 v[212:215], v158 offset:22528
	ds_read_b128 v[220:223], v158 offset:23552
	global_load_lds_dwordx4 v[172:173], off
	s_add_i32 m0, s61, 0x2000
	s_add_u32 s62, s40, 0x20000
	v_lshl_add_u64 v[216:217], s[40:41], 0, v[136:137]
	s_addc_u32 s63, s41, 0
	s_add_i32 s61, s56, s47
	global_load_lds_dwordx4 v[216:217], off
	v_lshl_add_u64 v[224:225], s[62:63], 0, v[132:133]
	s_mov_b32 m0, s61
	v_lshl_add_u64 v[226:227], s[42:43], 0, v[134:135]
	global_load_lds_dwordx4 v[224:225], off
	v_lshl_add_u64 v[224:225], s[62:63], 0, v[136:137]
	s_add_i32 m0, s61, 0x2000
	s_nop 0
	global_load_lds_dwordx4 v[224:225], off
	v_lshl_add_u64 v[224:225], s[42:43], 0, v[130:131]
	s_mov_b32 m0, s35
	s_nop 0
	global_load_lds_dwordx4 v[224:225], off
	s_mov_b32 m0, s48
	s_nop 0
	global_load_lds_dwordx4 v[226:227], off
	s_waitcnt vmcnt(8)
	s_waitcnt lgkmcnt(0)
	s_barrier
; #define PG8_STAGE(bufoff, gbase, voff) do { _Pragma("unroll") for (int _i = 0; _i < 2; ++_i) \
;         __builtin_amdgcn_global_load_lds((const unsigned*)((const char*)(gbase) + (voff)[_i]), (PG8_LAS unsigned*)(lds + (bufoff) + ldsw + _i * 8192), 16, 0, 0); } while (0)
; #define PG8_LDA(dst, b, h) do { _Pragma("unroll") for (int m = 0; m < 4; ++m) _Pragma("unroll") for (int k = 0; k < 2; ++k) dst[m][k] = *(const PG8_LAS bf16x8*)(lds + PG8_SA(b, h) + aoff + m * 2048 + k * 1024); } while (0)
; #define PG8_LDB(dst, b, h) do { _Pragma("unroll") for (int n = 0; n < 2; ++n) _Pragma("unroll") for (int k = 0; k < 2; ++k) dst[n][k] = *(const PG8_LAS bf16x8*)(lds + PG8_SB(b, h) + boff + n * 2048 + k * 1024); } while (0)
; #define PG8_MMA(ai, bj, At, Bt) do { __builtin_amdgcn_s_setprio(1); _Pragma("unroll") for (int m = 0; m < 4; ++m) _Pragma("unroll") for (int n = 0; n < 2; ++n) _Pragma("unroll") for (int k = 0; k < 2; ++k) \
;         acc[ai][bj][m][n] = __builtin_amdgcn_mfma_f32_16x16x32_bf16(Bt[n][k], At[m][k], acc[ai][bj][m][n], 0, 0, 0); __builtin_amdgcn_s_setprio(0); } while (0)
; #define PG8_WAIT_V(n) asm volatile("s_waitcnt vmcnt(" #n ")" ::: "memory")
; #define PG8_WAIT_L(n) asm volatile("s_waitcnt lgkmcnt(" #n ")" ::: "memory")
; #define PG8_BAR __builtin_amdgcn_s_barrier()
; #define PG8_SCHED __builtin_amdgcn_sched_barrier(0)
; template <class Epi, class Sched, bool ALIGN_EPI = false, bool SP2 = false>
; __device__ __forceinline__ void gemm_phase(PG8_LAS unsigned char* lds, const Gemm g, const Sched& S, const Epi& E) {
;     ...
;             PG8_WAIT_V(8); PG8_WAIT_L(0); PG8_BAR; PG8_MMA(1, 0, At, B0); PG8_MMA(1, 1, At, B1); PG8_BAR; PG8_SCHED;
;             PG8_LDB(B0, 1, 0); PG8_LDB(B1, 1, 1); PG8_SCHED; PG8_LDA(At, 1, 0); PG8_STAGE(PG8_SA(0, 1), a2 + hstepA, voffA);
;             PG8_WAIT_V(8); PG8_WAIT_L(0); PG8_BAR; PG8_MMA(0, 0, At, B0); PG8_MMA(0, 1, At, B1); PG8_BAR; PG8_SCHED;
	s_setprio 1
	s_waitcnt lgkmcnt(0)
	v_mfma_f32_16x16x32_bf16 v[62:65], v[146:149], v[188:191], v[62:65]
	v_mfma_f32_16x16x32_bf16 v[58:61], v[160:163], v[188:191], v[58:61]
	v_mfma_f32_16x16x32_bf16 v[46:49], v[146:149], v[196:199], v[46:49]
	v_mfma_f32_16x16x32_bf16 v[42:45], v[160:163], v[196:199], v[42:45]
	v_mfma_f32_16x16x32_bf16 v[30:33], v[146:149], v[204:207], v[30:33]
	v_mfma_f32_16x16x32_bf16 v[26:29], v[160:163], v[204:207], v[26:29]
	v_mfma_f32_16x16x32_bf16 v[14:17], v[146:149], v[212:215], v[14:17]
	v_mfma_f32_16x16x32_bf16 v[10:13], v[160:163], v[212:215], v[10:13]
	v_mfma_f32_16x16x32_bf16 v[62:65], v[150:153], v[192:195], v[62:65]
	v_mfma_f32_16x16x32_bf16 v[58:61], v[164:167], v[192:195], v[58:61]
	v_mfma_f32_16x16x32_bf16 v[46:49], v[150:153], v[200:203], v[46:49]
	v_mfma_f32_16x16x32_bf16 v[42:45], v[164:167], v[200:203], v[42:45]
	v_mfma_f32_16x16x32_bf16 v[30:33], v[150:153], v[208:211], v[30:33]
	v_mfma_f32_16x16x32_bf16 v[26:29], v[164:167], v[208:211], v[26:29]
	v_mfma_f32_16x16x32_bf16 v[14:17], v[150:153], v[220:223], v[14:17]
	v_mfma_f32_16x16x32_bf16 v[10:13], v[164:167], v[220:223], v[10:13]
	s_setprio 0
	s_setprio 1
	v_mfma_f32_16x16x32_bf16 v[54:57], v[168:171], v[188:191], v[54:57]
	v_mfma_f32_16x16x32_bf16 v[50:53], v[180:183], v[188:191], v[50:53]
	v_mfma_f32_16x16x32_bf16 v[38:41], v[168:171], v[196:199], v[38:41]
	v_mfma_f32_16x16x32_bf16 v[34:37], v[180:183], v[196:199], v[34:37]
	v_mfma_f32_16x16x32_bf16 v[22:25], v[168:171], v[204:207], v[22:25]
	v_mfma_f32_16x16x32_bf16 v[18:21], v[180:183], v[204:207], v[18:21]
	v_mfma_f32_16x16x32_bf16 v[6:9], v[168:171], v[212:215], v[6:9]
	v_mfma_f32_16x16x32_bf16 v[2:5], v[180:183], v[212:215], v[2:5]
	v_mfma_f32_16x16x32_bf16 v[54:57], v[176:179], v[192:195], v[54:57]
	v_mfma_f32_16x16x32_bf16 v[50:53], v[184:187], v[192:195], v[50:53]
	v_mfma_f32_16x16x32_bf16 v[38:41], v[176:179], v[200:203], v[38:41]
	v_mfma_f32_16x16x32_bf16 v[34:37], v[184:187], v[200:203], v[34:37]
	v_mfma_f32_16x16x32_bf16 v[22:25], v[176:179], v[208:211], v[22:25]
	v_mfma_f32_16x16x32_bf16 v[18:21], v[184:187], v[208:211], v[18:21]
	v_mfma_f32_16x16x32_bf16 v[6:9], v[176:179], v[220:223], v[6:9]
	v_mfma_f32_16x16x32_bf16 v[2:5], v[184:187], v[220:223], v[2:5]
	s_setprio 0
	s_barrier
	s_add_i32 s61, 0, 0x18000
	v_add_u32_e32 v159, s61, v154
	s_add_i32 s62, 0, 0x1c000
	ds_read_b128 v[146:149], v159
	ds_read_b128 v[150:153], v159 offset:1024
	ds_read_b128 v[160:163], v159 offset:2048
	ds_read_b128 v[164:167], v159 offset:3072
	v_add_u32_e32 v159, s62, v154
	ds_read_b128 v[168:171], v159
	ds_read_b128 v[176:179], v159 offset:1024
	ds_read_b128 v[180:183], v159 offset:2048
	ds_read_b128 v[184:187], v159 offset:3072
	s_add_u32 s42, s42, 0x20000
	s_addc_u32 s43, s43, 0
	s_mov_b32 m0, s49
	v_lshl_add_u64 v[228:229], s[42:43], 0, v[130:131]
	ds_read_b128 v[188:191], v158 offset:32768
	ds_read_b128 v[192:195], v158 offset:33792
	ds_read_b128 v[196:199], v158 offset:34816
	ds_read_b128 v[200:203], v158 offset:35840
	ds_read_b128 v[204:207], v158 offset:36864
	ds_read_b128 v[208:211], v158 offset:37888
	ds_read_b128 v[212:215], v158 offset:38912
	ds_read_b128 v[220:223], v158 offset:39936
	global_load_lds_dwordx4 v[228:229], off
	v_lshl_add_u64 v[228:229], s[42:43], 0, v[134:135]
	s_mov_b32 m0, s50
	s_nop 0
	global_load_lds_dwordx4 v[228:229], off
	s_waitcnt vmcnt(8)
	s_waitcnt lgkmcnt(0)
	s_barrier
	s_setprio 1
	s_waitcnt lgkmcnt(0)
	v_mfma_f32_16x16x32_bf16 v[126:129], v[146:149], v[188:191], v[126:129]
	v_mfma_f32_16x16x32_bf16 v[122:125], v[160:163], v[188:191], v[122:125]
	v_mfma_f32_16x16x32_bf16 v[110:113], v[146:149], v[196:199], v[110:113]
	v_mfma_f32_16x16x32_bf16 v[106:109], v[160:163], v[196:199], v[106:109]
	v_mfma_f32_16x16x32_bf16 v[94:97], v[146:149], v[204:207], v[94:97]
	v_mfma_f32_16x16x32_bf16 v[90:93], v[160:163], v[204:207], v[90:93]
	v_mfma_f32_16x16x32_bf16 v[78:81], v[146:149], v[212:215], v[78:81]
	v_mfma_f32_16x16x32_bf16 v[74:77], v[160:163], v[212:215], v[74:77]
	v_mfma_f32_16x16x32_bf16 v[126:129], v[150:153], v[192:195], v[126:129]
	v_mfma_f32_16x16x32_bf16 v[122:125], v[164:167], v[192:195], v[122:125]
	v_mfma_f32_16x16x32_bf16 v[110:113], v[150:153], v[200:203], v[110:113]
	v_mfma_f32_16x16x32_bf16 v[106:109], v[164:167], v[200:203], v[106:109]
	v_mfma_f32_16x16x32_bf16 v[94:97], v[150:153], v[208:211], v[94:97]
	v_mfma_f32_16x16x32_bf16 v[90:93], v[164:167], v[208:211], v[90:93]
	v_mfma_f32_16x16x32_bf16 v[78:81], v[150:153], v[220:223], v[78:81]
	v_mfma_f32_16x16x32_bf16 v[74:77], v[164:167], v[220:223], v[74:77]
	s_setprio 0
	s_setprio 1
	v_mfma_f32_16x16x32_bf16 v[118:121], v[168:171], v[188:191], v[118:121]
	v_mfma_f32_16x16x32_bf16 v[114:117], v[180:183], v[188:191], v[114:117]
	v_mfma_f32_16x16x32_bf16 v[102:105], v[168:171], v[196:199], v[102:105]
	v_mfma_f32_16x16x32_bf16 v[98:101], v[180:183], v[196:199], v[98:101]
	v_mfma_f32_16x16x32_bf16 v[86:89], v[168:171], v[204:207], v[86:89]
	v_mfma_f32_16x16x32_bf16 v[82:85], v[180:183], v[204:207], v[82:85]
	v_mfma_f32_16x16x32_bf16 v[70:73], v[168:171], v[212:215], v[70:73]
	v_mfma_f32_16x16x32_bf16 v[66:69], v[180:183], v[212:215], v[66:69]
	v_mfma_f32_16x16x32_bf16 v[118:121], v[176:179], v[192:195], v[118:121]
	v_mfma_f32_16x16x32_bf16 v[114:117], v[184:187], v[192:195], v[114:117]
	v_mfma_f32_16x16x32_bf16 v[102:105], v[176:179], v[200:203], v[102:105]
	v_mfma_f32_16x16x32_bf16 v[98:101], v[184:187], v[200:203], v[98:101]
	v_mfma_f32_16x16x32_bf16 v[86:89], v[176:179], v[208:211], v[86:89]
	v_mfma_f32_16x16x32_bf16 v[82:85], v[184:187], v[208:211], v[82:85]
	v_mfma_f32_16x16x32_bf16 v[70:73], v[176:179], v[220:223], v[70:73]
	v_mfma_f32_16x16x32_bf16 v[66:69], v[184:187], v[220:223], v[66:69]
	s_setprio 0
	s_barrier
; #define PG8_STAGE(bufoff, gbase, voff) do { _Pragma("unroll") for (int _i = 0; _i < 2; ++_i) \
;         __builtin_amdgcn_global_load_lds((const unsigned*)((const char*)(gbase) + (voff)[_i]), (PG8_LAS unsigned*)(lds + (bufoff) + ldsw + _i * 8192), 16, 0, 0); } while (0)
; #define PG8_LDA(dst, b, h) do { _Pragma("unroll") for (int m = 0; m < 4; ++m) _Pragma("unroll") for (int k = 0; k < 2; ++k) dst[m][k] = *(const PG8_LAS bf16x8*)(lds + PG8_SA(b, h) + aoff + m * 2048 + k * 1024); } while (0)
; #define PG8_MMA(ai, bj, At, Bt) do { __builtin_amdgcn_s_setprio(1); _Pragma("unroll") for (int m = 0; m < 4; ++m) _Pragma("unroll") for (int n = 0; n < 2; ++n) _Pragma("unroll") for (int k = 0; k < 2; ++k) \
;         acc[ai][bj][m][n] = __builtin_amdgcn_mfma_f32_16x16x32_bf16(Bt[n][k], At[m][k], acc[ai][bj][m][n], 0, 0, 0); __builtin_amdgcn_s_setprio(0); } while (0)
; #define PG8_WAIT_V(n) asm volatile("s_waitcnt vmcnt(" #n ")" ::: "memory")
; #define PG8_WAIT_L(n) asm volatile("s_waitcnt lgkmcnt(" #n ")" ::: "memory")
; #define PG8_BAR __builtin_amdgcn_s_barrier()
; #define PG8_SCHED __builtin_amdgcn_sched_barrier(0)
; template <class Epi, class Sched, bool ALIGN_EPI = false, bool SP2 = false>
; __device__ __forceinline__ void gemm_phase(PG8_LAS unsigned char* lds, const Gemm g, const Sched& S, const Epi& E) {
;     ...
;         for (int t = 0; t < nt; t += 2) {
;             const bool last = (t == nt - 2);
;     ...
;             PG8_LDA(At, 1, 1); PG8_STAGE(PG8_SB(1, 0), b3, voffB); PG8_STAGE(PG8_SB(1, 1), b3 + hstepB, voffB); PG8_STAGE(PG8_SA(1, 0), a3, voffA);
;             PG8_WAIT_V(8); PG8_WAIT_L(0); PG8_BAR; PG8_MMA(1, 0, At, B0); PG8_MMA(1, 1, At, B1); PG8_BAR; PG8_SCHED;
	s_add_i32 s42, s61, s47
	v_lshl_add_u64 v[172:173], v[172:173], 0, s[16:17]
	s_mov_b32 m0, s42
	ds_read_b128 v[188:191], v158 offset:49152
	ds_read_b128 v[192:195], v158 offset:50176
	ds_read_b128 v[196:199], v158 offset:51200
	ds_read_b128 v[200:203], v158 offset:52224
	ds_read_b128 v[204:207], v158 offset:53248
	ds_read_b128 v[208:211], v158 offset:54272
	ds_read_b128 v[212:215], v158 offset:55296
	ds_read_b128 v[220:223], v158 offset:56320
	global_load_lds_dwordx4 v[172:173], off
	s_add_i32 m0, s42, 0x2000
	s_add_u32 s40, s40, 0x20080
	v_lshl_add_u64 v[172:173], v[216:217], 0, s[16:17]
	s_addc_u32 s41, s41, 0
	s_add_i32 s42, s62, s47
	global_load_lds_dwordx4 v[172:173], off
	v_lshl_add_u64 v[172:173], s[40:41], 0, v[132:133]
	s_mov_b32 m0, s42
	s_nop 0
	global_load_lds_dwordx4 v[172:173], off
	v_lshl_add_u64 v[172:173], s[40:41], 0, v[136:137]
	s_add_i32 m0, s42, 0x2000
	s_nop 0
	global_load_lds_dwordx4 v[172:173], off
	v_lshl_add_u64 v[172:173], v[224:225], 0, s[16:17]
	s_mov_b32 m0, s52
	s_nop 0
	global_load_lds_dwordx4 v[172:173], off
	v_lshl_add_u64 v[172:173], v[226:227], 0, s[16:17]
	s_mov_b32 m0, s53
	s_nop 0
	global_load_lds_dwordx4 v[172:173], off
	s_waitcnt vmcnt(8)
	s_waitcnt lgkmcnt(0)
	s_barrier
	s_setprio 1
	s_waitcnt lgkmcnt(0)
	v_mfma_f32_16x16x32_bf16 v[62:65], v[146:149], v[188:191], v[62:65]
	v_mfma_f32_16x16x32_bf16 v[58:61], v[160:163], v[188:191], v[58:61]
	v_mfma_f32_16x16x32_bf16 v[46:49], v[146:149], v[196:199], v[46:49]
	v_mfma_f32_16x16x32_bf16 v[42:45], v[160:163], v[196:199], v[42:45]
	v_mfma_f32_16x16x32_bf16 v[30:33], v[146:149], v[204:207], v[30:33]
	v_mfma_f32_16x16x32_bf16 v[26:29], v[160:163], v[204:207], v[26:29]
	v_mfma_f32_16x16x32_bf16 v[14:17], v[146:149], v[212:215], v[14:17]
	v_mfma_f32_16x16x32_bf16 v[10:13], v[160:163], v[212:215], v[10:13]
	v_mfma_f32_16x16x32_bf16 v[62:65], v[150:153], v[192:195], v[62:65]
	v_mfma_f32_16x16x32_bf16 v[58:61], v[164:167], v[192:195], v[58:61]
	v_mfma_f32_16x16x32_bf16 v[46:49], v[150:153], v[200:203], v[46:49]
	v_mfma_f32_16x16x32_bf16 v[42:45], v[164:167], v[200:203], v[42:45]
	v_mfma_f32_16x16x32_bf16 v[30:33], v[150:153], v[208:211], v[30:33]
	v_mfma_f32_16x16x32_bf16 v[26:29], v[164:167], v[208:211], v[26:29]
	v_mfma_f32_16x16x32_bf16 v[14:17], v[150:153], v[220:223], v[14:17]
	v_mfma_f32_16x16x32_bf16 v[10:13], v[164:167], v[220:223], v[10:13]
	s_setprio 0
	s_setprio 1
	v_mfma_f32_16x16x32_bf16 v[54:57], v[168:171], v[188:191], v[54:57]
	v_mfma_f32_16x16x32_bf16 v[50:53], v[180:183], v[188:191], v[50:53]
	v_mfma_f32_16x16x32_bf16 v[38:41], v[168:171], v[196:199], v[38:41]
	v_mfma_f32_16x16x32_bf16 v[34:37], v[180:183], v[196:199], v[34:37]
	v_mfma_f32_16x16x32_bf16 v[22:25], v[168:171], v[204:207], v[22:25]
	v_mfma_f32_16x16x32_bf16 v[18:21], v[180:183], v[204:207], v[18:21]
	v_mfma_f32_16x16x32_bf16 v[6:9], v[168:171], v[212:215], v[6:9]
	v_mfma_f32_16x16x32_bf16 v[2:5], v[180:183], v[212:215], v[2:5]
	v_mfma_f32_16x16x32_bf16 v[54:57], v[176:179], v[192:195], v[54:57]
	v_mfma_f32_16x16x32_bf16 v[50:53], v[184:187], v[192:195], v[50:53]
	v_mfma_f32_16x16x32_bf16 v[38:41], v[176:179], v[200:203], v[38:41]
	v_mfma_f32_16x16x32_bf16 v[34:37], v[184:187], v[200:203], v[34:37]
	v_mfma_f32_16x16x32_bf16 v[22:25], v[176:179], v[208:211], v[22:25]
	v_mfma_f32_16x16x32_bf16 v[18:21], v[184:187], v[208:211], v[18:21]
	v_mfma_f32_16x16x32_bf16 v[6:9], v[176:179], v[220:223], v[6:9]
	v_mfma_f32_16x16x32_bf16 v[2:5], v[184:187], v[220:223], v[2:5]
	s_setprio 0
	s_add_i32 s60, s60, 2
	s_add_u32 s36, s36, 0x100
	s_addc_u32 s37, s37, 0
	s_add_u32 s58, s58, 0x100
	s_addc_u32 s59, s59, 0
	s_cmp_gt_u32 s60, 5
	s_barrier
	s_cbranch_scc0 .LBB0_976
	s_and_b64 vcc, exec, s[18:19]
	s_cbranch_vccz .LBB0_979
	s_barrier

; #define PG8_STAGE(bufoff, gbase, voff) do { _Pragma("unroll") for (int _i = 0; _i < 2; ++_i) \
;         __builtin_amdgcn_global_load_lds((const unsigned*)((const char*)(gbase) + (voff)[_i]), (PG8_LAS unsigned*)(lds + (bufoff) + ldsw + _i * 8192), 16, 0, 0); } while (0)
; #define PG8_LDA(dst, b, h) do { _Pragma("unroll") for (int m = 0; m < 4; ++m) _Pragma("unroll") for (int k = 0; k < 2; ++k) dst[m][k] = *(const PG8_LAS bf16x8*)(lds + PG8_SA(b, h) + aoff + m * 2048 + k * 1024); } while (0)
; #define PG8_LDB(dst, b, h) do { _Pragma("unroll") for (int n = 0; n < 2; ++n) _Pragma("unroll") for (int k = 0; k < 2; ++k) dst[n][k] = *(const PG8_LAS bf16x8*)(lds + PG8_SB(b, h) + boff + n * 2048 + k * 1024); } while (0)
; #define PG8_MMA(ai, bj, At, Bt) do { __builtin_amdgcn_s_setprio(1); _Pragma("unroll") for (int m = 0; m < 4; ++m) _Pragma("unroll") for (int n = 0; n < 2; ++n) _Pragma("unroll") for (int k = 0; k < 2; ++k) \
;         acc[ai][bj][m][n] = __builtin_amdgcn_mfma_f32_16x16x32_bf16(Bt[n][k], At[m][k], acc[ai][bj][m][n], 0, 0, 0); __builtin_amdgcn_s_setprio(0); } while (0)
; #define PG8_WAIT_V(n) asm volatile("s_waitcnt vmcnt(" #n ")" ::: "memory")
; #define PG8_WAIT_L(n) asm volatile("s_waitcnt lgkmcnt(" #n ")" ::: "memory")
; #define PG8_BAR __builtin_amdgcn_s_barrier()
; #define PG8_SCHED __builtin_amdgcn_sched_barrier(0)
; template <class Epi, class Sched, bool ALIGN_EPI = false, bool SP2 = false>
; __device__ __forceinline__ void gemm_phase(PG8_LAS unsigned char* lds, const Gemm g, const Sched& S, const Epi& E) {
;     ...
;         for (int t = 0; t < nt; t += 2) {
;             const bool last = (t == nt - 2);
;             const char* a1 = cA + (size_t)(t + 1) * kstep;
;             const char* a2 = last ? nA : cA + (size_t)(t + 2) * kstep; const char* b2 = last ? nB : cB + (size_t)(t + 2) * kstep;
;             const char* a3 = a2 + kstep; const char* b3 = b2 + kstep;
;             if (last && has_next) S.a_ready(nxt);
;             if constexpr (SP2) {
;             PG8_LDB(B0, 0, 0); PG8_LDB(B1, 0, 1); PG8_SCHED; PG8_LDA(At, 0, 0); PG8_STAGE(PG8_SA(1, 1), a1 + hstepA, voffA);
;             PG8_WAIT_V(8); PG8_WAIT_L(0); PG8_BAR; PG8_MMA(0, 0, At, B0); PG8_MMA(0, 1, At, B1); PG8_BAR; PG8_SCHED;
;             PG8_LDA(At, 0, 1); PG8_STAGE(PG8_SB(0, 0), b2, voffB); PG8_STAGE(PG8_SB(0, 1), b2 + hstepB, voffB); PG8_STAGE(PG8_SA(0, 0), a2, voffA);
.LBB0_1081:
	ds_read_b128 v[130:133], v166
	ds_read_b128 v[134:137], v166 offset:1024
	ds_read_b128 v[154:157], v166 offset:2048
	ds_read_b128 v[158:161], v166 offset:3072
	ds_read_b128 v[170:173], v167
	ds_read_b128 v[176:179], v167 offset:1024
	ds_read_b128 v[180:183], v167 offset:2048
	ds_read_b128 v[184:187], v167 offset:3072
	s_add_u32 s40, s36, 0xfffc0080
	s_addc_u32 s41, s37, -1
	s_cmp_eq_u32 s59, 12
	s_cselect_b32 s43, s25, s41
	s_cselect_b32 s42, s31, s40
	s_cselect_b32 s41, s23, s58
	s_cselect_b32 s40, s38, s39
	v_lshl_add_u64 v[162:163], s[36:37], 0, v[146:147]
	s_add_i32 m0, s35, 0xc000
	ds_read_b128 v[188:191], v168
	ds_read_b128 v[192:195], v168 offset:1024
	ds_read_b128 v[196:199], v168 offset:2048
	ds_read_b128 v[200:203], v168 offset:3072
	ds_read_b128 v[204:207], v168 offset:4096
	ds_read_b128 v[208:211], v168 offset:5120
	ds_read_b128 v[212:215], v168 offset:6144
	ds_read_b128 v[220:223], v168 offset:7168
	global_load_lds_dwordx4 v[162:163], off
	v_lshl_add_u64 v[162:163], s[36:37], 0, v[148:149]
	s_add_i32 m0, s35, 0xe000
	s_nop 0
	global_load_lds_dwordx4 v[162:163], off
	s_waitcnt vmcnt(8)
	s_waitcnt lgkmcnt(0)
	s_barrier
	s_setprio 1
	s_waitcnt lgkmcnt(0)
	v_mfma_f32_16x16x32_bf16 v[126:129], v[130:133], v[188:191], v[126:129]
	v_mfma_f32_16x16x32_bf16 v[122:125], v[154:157], v[188:191], v[122:125]
	v_mfma_f32_16x16x32_bf16 v[110:113], v[130:133], v[196:199], v[110:113]
	v_mfma_f32_16x16x32_bf16 v[106:109], v[154:157], v[196:199], v[106:109]
	v_mfma_f32_16x16x32_bf16 v[94:97], v[130:133], v[204:207], v[94:97]
	v_mfma_f32_16x16x32_bf16 v[90:93], v[154:157], v[204:207], v[90:93]
	v_mfma_f32_16x16x32_bf16 v[78:81], v[130:133], v[212:215], v[78:81]
	v_mfma_f32_16x16x32_bf16 v[74:77], v[154:157], v[212:215], v[74:77]
	v_mfma_f32_16x16x32_bf16 v[126:129], v[134:137], v[192:195], v[126:129]
	v_mfma_f32_16x16x32_bf16 v[122:125], v[158:161], v[192:195], v[122:125]
	v_mfma_f32_16x16x32_bf16 v[110:113], v[134:137], v[200:203], v[110:113]
	v_mfma_f32_16x16x32_bf16 v[106:109], v[158:161], v[200:203], v[106:109]
	v_mfma_f32_16x16x32_bf16 v[94:97], v[134:137], v[208:211], v[94:97]
	v_mfma_f32_16x16x32_bf16 v[90:93], v[158:161], v[208:211], v[90:93]
	v_mfma_f32_16x16x32_bf16 v[78:81], v[134:137], v[220:223], v[78:81]
	v_mfma_f32_16x16x32_bf16 v[74:77], v[158:161], v[220:223], v[74:77]
	s_setprio 0
	s_setprio 1
	v_mfma_f32_16x16x32_bf16 v[118:121], v[170:173], v[188:191], v[118:121]
	v_mfma_f32_16x16x32_bf16 v[114:117], v[180:183], v[188:191], v[114:117]
	v_mfma_f32_16x16x32_bf16 v[102:105], v[170:173], v[196:199], v[102:105]
	v_mfma_f32_16x16x32_bf16 v[98:101], v[180:183], v[196:199], v[98:101]
	v_mfma_f32_16x16x32_bf16 v[86:89], v[170:173], v[204:207], v[86:89]
	v_mfma_f32_16x16x32_bf16 v[82:85], v[180:183], v[204:207], v[82:85]
	v_mfma_f32_16x16x32_bf16 v[70:73], v[170:173], v[212:215], v[70:73]
	v_mfma_f32_16x16x32_bf16 v[66:69], v[180:183], v[212:215], v[66:69]
	v_mfma_f32_16x16x32_bf16 v[118:121], v[176:179], v[192:195], v[118:121]
	v_mfma_f32_16x16x32_bf16 v[114:117], v[184:187], v[192:195], v[114:117]
	v_mfma_f32_16x16x32_bf16 v[102:105], v[176:179], v[200:203], v[102:105]
	v_mfma_f32_16x16x32_bf16 v[98:101], v[184:187], v[200:203], v[98:101]
	v_mfma_f32_16x16x32_bf16 v[86:89], v[176:179], v[208:211], v[86:89]
	v_mfma_f32_16x16x32_bf16 v[82:85], v[184:187], v[208:211], v[82:85]
	v_mfma_f32_16x16x32_bf16 v[70:73], v[176:179], v[220:223], v[70:73]
	v_mfma_f32_16x16x32_bf16 v[66:69], v[184:187], v[220:223], v[66:69]
	s_setprio 0
	s_barrier
	s_add_i32 s60, s56, s47
	v_lshl_add_u64 v[162:163], s[40:41], 0, v[140:141]
	s_mov_b32 m0, s60
	ds_read_b128 v[188:191], v168 offset:16384
	ds_read_b128 v[192:195], v168 offset:17408
	ds_read_b128 v[196:199], v168 offset:18432
	ds_read_b128 v[200:203], v168 offset:19456
	ds_read_b128 v[204:207], v168 offset:20480
	ds_read_b128 v[208:211], v168 offset:21504
	ds_read_b128 v[212:215], v168 offset:22528
	ds_read_b128 v[220:223], v168 offset:23552
	global_load_lds_dwordx4 v[162:163], off
	s_add_i32 m0, s60, 0x2000
	s_add_u32 s60, s40, 0x40000
	v_lshl_add_u64 v[216:217], s[40:41], 0, v[144:145]
	s_addc_u32 s61, s41, 0
	s_add_i32 s62, s57, s47
	global_load_lds_dwordx4 v[216:217], off
	v_lshl_add_u64 v[224:225], s[60:61], 0, v[140:141]
	s_mov_b32 m0, s62
	v_lshl_add_u64 v[226:227], s[42:43], 0, v[142:143]
	global_load_lds_dwordx4 v[224:225], off
	v_lshl_add_u64 v[224:225], s[60:61], 0, v[144:145]
	s_add_i32 m0, s62, 0x2000
	s_nop 0
	global_load_lds_dwordx4 v[224:225], off
	v_lshl_add_u64 v[224:225], s[42:43], 0, v[138:139]
	s_mov_b32 m0, s35
	s_nop 0
	global_load_lds_dwordx4 v[224:225], off
	s_mov_b32 m0, s48
	s_nop 0
	global_load_lds_dwordx4 v[226:227], off
	s_waitcnt vmcnt(8)
	s_waitcnt lgkmcnt(0)
	s_barrier
; #define PG8_STAGE(bufoff, gbase, voff) do { _Pragma("unroll") for (int _i = 0; _i < 2; ++_i) \
;         __builtin_amdgcn_global_load_lds((const unsigned*)((const char*)(gbase) + (voff)[_i]), (PG8_LAS unsigned*)(lds + (bufoff) + ldsw + _i * 8192), 16, 0, 0); } while (0)
; #define PG8_LDA(dst, b, h) do { _Pragma("unroll") for (int m = 0; m < 4; ++m) _Pragma("unroll") for (int k = 0; k < 2; ++k) dst[m][k] = *(const PG8_LAS bf16x8*)(lds + PG8_SA(b, h) + aoff + m * 2048 + k * 1024); } while (0)
; #define PG8_LDB(dst, b, h) do { _Pragma("unroll") for (int n = 0; n < 2; ++n) _Pragma("unroll") for (int k = 0; k < 2; ++k) dst[n][k] = *(const PG8_LAS bf16x8*)(lds + PG8_SB(b, h) + boff + n * 2048 + k * 1024); } while (0)
; #define PG8_MMA(ai, bj, At, Bt) do { __builtin_amdgcn_s_setprio(1); _Pragma("unroll") for (int m = 0; m < 4; ++m) _Pragma("unroll") for (int n = 0; n < 2; ++n) _Pragma("unroll") for (int k = 0; k < 2; ++k) \
;         acc[ai][bj][m][n] = __builtin_amdgcn_mfma_f32_16x16x32_bf16(Bt[n][k], At[m][k], acc[ai][bj][m][n], 0, 0, 0); __builtin_amdgcn_s_setprio(0); } while (0)
; #define PG8_WAIT_V(n) asm volatile("s_waitcnt vmcnt(" #n ")" ::: "memory")
; #define PG8_WAIT_L(n) asm volatile("s_waitcnt lgkmcnt(" #n ")" ::: "memory")
; #define PG8_BAR __builtin_amdgcn_s_barrier()
; #define PG8_SCHED __builtin_amdgcn_sched_barrier(0)
; template <class Epi, class Sched, bool ALIGN_EPI = false, bool SP2 = false>
; __device__ __forceinline__ void gemm_phase(PG8_LAS unsigned char* lds, const Gemm g, const Sched& S, const Epi& E) {
;     ...
;             PG8_WAIT_V(8); PG8_WAIT_L(0); PG8_BAR; PG8_MMA(1, 0, At, B0); PG8_MMA(1, 1, At, B1); PG8_BAR; PG8_SCHED;
;             PG8_LDB(B0, 1, 0); PG8_LDB(B1, 1, 1); PG8_SCHED; PG8_LDA(At, 1, 0); PG8_STAGE(PG8_SA(0, 1), a2 + hstepA, voffA);
;             PG8_WAIT_V(8); PG8_WAIT_L(0); PG8_BAR; PG8_MMA(0, 0, At, B0); PG8_MMA(0, 1, At, B1); PG8_BAR; PG8_SCHED;
	s_setprio 1
	s_waitcnt lgkmcnt(0)
	v_mfma_f32_16x16x32_bf16 v[62:65], v[130:133], v[188:191], v[62:65]
	v_mfma_f32_16x16x32_bf16 v[58:61], v[154:157], v[188:191], v[58:61]
	v_mfma_f32_16x16x32_bf16 v[46:49], v[130:133], v[196:199], v[46:49]
	v_mfma_f32_16x16x32_bf16 v[42:45], v[154:157], v[196:199], v[42:45]
	v_mfma_f32_16x16x32_bf16 v[30:33], v[130:133], v[204:207], v[30:33]
	v_mfma_f32_16x16x32_bf16 v[26:29], v[154:157], v[204:207], v[26:29]
	v_mfma_f32_16x16x32_bf16 v[14:17], v[130:133], v[212:215], v[14:17]
	v_mfma_f32_16x16x32_bf16 v[10:13], v[154:157], v[212:215], v[10:13]
	v_mfma_f32_16x16x32_bf16 v[62:65], v[134:137], v[192:195], v[62:65]
	v_mfma_f32_16x16x32_bf16 v[58:61], v[158:161], v[192:195], v[58:61]
	v_mfma_f32_16x16x32_bf16 v[46:49], v[134:137], v[200:203], v[46:49]
	v_mfma_f32_16x16x32_bf16 v[42:45], v[158:161], v[200:203], v[42:45]
	v_mfma_f32_16x16x32_bf16 v[30:33], v[134:137], v[208:211], v[30:33]
	v_mfma_f32_16x16x32_bf16 v[26:29], v[158:161], v[208:211], v[26:29]
	v_mfma_f32_16x16x32_bf16 v[14:17], v[134:137], v[220:223], v[14:17]
	v_mfma_f32_16x16x32_bf16 v[10:13], v[158:161], v[220:223], v[10:13]
	s_setprio 0
	s_setprio 1
	v_mfma_f32_16x16x32_bf16 v[54:57], v[170:173], v[188:191], v[54:57]
	v_mfma_f32_16x16x32_bf16 v[50:53], v[180:183], v[188:191], v[50:53]
	v_mfma_f32_16x16x32_bf16 v[38:41], v[170:173], v[196:199], v[38:41]
	v_mfma_f32_16x16x32_bf16 v[34:37], v[180:183], v[196:199], v[34:37]
	v_mfma_f32_16x16x32_bf16 v[22:25], v[170:173], v[204:207], v[22:25]
	v_mfma_f32_16x16x32_bf16 v[18:21], v[180:183], v[204:207], v[18:21]
	v_mfma_f32_16x16x32_bf16 v[6:9], v[170:173], v[212:215], v[6:9]
	v_mfma_f32_16x16x32_bf16 v[2:5], v[180:183], v[212:215], v[2:5]
	v_mfma_f32_16x16x32_bf16 v[54:57], v[176:179], v[192:195], v[54:57]
	v_mfma_f32_16x16x32_bf16 v[50:53], v[184:187], v[192:195], v[50:53]
	v_mfma_f32_16x16x32_bf16 v[38:41], v[176:179], v[200:203], v[38:41]
	v_mfma_f32_16x16x32_bf16 v[34:37], v[184:187], v[200:203], v[34:37]
	v_mfma_f32_16x16x32_bf16 v[22:25], v[176:179], v[208:211], v[22:25]
	v_mfma_f32_16x16x32_bf16 v[18:21], v[184:187], v[208:211], v[18:21]
	v_mfma_f32_16x16x32_bf16 v[6:9], v[176:179], v[220:223], v[6:9]
	v_mfma_f32_16x16x32_bf16 v[2:5], v[184:187], v[220:223], v[2:5]
	s_setprio 0
	s_barrier
	s_add_i32 s60, 0, 0x18000
	s_add_i32 s61, 0, 0x1c000
	v_add_u32_e32 v158, s60, v164
	v_add_u32_e32 v175, s61, v164
	ds_read_b128 v[130:133], v158
	ds_read_b128 v[134:137], v158 offset:1024
	ds_read_b128 v[154:157], v158 offset:2048
	ds_read_b128 v[158:161], v158 offset:3072
	ds_read_b128 v[170:173], v175
	ds_read_b128 v[176:179], v175 offset:1024
	ds_read_b128 v[180:183], v175 offset:2048
	ds_read_b128 v[184:187], v175 offset:3072
	s_add_u32 s42, s42, 0x40000
	s_addc_u32 s43, s43, 0
	s_mov_b32 m0, s49
	v_lshl_add_u64 v[228:229], s[42:43], 0, v[138:139]
	ds_read_b128 v[188:191], v168 offset:32768
	ds_read_b128 v[192:195], v168 offset:33792
	ds_read_b128 v[196:199], v168 offset:34816
	ds_read_b128 v[200:203], v168 offset:35840
	ds_read_b128 v[204:207], v168 offset:36864
	ds_read_b128 v[208:211], v168 offset:37888
	ds_read_b128 v[212:215], v168 offset:38912
	ds_read_b128 v[220:223], v168 offset:39936
	global_load_lds_dwordx4 v[228:229], off
	v_lshl_add_u64 v[228:229], s[42:43], 0, v[142:143]
	s_mov_b32 m0, s50
	s_nop 0
	global_load_lds_dwordx4 v[228:229], off
	s_waitcnt vmcnt(8)
	s_waitcnt lgkmcnt(0)
	s_barrier
	s_setprio 1
	s_waitcnt lgkmcnt(0)
	v_mfma_f32_16x16x32_bf16 v[126:129], v[130:133], v[188:191], v[126:129]
	v_mfma_f32_16x16x32_bf16 v[122:125], v[154:157], v[188:191], v[122:125]
	v_mfma_f32_16x16x32_bf16 v[110:113], v[130:133], v[196:199], v[110:113]
	v_mfma_f32_16x16x32_bf16 v[106:109], v[154:157], v[196:199], v[106:109]
	v_mfma_f32_16x16x32_bf16 v[94:97], v[130:133], v[204:207], v[94:97]
	v_mfma_f32_16x16x32_bf16 v[90:93], v[154:157], v[204:207], v[90:93]
	v_mfma_f32_16x16x32_bf16 v[78:81], v[130:133], v[212:215], v[78:81]
	v_mfma_f32_16x16x32_bf16 v[74:77], v[154:157], v[212:215], v[74:77]
	v_mfma_f32_16x16x32_bf16 v[126:129], v[134:137], v[192:195], v[126:129]
	v_mfma_f32_16x16x32_bf16 v[122:125], v[158:161], v[192:195], v[122:125]
	v_mfma_f32_16x16x32_bf16 v[110:113], v[134:137], v[200:203], v[110:113]
	v_mfma_f32_16x16x32_bf16 v[106:109], v[158:161], v[200:203], v[106:109]
	v_mfma_f32_16x16x32_bf16 v[94:97], v[134:137], v[208:211], v[94:97]
	v_mfma_f32_16x16x32_bf16 v[90:93], v[158:161], v[208:211], v[90:93]
	v_mfma_f32_16x16x32_bf16 v[78:81], v[134:137], v[220:223], v[78:81]
	v_mfma_f32_16x16x32_bf16 v[74:77], v[158:161], v[220:223], v[74:77]
	s_setprio 0
	s_setprio 1
	v_mfma_f32_16x16x32_bf16 v[118:121], v[170:173], v[188:191], v[118:121]
	v_mfma_f32_16x16x32_bf16 v[114:117], v[180:183], v[188:191], v[114:117]
	v_mfma_f32_16x16x32_bf16 v[102:105], v[170:173], v[196:199], v[102:105]
	v_mfma_f32_16x16x32_bf16 v[98:101], v[180:183], v[196:199], v[98:101]
	v_mfma_f32_16x16x32_bf16 v[86:89], v[170:173], v[204:207], v[86:89]
	v_mfma_f32_16x16x32_bf16 v[82:85], v[180:183], v[204:207], v[82:85]
	v_mfma_f32_16x16x32_bf16 v[70:73], v[170:173], v[212:215], v[70:73]
	v_mfma_f32_16x16x32_bf16 v[66:69], v[180:183], v[212:215], v[66:69]
	v_mfma_f32_16x16x32_bf16 v[118:121], v[176:179], v[192:195], v[118:121]
	v_mfma_f32_16x16x32_bf16 v[114:117], v[184:187], v[192:195], v[114:117]
	v_mfma_f32_16x16x32_bf16 v[102:105], v[176:179], v[200:203], v[102:105]
	v_mfma_f32_16x16x32_bf16 v[98:101], v[184:187], v[200:203], v[98:101]
	v_mfma_f32_16x16x32_bf16 v[86:89], v[176:179], v[208:211], v[86:89]
	v_mfma_f32_16x16x32_bf16 v[82:85], v[184:187], v[208:211], v[82:85]
	v_mfma_f32_16x16x32_bf16 v[70:73], v[176:179], v[220:223], v[70:73]
	v_mfma_f32_16x16x32_bf16 v[66:69], v[184:187], v[220:223], v[66:69]
	s_setprio 0
	s_barrier
; #define PG8_STAGE(bufoff, gbase, voff) do { _Pragma("unroll") for (int _i = 0; _i < 2; ++_i) \
;         __builtin_amdgcn_global_load_lds((const unsigned*)((const char*)(gbase) + (voff)[_i]), (PG8_LAS unsigned*)(lds + (bufoff) + ldsw + _i * 8192), 16, 0, 0); } while (0)
; #define PG8_LDA(dst, b, h) do { _Pragma("unroll") for (int m = 0; m < 4; ++m) _Pragma("unroll") for (int k = 0; k < 2; ++k) dst[m][k] = *(const PG8_LAS bf16x8*)(lds + PG8_SA(b, h) + aoff + m * 2048 + k * 1024); } while (0)
; #define PG8_MMA(ai, bj, At, Bt) do { __builtin_amdgcn_s_setprio(1); _Pragma("unroll") for (int m = 0; m < 4; ++m) _Pragma("unroll") for (int n = 0; n < 2; ++n) _Pragma("unroll") for (int k = 0; k < 2; ++k) \
;         acc[ai][bj][m][n] = __builtin_amdgcn_mfma_f32_16x16x32_bf16(Bt[n][k], At[m][k], acc[ai][bj][m][n], 0, 0, 0); __builtin_amdgcn_s_setprio(0); } while (0)
; #define PG8_WAIT_V(n) asm volatile("s_waitcnt vmcnt(" #n ")" ::: "memory")
; #define PG8_WAIT_L(n) asm volatile("s_waitcnt lgkmcnt(" #n ")" ::: "memory")
; #define PG8_BAR __builtin_amdgcn_s_barrier()
; #define PG8_SCHED __builtin_amdgcn_sched_barrier(0)
; template <class Epi, class Sched, bool ALIGN_EPI = false, bool SP2 = false>
; __device__ __forceinline__ void gemm_phase(PG8_LAS unsigned char* lds, const Gemm g, const Sched& S, const Epi& E) {
;     ...
;         for (int t = 0; t < nt; t += 2) {
;             const bool last = (t == nt - 2);
;     ...
;             PG8_LDA(At, 1, 1); PG8_STAGE(PG8_SB(1, 0), b3, voffB); PG8_STAGE(PG8_SB(1, 1), b3 + hstepB, voffB); PG8_STAGE(PG8_SA(1, 0), a3, voffA);
;             PG8_WAIT_V(8); PG8_WAIT_L(0); PG8_BAR; PG8_MMA(1, 0, At, B0); PG8_MMA(1, 1, At, B1); PG8_BAR; PG8_SCHED;
	s_add_i32 s42, s60, s47
	v_lshl_add_u64 v[162:163], v[162:163], 0, s[18:19]
	s_mov_b32 m0, s42
	ds_read_b128 v[188:191], v168 offset:49152
	ds_read_b128 v[192:195], v168 offset:50176
	ds_read_b128 v[196:199], v168 offset:51200
	ds_read_b128 v[200:203], v168 offset:52224
	ds_read_b128 v[204:207], v168 offset:53248
	ds_read_b128 v[208:211], v168 offset:54272
	ds_read_b128 v[212:215], v168 offset:55296
	ds_read_b128 v[220:223], v168 offset:56320
	global_load_lds_dwordx4 v[162:163], off
	s_add_i32 m0, s42, 0x2000
	s_add_u32 s40, s40, 0x40080
	v_lshl_add_u64 v[162:163], v[216:217], 0, s[18:19]
	s_addc_u32 s41, s41, 0
	s_add_i32 s42, s61, s47
	global_load_lds_dwordx4 v[162:163], off
	v_lshl_add_u64 v[162:163], s[40:41], 0, v[140:141]
	s_mov_b32 m0, s42
	s_nop 0
	global_load_lds_dwordx4 v[162:163], off
	v_lshl_add_u64 v[162:163], s[40:41], 0, v[144:145]
	s_add_i32 m0, s42, 0x2000
	s_nop 0
	global_load_lds_dwordx4 v[162:163], off
	v_lshl_add_u64 v[162:163], v[224:225], 0, s[18:19]
	s_mov_b32 m0, s52
	s_nop 0
	global_load_lds_dwordx4 v[162:163], off
	v_lshl_add_u64 v[162:163], v[226:227], 0, s[18:19]
	s_mov_b32 m0, s53
	s_nop 0
	global_load_lds_dwordx4 v[162:163], off
	s_waitcnt vmcnt(8)
	s_waitcnt lgkmcnt(0)
	s_barrier
	s_setprio 1
	s_waitcnt lgkmcnt(0)
	v_mfma_f32_16x16x32_bf16 v[62:65], v[130:133], v[188:191], v[62:65]
	v_mfma_f32_16x16x32_bf16 v[58:61], v[154:157], v[188:191], v[58:61]
	v_mfma_f32_16x16x32_bf16 v[46:49], v[130:133], v[196:199], v[46:49]
	v_mfma_f32_16x16x32_bf16 v[42:45], v[154:157], v[196:199], v[42:45]
	v_mfma_f32_16x16x32_bf16 v[30:33], v[130:133], v[204:207], v[30:33]
	v_mfma_f32_16x16x32_bf16 v[26:29], v[154:157], v[204:207], v[26:29]
	v_mfma_f32_16x16x32_bf16 v[14:17], v[130:133], v[212:215], v[14:17]
	v_mfma_f32_16x16x32_bf16 v[10:13], v[154:157], v[212:215], v[10:13]
	v_mfma_f32_16x16x32_bf16 v[62:65], v[134:137], v[192:195], v[62:65]
	v_mfma_f32_16x16x32_bf16 v[58:61], v[158:161], v[192:195], v[58:61]
	v_mfma_f32_16x16x32_bf16 v[46:49], v[134:137], v[200:203], v[46:49]
	v_mfma_f32_16x16x32_bf16 v[42:45], v[158:161], v[200:203], v[42:45]
	v_mfma_f32_16x16x32_bf16 v[30:33], v[134:137], v[208:211], v[30:33]
	v_mfma_f32_16x16x32_bf16 v[26:29], v[158:161], v[208:211], v[26:29]
	v_mfma_f32_16x16x32_bf16 v[14:17], v[134:137], v[220:223], v[14:17]
	v_mfma_f32_16x16x32_bf16 v[10:13], v[158:161], v[220:223], v[10:13]
	s_setprio 0
	s_setprio 1
	v_mfma_f32_16x16x32_bf16 v[54:57], v[170:173], v[188:191], v[54:57]
	v_mfma_f32_16x16x32_bf16 v[50:53], v[180:183], v[188:191], v[50:53]
	v_mfma_f32_16x16x32_bf16 v[38:41], v[170:173], v[196:199], v[38:41]
	v_mfma_f32_16x16x32_bf16 v[34:37], v[180:183], v[196:199], v[34:37]
	v_mfma_f32_16x16x32_bf16 v[22:25], v[170:173], v[204:207], v[22:25]
	v_mfma_f32_16x16x32_bf16 v[18:21], v[180:183], v[204:207], v[18:21]
	v_mfma_f32_16x16x32_bf16 v[6:9], v[170:173], v[212:215], v[6:9]
	v_mfma_f32_16x16x32_bf16 v[2:5], v[180:183], v[212:215], v[2:5]
	v_mfma_f32_16x16x32_bf16 v[54:57], v[176:179], v[192:195], v[54:57]
	v_mfma_f32_16x16x32_bf16 v[50:53], v[184:187], v[192:195], v[50:53]
	v_mfma_f32_16x16x32_bf16 v[38:41], v[176:179], v[200:203], v[38:41]
	v_mfma_f32_16x16x32_bf16 v[34:37], v[184:187], v[200:203], v[34:37]
	v_mfma_f32_16x16x32_bf16 v[22:25], v[176:179], v[208:211], v[22:25]
	v_mfma_f32_16x16x32_bf16 v[18:21], v[184:187], v[208:211], v[18:21]
	v_mfma_f32_16x16x32_bf16 v[6:9], v[176:179], v[220:223], v[6:9]
	v_mfma_f32_16x16x32_bf16 v[2:5], v[184:187], v[220:223], v[2:5]
	s_setprio 0
	s_add_i32 s59, s59, 2
	s_add_u32 s36, s36, 0x100
	s_addc_u32 s37, s37, 0
	s_add_u32 s39, s39, 0x100
	s_addc_u32 s58, s58, 0
	s_cmp_gt_u32 s59, 13
	s_barrier
	s_cbranch_scc0 .LBB0_1081
	s_and_b64 vcc, exec, s[20:21]
	s_cbranch_vccz .LBB0_1084
	s_barrier

; #define PG8_STAGE(bufoff, gbase, voff) do { _Pragma("unroll") for (int _i = 0; _i < 2; ++_i) \
;         __builtin_amdgcn_global_load_lds((const unsigned*)((const char*)(gbase) + (voff)[_i]), (PG8_LAS unsigned*)(lds + (bufoff) + ldsw + _i * 8192), 16, 0, 0); } while (0)
; #define PG8_LDA(dst, b, h) do { _Pragma("unroll") for (int m = 0; m < 4; ++m) _Pragma("unroll") for (int k = 0; k < 2; ++k) dst[m][k] = *(const PG8_LAS bf16x8*)(lds + PG8_SA(b, h) + aoff + m * 2048 + k * 1024); } while (0)
; #define PG8_LDB(dst, b, h) do { _Pragma("unroll") for (int n = 0; n < 2; ++n) _Pragma("unroll") for (int k = 0; k < 2; ++k) dst[n][k] = *(const PG8_LAS bf16x8*)(lds + PG8_SB(b, h) + boff + n * 2048 + k * 1024); } while (0)
; #define PG8_MMA(ai, bj, At, Bt) do { __builtin_amdgcn_s_setprio(1); _Pragma("unroll") for (int m = 0; m < 4; ++m) _Pragma("unroll") for (int n = 0; n < 2; ++n) _Pragma("unroll") for (int k = 0; k < 2; ++k) \
;         acc[ai][bj][m][n] = __builtin_amdgcn_mfma_f32_16x16x32_bf16(Bt[n][k], At[m][k], acc[ai][bj][m][n], 0, 0, 0); __builtin_amdgcn_s_setprio(0); } while (0)
; #define PG8_WAIT_V(n) asm volatile("s_waitcnt vmcnt(" #n ")" ::: "memory")
; #define PG8_WAIT_L(n) asm volatile("s_waitcnt lgkmcnt(" #n ")" ::: "memory")
; #define PG8_BAR __builtin_amdgcn_s_barrier()
; #define PG8_SCHED __builtin_amdgcn_sched_barrier(0)
; template <class Epi, class Sched, bool ALIGN_EPI = false, bool SP2 = false>
; __device__ __forceinline__ void gemm_phase(PG8_LAS unsigned char* lds, const Gemm g, const Sched& S, const Epi& E) {
;     ...
;         for (int t = 0; t < nt; t += 2) {
;             const bool last = (t == nt - 2);
;             const char* a1 = cA + (size_t)(t + 1) * kstep;
;             const char* a2 = last ? nA : cA + (size_t)(t + 2) * kstep; const char* b2 = last ? nB : cB + (size_t)(t + 2) * kstep;
;             const char* a3 = a2 + kstep; const char* b3 = b2 + kstep;
;             if (last && has_next) S.a_ready(nxt);
;             if constexpr (SP2) {
;             PG8_LDB(B0, 0, 0); PG8_LDB(B1, 0, 1); PG8_SCHED; PG8_LDA(At, 0, 0); PG8_STAGE(PG8_SA(1, 1), a1 + hstepA, voffA);
;             PG8_WAIT_V(8); PG8_WAIT_L(0); PG8_BAR; PG8_MMA(0, 0, At, B0); PG8_MMA(0, 1, At, B1); PG8_BAR; PG8_SCHED;
;             PG8_LDA(At, 0, 1); PG8_STAGE(PG8_SB(0, 0), b2, voffB); PG8_STAGE(PG8_SB(0, 1), b2 + hstepB, voffB); PG8_STAGE(PG8_SA(0, 0), a2, voffA);
.LBB0_1192:
	ds_read_b128 v[60:63], v224
	ds_read_b128 v[64:67], v224 offset:1024
	ds_read_b128 v[72:75], v224 offset:2048
	ds_read_b128 v[76:79], v224 offset:3072
	ds_read_b128 v[80:83], v225
	ds_read_b128 v[84:87], v225 offset:1024
	ds_read_b128 v[88:91], v225 offset:2048
	ds_read_b128 v[92:95], v225 offset:3072
	s_add_u32 s60, s58, 0x100
	s_addc_u32 s61, s59, 0
	s_cmp_eq_u32 s57, 12
	s_cselect_b32 s65, s33, s61
	s_cselect_b32 s64, s38, s60
	s_cselect_b32 s63, s39, s55
	s_cselect_b32 s62, s47, s49
	v_lshl_add_u64 v[148:149], s[58:59], 0, v[190:191]
	s_add_i32 m0, s71, 0xc000
	ds_read_b128 v[112:115], v226
	ds_read_b128 v[140:143], v226 offset:1024
	ds_read_b128 v[170:173], v226 offset:2048
	ds_read_b128 v[174:177], v226 offset:3072
	ds_read_b128 v[178:181], v226 offset:4096
	ds_read_b128 v[198:201], v226 offset:5120
	ds_read_b128 v[202:205], v226 offset:6144
	ds_read_b128 v[206:209], v226 offset:7168
	global_load_lds_dwordx4 v[148:149], off
	v_lshl_add_u64 v[148:149], s[58:59], 0, v[192:193]
	s_add_i32 m0, s71, 0xe000
	s_nop 0
	global_load_lds_dwordx4 v[148:149], off
	s_waitcnt vmcnt(8)
	s_waitcnt lgkmcnt(0)
	s_barrier
	s_setprio 1
	s_waitcnt lgkmcnt(0)
	v_mfma_f32_16x16x32_bf16 v[154:157], v[60:63], v[112:115], v[154:157]
	v_mfma_f32_16x16x32_bf16 v[158:161], v[72:75], v[112:115], v[158:161]
	v_mfma_f32_16x16x32_bf16 v[128:131], v[60:63], v[170:173], v[128:131]
	v_mfma_f32_16x16x32_bf16 v[124:127], v[72:75], v[170:173], v[124:127]
	v_mfma_f32_16x16x32_bf16 v[162:165], v[60:63], v[178:181], v[162:165]
	v_mfma_f32_16x16x32_bf16 v[148:151], v[72:75], v[178:181], v[150:153]
	v_mfma_f32_16x16x32_bf16 v[166:169], v[60:63], v[202:205], v[166:169]
	v_mfma_f32_16x16x32_bf16 v[144:147], v[72:75], v[202:205], v[144:147]
	v_mfma_f32_16x16x32_bf16 v[154:157], v[64:67], v[140:143], v[154:157]
	v_mfma_f32_16x16x32_bf16 v[158:161], v[76:79], v[140:143], v[158:161]
	v_mfma_f32_16x16x32_bf16 v[128:131], v[64:67], v[174:177], v[128:131]
	v_mfma_f32_16x16x32_bf16 v[124:127], v[76:79], v[174:177], v[124:127]
	v_mfma_f32_16x16x32_bf16 v[162:165], v[64:67], v[198:201], v[162:165]
	v_mfma_f32_16x16x32_bf16 v[148:151], v[76:79], v[198:201], v[148:151]
	v_mfma_f32_16x16x32_bf16 v[166:169], v[64:67], v[206:209], v[166:169]
	v_mfma_f32_16x16x32_bf16 v[144:147], v[76:79], v[206:209], v[144:147]
	s_setprio 0
	s_setprio 1
	v_mfma_f32_16x16x32_bf16 v[136:139], v[80:83], v[112:115], v[136:139]
	v_mfma_f32_16x16x32_bf16 v[120:123], v[80:83], v[170:173], v[120:123]
	v_mfma_f32_16x16x32_bf16 v[116:119], v[88:91], v[170:173], v[116:119]
	v_mfma_f32_16x16x32_bf16 v[104:107], v[80:83], v[178:181], v[104:107]
	v_mfma_f32_16x16x32_bf16 v[108:111], v[88:91], v[178:181], v[108:111]
	v_mfma_f32_16x16x32_bf16 v[96:99], v[80:83], v[202:205], v[96:99]
	v_mfma_f32_16x16x32_bf16 v[100:103], v[88:91], v[202:205], v[100:103]
	v_mfma_f32_16x16x32_bf16 v[136:139], v[84:87], v[140:143], v[136:139]
	v_mfma_f32_16x16x32_bf16 v[112:115], v[88:91], v[112:115], v[132:135]
	v_mfma_f32_16x16x32_bf16 v[120:123], v[84:87], v[174:177], v[120:123]
	v_mfma_f32_16x16x32_bf16 v[116:119], v[92:95], v[174:177], v[116:119]
	v_mfma_f32_16x16x32_bf16 v[104:107], v[84:87], v[198:201], v[104:107]
	v_mfma_f32_16x16x32_bf16 v[108:111], v[92:95], v[198:201], v[108:111]
	v_mfma_f32_16x16x32_bf16 v[96:99], v[84:87], v[206:209], v[96:99]
	v_mfma_f32_16x16x32_bf16 v[100:103], v[92:95], v[206:209], v[100:103]
	v_mfma_f32_16x16x32_bf16 v[112:115], v[92:95], v[140:143], v[112:115]
	s_setprio 0
	s_barrier
	s_add_i32 s58, s90, s70
	v_lshl_add_u64 v[210:211], s[62:63], 0, v[184:185]
	s_mov_b32 m0, s58
	ds_read_b128 v[132:135], v226 offset:16384
	ds_read_b128 v[140:143], v226 offset:17408
	ds_read_b128 v[170:173], v226 offset:18432
	ds_read_b128 v[174:177], v226 offset:19456
	ds_read_b128 v[178:181], v226 offset:20480
	ds_read_b128 v[198:201], v226 offset:21504
	ds_read_b128 v[202:205], v226 offset:22528
	ds_read_b128 v[206:209], v226 offset:23552
	global_load_lds_dwordx4 v[210:211], off
	s_add_i32 m0, s58, 0x2000
	s_add_u32 s58, s62, 0x40000
	v_lshl_add_u64 v[212:213], s[62:63], 0, v[188:189]
	s_addc_u32 s59, s63, 0
	s_add_i32 s72, s91, s70
	global_load_lds_dwordx4 v[212:213], off
	v_lshl_add_u64 v[152:153], s[58:59], 0, v[184:185]
	s_mov_b32 m0, s72
	v_lshl_add_u64 v[214:215], s[64:65], 0, v[182:183]
	global_load_lds_dwordx4 v[152:153], off
	v_lshl_add_u64 v[152:153], s[58:59], 0, v[188:189]
	s_add_i32 m0, s72, 0x2000
	v_lshl_add_u64 v[216:217], s[64:65], 0, v[186:187]
	global_load_lds_dwordx4 v[152:153], off
	s_mov_b32 m0, s71
	s_nop 0
	global_load_lds_dwordx4 v[214:215], off
	s_mov_b32 m0, s76
	s_nop 0
	global_load_lds_dwordx4 v[216:217], off
	s_waitcnt vmcnt(8)
	s_waitcnt lgkmcnt(0)
	s_barrier
; #define PG8_STAGE(bufoff, gbase, voff) do { _Pragma("unroll") for (int _i = 0; _i < 2; ++_i) \
;         __builtin_amdgcn_global_load_lds((const unsigned*)((const char*)(gbase) + (voff)[_i]), (PG8_LAS unsigned*)(lds + (bufoff) + ldsw + _i * 8192), 16, 0, 0); } while (0)
; #define PG8_LDA(dst, b, h) do { _Pragma("unroll") for (int m = 0; m < 4; ++m) _Pragma("unroll") for (int k = 0; k < 2; ++k) dst[m][k] = *(const PG8_LAS bf16x8*)(lds + PG8_SA(b, h) + aoff + m * 2048 + k * 1024); } while (0)
; #define PG8_LDB(dst, b, h) do { _Pragma("unroll") for (int n = 0; n < 2; ++n) _Pragma("unroll") for (int k = 0; k < 2; ++k) dst[n][k] = *(const PG8_LAS bf16x8*)(lds + PG8_SB(b, h) + boff + n * 2048 + k * 1024); } while (0)
; #define PG8_MMA(ai, bj, At, Bt) do { __builtin_amdgcn_s_setprio(1); _Pragma("unroll") for (int m = 0; m < 4; ++m) _Pragma("unroll") for (int n = 0; n < 2; ++n) _Pragma("unroll") for (int k = 0; k < 2; ++k) \
;         acc[ai][bj][m][n] = __builtin_amdgcn_mfma_f32_16x16x32_bf16(Bt[n][k], At[m][k], acc[ai][bj][m][n], 0, 0, 0); __builtin_amdgcn_s_setprio(0); } while (0)
; #define PG8_WAIT_V(n) asm volatile("s_waitcnt vmcnt(" #n ")" ::: "memory")
; #define PG8_WAIT_L(n) asm volatile("s_waitcnt lgkmcnt(" #n ")" ::: "memory")
; #define PG8_BAR __builtin_amdgcn_s_barrier()
; #define PG8_SCHED __builtin_amdgcn_sched_barrier(0)
; template <class Epi, class Sched, bool ALIGN_EPI = false, bool SP2 = false>
; __device__ __forceinline__ void gemm_phase(PG8_LAS unsigned char* lds, const Gemm g, const Sched& S, const Epi& E) {
;     ...
;             PG8_WAIT_V(8); PG8_WAIT_L(0); PG8_BAR; PG8_MMA(1, 0, At, B0); PG8_MMA(1, 1, At, B1); PG8_BAR; PG8_SCHED;
;             PG8_LDB(B0, 1, 0); PG8_LDB(B1, 1, 1); PG8_SCHED; PG8_LDA(At, 1, 0); PG8_STAGE(PG8_SA(0, 1), a2 + hstepA, voffA);
;             PG8_WAIT_V(8); PG8_WAIT_L(0); PG8_BAR; PG8_MMA(0, 0, At, B0); PG8_MMA(0, 1, At, B1); PG8_BAR; PG8_SCHED;
	s_setprio 1
	s_waitcnt lgkmcnt(0)
	v_mfma_f32_16x16x32_bf16 v[48:51], v[60:63], v[132:135], v[48:51]
	v_mfma_f32_16x16x32_bf16 v[52:55], v[72:75], v[132:135], v[52:55]
	v_mfma_f32_16x16x32_bf16 v[28:31], v[60:63], v[170:173], v[28:31]
	v_mfma_f32_16x16x32_bf16 v[24:27], v[72:75], v[170:173], v[24:27]
	v_mfma_f32_16x16x32_bf16 v[68:71], v[60:63], v[178:181], v[68:71]
	v_mfma_f32_16x16x32_bf16 v[44:47], v[72:75], v[178:181], v[44:47]
	v_mfma_f32_16x16x32_bf16 v[56:59], v[60:63], v[202:205], v[56:59]
	v_mfma_f32_16x16x32_bf16 v[40:43], v[72:75], v[202:205], v[40:43]
	v_mfma_f32_16x16x32_bf16 v[48:51], v[64:67], v[140:143], v[48:51]
	v_mfma_f32_16x16x32_bf16 v[52:55], v[76:79], v[140:143], v[52:55]
	v_mfma_f32_16x16x32_bf16 v[28:31], v[64:67], v[174:177], v[28:31]
	v_mfma_f32_16x16x32_bf16 v[24:27], v[76:79], v[174:177], v[24:27]
	v_mfma_f32_16x16x32_bf16 v[68:71], v[64:67], v[198:201], v[68:71]
	v_mfma_f32_16x16x32_bf16 v[44:47], v[76:79], v[198:201], v[44:47]
	v_mfma_f32_16x16x32_bf16 v[56:59], v[64:67], v[206:209], v[56:59]
	v_mfma_f32_16x16x32_bf16 v[40:43], v[76:79], v[206:209], v[40:43]
	s_setprio 0
	s_setprio 1
	v_mfma_f32_16x16x32_bf16 v[36:39], v[80:83], v[132:135], v[36:39]
	v_mfma_f32_16x16x32_bf16 v[32:35], v[88:91], v[132:135], v[32:35]
	v_mfma_f32_16x16x32_bf16 v[20:23], v[80:83], v[170:173], v[20:23]
	v_mfma_f32_16x16x32_bf16 v[16:19], v[88:91], v[170:173], v[16:19]
	v_mfma_f32_16x16x32_bf16 v[12:15], v[80:83], v[178:181], v[12:15]
	v_mfma_f32_16x16x32_bf16 v[8:11], v[88:91], v[178:181], v[8:11]
	v_mfma_f32_16x16x32_bf16 v[4:7], v[80:83], v[202:205], v[4:7]
	v_mfma_f32_16x16x32_bf16 v[0:3], v[88:91], v[202:205], v[0:3]
	v_mfma_f32_16x16x32_bf16 v[36:39], v[84:87], v[140:143], v[36:39]
	v_mfma_f32_16x16x32_bf16 v[32:35], v[92:95], v[140:143], v[32:35]
	v_mfma_f32_16x16x32_bf16 v[20:23], v[84:87], v[174:177], v[20:23]
	v_mfma_f32_16x16x32_bf16 v[16:19], v[92:95], v[174:177], v[16:19]
	v_mfma_f32_16x16x32_bf16 v[12:15], v[84:87], v[198:201], v[12:15]
	v_mfma_f32_16x16x32_bf16 v[8:11], v[92:95], v[198:201], v[8:11]
	v_mfma_f32_16x16x32_bf16 v[4:7], v[84:87], v[206:209], v[4:7]
	v_mfma_f32_16x16x32_bf16 v[0:3], v[92:95], v[206:209], v[0:3]
	s_setprio 0
	s_barrier
	s_add_i32 s72, 0, 0x18000
	s_add_i32 s73, 0, 0x1c000
	v_add_u32_e32 v76, s72, v219
	v_add_u32_e32 v92, s73, v219
	ds_read_b128 v[60:63], v76
	ds_read_b128 v[64:67], v76 offset:1024
	ds_read_b128 v[72:75], v76 offset:2048
	ds_read_b128 v[76:79], v76 offset:3072
	ds_read_b128 v[80:83], v92
	ds_read_b128 v[84:87], v92 offset:1024
	ds_read_b128 v[88:91], v92 offset:2048
	ds_read_b128 v[92:95], v92 offset:3072
	s_add_u32 s58, s64, 0x40000
	s_addc_u32 s59, s65, 0
	s_mov_b32 m0, s77
	v_lshl_add_u64 v[152:153], s[58:59], 0, v[182:183]
	ds_read_b128 v[132:135], v226 offset:32768
	ds_read_b128 v[140:143], v226 offset:33792
	ds_read_b128 v[170:173], v226 offset:34816
	ds_read_b128 v[174:177], v226 offset:35840
	ds_read_b128 v[178:181], v226 offset:36864
	ds_read_b128 v[198:201], v226 offset:37888
	ds_read_b128 v[202:205], v226 offset:38912
	ds_read_b128 v[206:209], v226 offset:39936
	global_load_lds_dwordx4 v[152:153], off
	v_lshl_add_u64 v[152:153], s[58:59], 0, v[186:187]
	s_mov_b32 m0, s78
	s_nop 0
	global_load_lds_dwordx4 v[152:153], off
	s_waitcnt vmcnt(8)
	s_waitcnt lgkmcnt(0)
	s_barrier
	s_setprio 1
	s_waitcnt lgkmcnt(0)
	v_mfma_f32_16x16x32_bf16 v[152:155], v[60:63], v[132:135], v[154:157]
	v_mfma_f32_16x16x32_bf16 v[158:161], v[72:75], v[132:135], v[158:161]
	v_mfma_f32_16x16x32_bf16 v[128:131], v[60:63], v[170:173], v[128:131]
	v_mfma_f32_16x16x32_bf16 v[124:127], v[72:75], v[170:173], v[124:127]
	v_mfma_f32_16x16x32_bf16 v[162:165], v[60:63], v[178:181], v[162:165]
	v_mfma_f32_16x16x32_bf16 v[148:151], v[72:75], v[178:181], v[148:151]
	v_mfma_f32_16x16x32_bf16 v[166:169], v[60:63], v[202:205], v[166:169]
	v_mfma_f32_16x16x32_bf16 v[144:147], v[72:75], v[202:205], v[144:147]
	v_mfma_f32_16x16x32_bf16 v[154:157], v[64:67], v[140:143], v[152:155]
	v_mfma_f32_16x16x32_bf16 v[158:161], v[76:79], v[140:143], v[158:161]
	v_mfma_f32_16x16x32_bf16 v[128:131], v[64:67], v[174:177], v[128:131]
	v_mfma_f32_16x16x32_bf16 v[124:127], v[76:79], v[174:177], v[124:127]
	v_mfma_f32_16x16x32_bf16 v[162:165], v[64:67], v[198:201], v[162:165]
	v_mfma_f32_16x16x32_bf16 v[150:153], v[76:79], v[198:201], v[148:151]
	v_mfma_f32_16x16x32_bf16 v[166:169], v[64:67], v[206:209], v[166:169]
	v_mfma_f32_16x16x32_bf16 v[144:147], v[76:79], v[206:209], v[144:147]
	s_setprio 0
	s_setprio 1
	v_mfma_f32_16x16x32_bf16 v[112:115], v[88:91], v[132:135], v[112:115]
	v_mfma_f32_16x16x32_bf16 v[136:139], v[80:83], v[132:135], v[136:139]
	v_mfma_f32_16x16x32_bf16 v[132:135], v[92:95], v[140:143], v[112:115]
	v_mfma_f32_16x16x32_bf16 v[112:115], v[80:83], v[170:173], v[120:123]
	v_mfma_f32_16x16x32_bf16 v[120:123], v[84:87], v[174:177], v[112:115]
	v_mfma_f32_16x16x32_bf16 v[112:115], v[88:91], v[170:173], v[116:119]
	v_mfma_f32_16x16x32_bf16 v[104:107], v[80:83], v[178:181], v[104:107]
	v_mfma_f32_16x16x32_bf16 v[108:111], v[88:91], v[178:181], v[108:111]
	v_mfma_f32_16x16x32_bf16 v[96:99], v[80:83], v[202:205], v[96:99]
	v_mfma_f32_16x16x32_bf16 v[100:103], v[88:91], v[202:205], v[100:103]
	v_mfma_f32_16x16x32_bf16 v[136:139], v[84:87], v[140:143], v[136:139]
	v_mfma_f32_16x16x32_bf16 v[116:119], v[92:95], v[174:177], v[112:115]
	v_mfma_f32_16x16x32_bf16 v[104:107], v[84:87], v[198:201], v[104:107]
	v_mfma_f32_16x16x32_bf16 v[108:111], v[92:95], v[198:201], v[108:111]
	v_mfma_f32_16x16x32_bf16 v[96:99], v[84:87], v[206:209], v[96:99]
	v_mfma_f32_16x16x32_bf16 v[100:103], v[92:95], v[206:209], v[100:103]
	s_setprio 0
	s_barrier
; #define PG8_STAGE(bufoff, gbase, voff) do { _Pragma("unroll") for (int _i = 0; _i < 2; ++_i) \
;         __builtin_amdgcn_global_load_lds((const unsigned*)((const char*)(gbase) + (voff)[_i]), (PG8_LAS unsigned*)(lds + (bufoff) + ldsw + _i * 8192), 16, 0, 0); } while (0)
; #define PG8_LDA(dst, b, h) do { _Pragma("unroll") for (int m = 0; m < 4; ++m) _Pragma("unroll") for (int k = 0; k < 2; ++k) dst[m][k] = *(const PG8_LAS bf16x8*)(lds + PG8_SA(b, h) + aoff + m * 2048 + k * 1024); } while (0)
; #define PG8_MMA(ai, bj, At, Bt) do { __builtin_amdgcn_s_setprio(1); _Pragma("unroll") for (int m = 0; m < 4; ++m) _Pragma("unroll") for (int n = 0; n < 2; ++n) _Pragma("unroll") for (int k = 0; k < 2; ++k) \
;         acc[ai][bj][m][n] = __builtin_amdgcn_mfma_f32_16x16x32_bf16(Bt[n][k], At[m][k], acc[ai][bj][m][n], 0, 0, 0); __builtin_amdgcn_s_setprio(0); } while (0)
; #define PG8_WAIT_V(n) asm volatile("s_waitcnt vmcnt(" #n ")" ::: "memory")
; #define PG8_WAIT_L(n) asm volatile("s_waitcnt lgkmcnt(" #n ")" ::: "memory")
; #define PG8_BAR __builtin_amdgcn_s_barrier()
; #define PG8_SCHED __builtin_amdgcn_sched_barrier(0)
; template <class Epi, class Sched, bool ALIGN_EPI = false, bool SP2 = false>
; __device__ __forceinline__ void gemm_phase(PG8_LAS unsigned char* lds, const Gemm g, const Sched& S, const Epi& E) {
;     ...
;         for (int t = 0; t < nt; t += 2) {
;             const bool last = (t == nt - 2);
;     ...
;             PG8_LDA(At, 1, 1); PG8_STAGE(PG8_SB(1, 0), b3, voffB); PG8_STAGE(PG8_SB(1, 1), b3 + hstepB, voffB); PG8_STAGE(PG8_SA(1, 0), a3, voffA);
;             PG8_WAIT_V(8); PG8_WAIT_L(0); PG8_BAR; PG8_MMA(1, 0, At, B0); PG8_MMA(1, 1, At, B1); PG8_BAR; PG8_SCHED;
	s_add_i32 s58, s72, s70
	v_lshl_add_u64 v[148:149], v[210:211], 0, s[26:27]
	s_mov_b32 m0, s58
	ds_read_b128 v[112:115], v226 offset:49152
	ds_read_b128 v[140:143], v226 offset:50176
	ds_read_b128 v[170:173], v226 offset:51200
	ds_read_b128 v[174:177], v226 offset:52224
	ds_read_b128 v[178:181], v226 offset:53248
	ds_read_b128 v[198:201], v226 offset:54272
	ds_read_b128 v[202:205], v226 offset:55296
	ds_read_b128 v[206:209], v226 offset:56320
	global_load_lds_dwordx4 v[148:149], off
	s_add_i32 m0, s58, 0x2000
	s_add_u32 s58, s62, 0x40080
	v_lshl_add_u64 v[148:149], v[212:213], 0, s[26:27]
	s_addc_u32 s59, s63, 0
	s_add_i32 s62, s73, s70
	global_load_lds_dwordx4 v[148:149], off
	v_lshl_add_u64 v[148:149], s[58:59], 0, v[184:185]
	s_mov_b32 m0, s62
	s_nop 0
	global_load_lds_dwordx4 v[148:149], off
	v_lshl_add_u64 v[148:149], s[58:59], 0, v[188:189]
	s_add_i32 m0, s62, 0x2000
	s_nop 0
	global_load_lds_dwordx4 v[148:149], off
	v_lshl_add_u64 v[148:149], v[214:215], 0, s[26:27]
	s_mov_b32 m0, s86
	s_nop 0
	global_load_lds_dwordx4 v[148:149], off
	v_lshl_add_u64 v[148:149], v[216:217], 0, s[26:27]
	s_mov_b32 m0, s87
	s_nop 0
	global_load_lds_dwordx4 v[148:149], off
	s_waitcnt vmcnt(8)
	s_waitcnt lgkmcnt(0)
	s_barrier
	s_setprio 1
	s_waitcnt lgkmcnt(0)
	v_mfma_f32_16x16x32_bf16 v[48:51], v[60:63], v[112:115], v[48:51]
	v_mfma_f32_16x16x32_bf16 v[52:55], v[72:75], v[112:115], v[52:55]
	v_mfma_f32_16x16x32_bf16 v[28:31], v[60:63], v[170:173], v[28:31]
	v_mfma_f32_16x16x32_bf16 v[24:27], v[72:75], v[170:173], v[24:27]
	v_mfma_f32_16x16x32_bf16 v[68:71], v[60:63], v[178:181], v[68:71]
	v_mfma_f32_16x16x32_bf16 v[44:47], v[72:75], v[178:181], v[44:47]
	v_mfma_f32_16x16x32_bf16 v[56:59], v[60:63], v[202:205], v[56:59]
	v_mfma_f32_16x16x32_bf16 v[40:43], v[72:75], v[202:205], v[40:43]
	v_mfma_f32_16x16x32_bf16 v[48:51], v[64:67], v[140:143], v[48:51]
	v_mfma_f32_16x16x32_bf16 v[52:55], v[76:79], v[140:143], v[52:55]
	v_mfma_f32_16x16x32_bf16 v[28:31], v[64:67], v[174:177], v[28:31]
	v_mfma_f32_16x16x32_bf16 v[24:27], v[76:79], v[174:177], v[24:27]
	v_mfma_f32_16x16x32_bf16 v[68:71], v[64:67], v[198:201], v[68:71]
	v_mfma_f32_16x16x32_bf16 v[44:47], v[76:79], v[198:201], v[44:47]
	v_mfma_f32_16x16x32_bf16 v[56:59], v[64:67], v[206:209], v[56:59]
	v_mfma_f32_16x16x32_bf16 v[40:43], v[76:79], v[206:209], v[40:43]
	s_setprio 0
	s_setprio 1
	v_mfma_f32_16x16x32_bf16 v[36:39], v[80:83], v[112:115], v[36:39]
	v_mfma_f32_16x16x32_bf16 v[32:35], v[88:91], v[112:115], v[32:35]
	v_mfma_f32_16x16x32_bf16 v[20:23], v[80:83], v[170:173], v[20:23]
	v_mfma_f32_16x16x32_bf16 v[16:19], v[88:91], v[170:173], v[16:19]
	v_mfma_f32_16x16x32_bf16 v[12:15], v[80:83], v[178:181], v[12:15]
	v_mfma_f32_16x16x32_bf16 v[8:11], v[88:91], v[178:181], v[8:11]
	v_mfma_f32_16x16x32_bf16 v[4:7], v[80:83], v[202:205], v[4:7]
	v_mfma_f32_16x16x32_bf16 v[0:3], v[88:91], v[202:205], v[0:3]
	v_mfma_f32_16x16x32_bf16 v[36:39], v[84:87], v[140:143], v[36:39]
	v_mfma_f32_16x16x32_bf16 v[32:35], v[92:95], v[140:143], v[32:35]
	v_mfma_f32_16x16x32_bf16 v[20:23], v[84:87], v[174:177], v[20:23]
	v_mfma_f32_16x16x32_bf16 v[16:19], v[92:95], v[174:177], v[16:19]
	v_mfma_f32_16x16x32_bf16 v[12:15], v[84:87], v[198:201], v[12:15]
	v_mfma_f32_16x16x32_bf16 v[8:11], v[92:95], v[198:201], v[8:11]
	v_mfma_f32_16x16x32_bf16 v[4:7], v[84:87], v[206:209], v[4:7]
	v_mfma_f32_16x16x32_bf16 v[0:3], v[92:95], v[206:209], v[0:3]
	s_setprio 0
	s_add_i32 s57, s57, 2
	s_add_u32 s49, s49, 0x100
	s_addc_u32 s55, s55, 0
	s_cmp_gt_u32 s57, 13
	s_mov_b64 s[58:59], s[60:61]
	s_barrier
	s_cbranch_scc0 .LBB0_1192
	s_and_b64 vcc, exec, s[28:29]
	s_cbranch_vccz .LBB0_1195
	s_barrier

; #define PG8_STAGE(bufoff, gbase, voff) do { _Pragma("unroll") for (int _i = 0; _i < 2; ++_i) \
;         __builtin_amdgcn_global_load_lds((const unsigned*)((const char*)(gbase) + (voff)[_i]), (PG8_LAS unsigned*)(lds + (bufoff) + ldsw + _i * 8192), 16, 0, 0); } while (0)
; #define PG8_LDA(dst, b, h) do { _Pragma("unroll") for (int m = 0; m < 4; ++m) _Pragma("unroll") for (int k = 0; k < 2; ++k) dst[m][k] = *(const PG8_LAS bf16x8*)(lds + PG8_SA(b, h) + aoff + m * 2048 + k * 1024); } while (0)
; #define PG8_LDB(dst, b, h) do { _Pragma("unroll") for (int n = 0; n < 2; ++n) _Pragma("unroll") for (int k = 0; k < 2; ++k) dst[n][k] = *(const PG8_LAS bf16x8*)(lds + PG8_SB(b, h) + boff + n * 2048 + k * 1024); } while (0)
; #define PG8_MMA(ai, bj, At, Bt) do { __builtin_amdgcn_s_setprio(1); _Pragma("unroll") for (int m = 0; m < 4; ++m) _Pragma("unroll") for (int n = 0; n < 2; ++n) _Pragma("unroll") for (int k = 0; k < 2; ++k) \
;         acc[ai][bj][m][n] = __builtin_amdgcn_mfma_f32_16x16x32_bf16(Bt[n][k], At[m][k], acc[ai][bj][m][n], 0, 0, 0); __builtin_amdgcn_s_setprio(0); } while (0)
; #define PG8_WAIT_V(n) asm volatile("s_waitcnt vmcnt(" #n ")" ::: "memory")
; #define PG8_WAIT_L(n) asm volatile("s_waitcnt lgkmcnt(" #n ")" ::: "memory")
; #define PG8_BAR __builtin_amdgcn_s_barrier()
; #define PG8_SCHED __builtin_amdgcn_sched_barrier(0)
; template <class Epi, class Sched, bool ALIGN_EPI = false, bool SP2 = false>
; __device__ __forceinline__ void gemm_phase(PG8_LAS unsigned char* lds, const Gemm g, const Sched& S, const Epi& E) {
;     ...
;             const bool last = (t == nt - 2);
;             const char* a1 = cA + (size_t)(t + 1) * kstep;
;             const char* a2 = last ? nA : cA + (size_t)(t + 2) * kstep; const char* b2 = last ? nB : cB + (size_t)(t + 2) * kstep;
;             const char* a3 = a2 + kstep; const char* b3 = b2 + kstep;
;     ...
;             PG8_LDB(B0, 0, 0); PG8_LDB(B1, 0, 1); PG8_SCHED; PG8_LDA(At, 0, 0); PG8_STAGE(PG8_SA(1, 1), a1 + hstepA, voffA);
;             PG8_WAIT_V(8); PG8_WAIT_L(0); PG8_BAR; PG8_MMA(0, 0, At, B0); PG8_MMA(0, 1, At, B1); PG8_BAR; PG8_SCHED;
;             PG8_LDA(At, 0, 1); PG8_STAGE(PG8_SB(0, 0), b2, voffB); PG8_STAGE(PG8_SB(0, 1), b2 + hstepB, voffB); PG8_STAGE(PG8_SA(0, 0), a2, voffA);
.LBB0_1329:
	ds_read_b128 v[144:147], v155
	ds_read_b128 v[148:151], v155 offset:1024
	ds_read_b128 v[158:161], v155 offset:2048
	ds_read_b128 v[162:165], v155 offset:3072
	ds_read_b128 v[166:169], v156
	ds_read_b128 v[170:173], v156 offset:1024
	ds_read_b128 v[174:177], v156 offset:2048
	ds_read_b128 v[178:181], v156 offset:3072
	s_add_u32 s20, s18, 0x100
	s_addc_u32 s21, s19, 0
	s_cmp_eq_u32 s49, 40
	s_cselect_b32 s25, s5, s21
	s_cselect_b32 s24, s4, s20
	s_cselect_b32 s23, s17, s48
	s_cselect_b32 s22, s16, s47
	v_lshl_add_u64 v[214:215], s[18:19], 0, v[136:137]
	s_add_i32 m0, s34, 0xc000
	ds_read_b128 v[182:185], v157
	ds_read_b128 v[186:189], v157 offset:1024
	ds_read_b128 v[190:193], v157 offset:2048
	ds_read_b128 v[194:197], v157 offset:3072
	ds_read_b128 v[198:201], v157 offset:4096
	ds_read_b128 v[202:205], v157 offset:5120
	ds_read_b128 v[206:209], v157 offset:6144
	ds_read_b128 v[210:213], v157 offset:7168
	global_load_lds_dwordx4 v[214:215], off
	v_lshl_add_u64 v[214:215], s[18:19], 0, v[138:139]
	s_add_i32 m0, s34, 0xe000
	s_nop 0
	global_load_lds_dwordx4 v[214:215], off
	s_waitcnt vmcnt(8)
	s_waitcnt lgkmcnt(0)
	s_barrier
	s_setprio 1
	s_waitcnt lgkmcnt(0)
	v_mfma_f32_16x16x32_bf16 v[124:127], v[144:147], v[182:185], v[124:127]
	v_mfma_f32_16x16x32_bf16 v[120:123], v[158:161], v[182:185], v[120:123]
	v_mfma_f32_16x16x32_bf16 v[112:115], v[144:147], v[190:193], v[112:115]
	v_mfma_f32_16x16x32_bf16 v[104:107], v[158:161], v[190:193], v[104:107]
	v_mfma_f32_16x16x32_bf16 v[92:95], v[144:147], v[198:201], v[92:95]
	v_mfma_f32_16x16x32_bf16 v[88:91], v[158:161], v[198:201], v[88:91]
	v_mfma_f32_16x16x32_bf16 v[80:83], v[144:147], v[206:209], v[80:83]
	v_mfma_f32_16x16x32_bf16 v[72:75], v[158:161], v[206:209], v[72:75]
	v_mfma_f32_16x16x32_bf16 v[124:127], v[148:151], v[186:189], v[124:127]
	v_mfma_f32_16x16x32_bf16 v[120:123], v[162:165], v[186:189], v[120:123]
	v_mfma_f32_16x16x32_bf16 v[112:115], v[148:151], v[194:197], v[112:115]
	v_mfma_f32_16x16x32_bf16 v[104:107], v[162:165], v[194:197], v[104:107]
	v_mfma_f32_16x16x32_bf16 v[92:95], v[148:151], v[202:205], v[92:95]
	v_mfma_f32_16x16x32_bf16 v[88:91], v[162:165], v[202:205], v[88:91]
	v_mfma_f32_16x16x32_bf16 v[80:83], v[148:151], v[210:213], v[80:83]
	v_mfma_f32_16x16x32_bf16 v[72:75], v[162:165], v[210:213], v[72:75]
	s_setprio 0
	s_setprio 1
	v_mfma_f32_16x16x32_bf16 v[116:119], v[166:169], v[182:185], v[116:119]
	v_mfma_f32_16x16x32_bf16 v[108:111], v[174:177], v[182:185], v[108:111]
	v_mfma_f32_16x16x32_bf16 v[100:103], v[166:169], v[190:193], v[100:103]
	v_mfma_f32_16x16x32_bf16 v[96:99], v[174:177], v[190:193], v[96:99]
	v_mfma_f32_16x16x32_bf16 v[84:87], v[166:169], v[198:201], v[84:87]
	v_mfma_f32_16x16x32_bf16 v[76:79], v[174:177], v[198:201], v[76:79]
	v_mfma_f32_16x16x32_bf16 v[68:71], v[166:169], v[206:209], v[68:71]
	v_mfma_f32_16x16x32_bf16 v[64:67], v[174:177], v[206:209], v[64:67]
	v_mfma_f32_16x16x32_bf16 v[116:119], v[170:173], v[186:189], v[116:119]
	v_mfma_f32_16x16x32_bf16 v[108:111], v[178:181], v[186:189], v[108:111]
	v_mfma_f32_16x16x32_bf16 v[100:103], v[170:173], v[194:197], v[100:103]
	v_mfma_f32_16x16x32_bf16 v[96:99], v[178:181], v[194:197], v[96:99]
	v_mfma_f32_16x16x32_bf16 v[84:87], v[170:173], v[202:205], v[84:87]
	v_mfma_f32_16x16x32_bf16 v[76:79], v[178:181], v[202:205], v[76:79]
	v_mfma_f32_16x16x32_bf16 v[68:71], v[170:173], v[210:213], v[68:71]
	v_mfma_f32_16x16x32_bf16 v[64:67], v[178:181], v[210:213], v[64:67]
	s_setprio 0
	s_barrier
	s_add_i32 s18, s41, s33
	v_lshl_add_u64 v[214:215], s[22:23], 0, v[130:131]
	s_mov_b32 m0, s18
	ds_read_b128 v[182:185], v157 offset:16384
	ds_read_b128 v[186:189], v157 offset:17408
	ds_read_b128 v[190:193], v157 offset:18432
	ds_read_b128 v[194:197], v157 offset:19456
	ds_read_b128 v[198:201], v157 offset:20480
	ds_read_b128 v[202:205], v157 offset:21504
	ds_read_b128 v[206:209], v157 offset:22528
	ds_read_b128 v[210:213], v157 offset:23552
	global_load_lds_dwordx4 v[214:215], off
	s_add_i32 m0, s18, 0x2000
	s_add_u32 s18, s22, 0xb0000
	v_lshl_add_u64 v[216:217], s[22:23], 0, v[134:135]
	s_addc_u32 s19, s23, 0
	s_add_i32 s50, s42, s33
	global_load_lds_dwordx4 v[216:217], off
	v_lshl_add_u64 v[218:219], s[18:19], 0, v[130:131]
	s_mov_b32 m0, s50
	v_lshl_add_u64 v[220:221], s[24:25], 0, v[132:133]
	global_load_lds_dwordx4 v[218:219], off
	v_lshl_add_u64 v[218:219], s[18:19], 0, v[134:135]
	s_add_i32 m0, s50, 0x2000
	s_nop 0
	global_load_lds_dwordx4 v[218:219], off
	v_lshl_add_u64 v[218:219], s[24:25], 0, v[128:129]
	s_mov_b32 m0, s34
	s_nop 0
	global_load_lds_dwordx4 v[218:219], off
	s_mov_b32 m0, s35
	s_nop 0
	global_load_lds_dwordx4 v[220:221], off
	s_waitcnt vmcnt(8)
	s_waitcnt lgkmcnt(0)
	s_barrier
; #define PG8_STAGE(bufoff, gbase, voff) do { _Pragma("unroll") for (int _i = 0; _i < 2; ++_i) \
;         __builtin_amdgcn_global_load_lds((const unsigned*)((const char*)(gbase) + (voff)[_i]), (PG8_LAS unsigned*)(lds + (bufoff) + ldsw + _i * 8192), 16, 0, 0); } while (0)
; #define PG8_LDA(dst, b, h) do { _Pragma("unroll") for (int m = 0; m < 4; ++m) _Pragma("unroll") for (int k = 0; k < 2; ++k) dst[m][k] = *(const PG8_LAS bf16x8*)(lds + PG8_SA(b, h) + aoff + m * 2048 + k * 1024); } while (0)
; #define PG8_LDB(dst, b, h) do { _Pragma("unroll") for (int n = 0; n < 2; ++n) _Pragma("unroll") for (int k = 0; k < 2; ++k) dst[n][k] = *(const PG8_LAS bf16x8*)(lds + PG8_SB(b, h) + boff + n * 2048 + k * 1024); } while (0)
; #define PG8_MMA(ai, bj, At, Bt) do { __builtin_amdgcn_s_setprio(1); _Pragma("unroll") for (int m = 0; m < 4; ++m) _Pragma("unroll") for (int n = 0; n < 2; ++n) _Pragma("unroll") for (int k = 0; k < 2; ++k) \
;         acc[ai][bj][m][n] = __builtin_amdgcn_mfma_f32_16x16x32_bf16(Bt[n][k], At[m][k], acc[ai][bj][m][n], 0, 0, 0); __builtin_amdgcn_s_setprio(0); } while (0)
; #define PG8_WAIT_V(n) asm volatile("s_waitcnt vmcnt(" #n ")" ::: "memory")
; #define PG8_WAIT_L(n) asm volatile("s_waitcnt lgkmcnt(" #n ")" ::: "memory")
; #define PG8_BAR __builtin_amdgcn_s_barrier()
; #define PG8_SCHED __builtin_amdgcn_sched_barrier(0)
; template <class Epi, class Sched, bool ALIGN_EPI = false, bool SP2 = false>
; __device__ __forceinline__ void gemm_phase(PG8_LAS unsigned char* lds, const Gemm g, const Sched& S, const Epi& E) {
;     ...
;             PG8_WAIT_V(8); PG8_WAIT_L(0); PG8_BAR; PG8_MMA(1, 0, At, B0); PG8_MMA(1, 1, At, B1); PG8_BAR; PG8_SCHED;
;             PG8_LDB(B0, 1, 0); PG8_LDB(B1, 1, 1); PG8_SCHED; PG8_LDA(At, 1, 0); PG8_STAGE(PG8_SA(0, 1), a2 + hstepA, voffA);
;             PG8_WAIT_V(8); PG8_WAIT_L(0); PG8_BAR; PG8_MMA(0, 0, At, B0); PG8_MMA(0, 1, At, B1); PG8_BAR; PG8_SCHED;
	s_setprio 1
	s_waitcnt lgkmcnt(0)
	v_mfma_f32_16x16x32_bf16 v[60:63], v[144:147], v[182:185], v[60:63]
	v_mfma_f32_16x16x32_bf16 v[56:59], v[158:161], v[182:185], v[56:59]
	v_mfma_f32_16x16x32_bf16 v[48:51], v[144:147], v[190:193], v[48:51]
	v_mfma_f32_16x16x32_bf16 v[40:43], v[158:161], v[190:193], v[40:43]
	v_mfma_f32_16x16x32_bf16 v[28:31], v[144:147], v[198:201], v[28:31]
	v_mfma_f32_16x16x32_bf16 v[24:27], v[158:161], v[198:201], v[24:27]
	v_mfma_f32_16x16x32_bf16 v[20:23], v[144:147], v[206:209], v[20:23]
	v_mfma_f32_16x16x32_bf16 v[12:15], v[158:161], v[206:209], v[12:15]
	v_mfma_f32_16x16x32_bf16 v[60:63], v[148:151], v[186:189], v[60:63]
	v_mfma_f32_16x16x32_bf16 v[56:59], v[162:165], v[186:189], v[56:59]
	v_mfma_f32_16x16x32_bf16 v[48:51], v[148:151], v[194:197], v[48:51]
	v_mfma_f32_16x16x32_bf16 v[40:43], v[162:165], v[194:197], v[40:43]
	v_mfma_f32_16x16x32_bf16 v[28:31], v[148:151], v[202:205], v[28:31]
	v_mfma_f32_16x16x32_bf16 v[24:27], v[162:165], v[202:205], v[24:27]
	v_mfma_f32_16x16x32_bf16 v[20:23], v[148:151], v[210:213], v[20:23]
	v_mfma_f32_16x16x32_bf16 v[12:15], v[162:165], v[210:213], v[12:15]
	s_setprio 0
	s_setprio 1
	v_mfma_f32_16x16x32_bf16 v[52:55], v[166:169], v[182:185], v[52:55]
	v_mfma_f32_16x16x32_bf16 v[44:47], v[174:177], v[182:185], v[44:47]
	v_mfma_f32_16x16x32_bf16 v[36:39], v[166:169], v[190:193], v[36:39]
	v_mfma_f32_16x16x32_bf16 v[32:35], v[174:177], v[190:193], v[32:35]
	v_mfma_f32_16x16x32_bf16 v[16:19], v[166:169], v[198:201], v[16:19]
	v_mfma_f32_16x16x32_bf16 v[8:11], v[174:177], v[198:201], v[8:11]
	v_mfma_f32_16x16x32_bf16 v[4:7], v[166:169], v[206:209], v[4:7]
	v_mfma_f32_16x16x32_bf16 v[0:3], v[174:177], v[206:209], v[0:3]
	v_mfma_f32_16x16x32_bf16 v[52:55], v[170:173], v[186:189], v[52:55]
	v_mfma_f32_16x16x32_bf16 v[44:47], v[178:181], v[186:189], v[44:47]
	v_mfma_f32_16x16x32_bf16 v[36:39], v[170:173], v[194:197], v[36:39]
	v_mfma_f32_16x16x32_bf16 v[32:35], v[178:181], v[194:197], v[32:35]
	v_mfma_f32_16x16x32_bf16 v[16:19], v[170:173], v[202:205], v[16:19]
	v_mfma_f32_16x16x32_bf16 v[8:11], v[178:181], v[202:205], v[8:11]
	v_mfma_f32_16x16x32_bf16 v[4:7], v[170:173], v[210:213], v[4:7]
	v_mfma_f32_16x16x32_bf16 v[0:3], v[178:181], v[210:213], v[0:3]
	s_setprio 0
	s_barrier
	s_add_i32 s50, 0, 0x18000
	s_add_i32 s51, 0, 0x1c000
	v_add_u32_e32 v162, s50, v153
	v_add_u32_e32 v178, s51, v153
	ds_read_b128 v[144:147], v162
	ds_read_b128 v[148:151], v162 offset:1024
	ds_read_b128 v[158:161], v162 offset:2048
	ds_read_b128 v[162:165], v162 offset:3072
	ds_read_b128 v[166:169], v178
	ds_read_b128 v[170:173], v178 offset:1024
	ds_read_b128 v[174:177], v178 offset:2048
	ds_read_b128 v[178:181], v178 offset:3072
	s_add_u32 s18, s24, 0xb0000
	s_addc_u32 s19, s25, 0
	s_mov_b32 m0, s36
	v_lshl_add_u64 v[222:223], s[18:19], 0, v[128:129]
	ds_read_b128 v[182:185], v157 offset:32768
	ds_read_b128 v[186:189], v157 offset:33792
	ds_read_b128 v[190:193], v157 offset:34816
	ds_read_b128 v[194:197], v157 offset:35840
	ds_read_b128 v[198:201], v157 offset:36864
	ds_read_b128 v[202:205], v157 offset:37888
	ds_read_b128 v[206:209], v157 offset:38912
	ds_read_b128 v[210:213], v157 offset:39936
	global_load_lds_dwordx4 v[222:223], off
	v_lshl_add_u64 v[222:223], s[18:19], 0, v[132:133]
	s_mov_b32 m0, s37
	s_nop 0
	global_load_lds_dwordx4 v[222:223], off
	s_waitcnt vmcnt(8)
	s_waitcnt lgkmcnt(0)
	s_barrier
	s_setprio 1
	s_waitcnt lgkmcnt(0)
	v_mfma_f32_16x16x32_bf16 v[124:127], v[144:147], v[182:185], v[124:127]
	v_mfma_f32_16x16x32_bf16 v[120:123], v[158:161], v[182:185], v[120:123]
	v_mfma_f32_16x16x32_bf16 v[112:115], v[144:147], v[190:193], v[112:115]
	v_mfma_f32_16x16x32_bf16 v[104:107], v[158:161], v[190:193], v[104:107]
	v_mfma_f32_16x16x32_bf16 v[92:95], v[144:147], v[198:201], v[92:95]
	v_mfma_f32_16x16x32_bf16 v[88:91], v[158:161], v[198:201], v[88:91]
	v_mfma_f32_16x16x32_bf16 v[80:83], v[144:147], v[206:209], v[80:83]
	v_mfma_f32_16x16x32_bf16 v[72:75], v[158:161], v[206:209], v[72:75]
	v_mfma_f32_16x16x32_bf16 v[124:127], v[148:151], v[186:189], v[124:127]
	v_mfma_f32_16x16x32_bf16 v[120:123], v[162:165], v[186:189], v[120:123]
	v_mfma_f32_16x16x32_bf16 v[112:115], v[148:151], v[194:197], v[112:115]
	v_mfma_f32_16x16x32_bf16 v[104:107], v[162:165], v[194:197], v[104:107]
	v_mfma_f32_16x16x32_bf16 v[92:95], v[148:151], v[202:205], v[92:95]
	v_mfma_f32_16x16x32_bf16 v[88:91], v[162:165], v[202:205], v[88:91]
	v_mfma_f32_16x16x32_bf16 v[80:83], v[148:151], v[210:213], v[80:83]
	v_mfma_f32_16x16x32_bf16 v[72:75], v[162:165], v[210:213], v[72:75]
	s_setprio 0
	s_setprio 1
	v_mfma_f32_16x16x32_bf16 v[116:119], v[166:169], v[182:185], v[116:119]
	v_mfma_f32_16x16x32_bf16 v[108:111], v[174:177], v[182:185], v[108:111]
	v_mfma_f32_16x16x32_bf16 v[100:103], v[166:169], v[190:193], v[100:103]
	v_mfma_f32_16x16x32_bf16 v[96:99], v[174:177], v[190:193], v[96:99]
	v_mfma_f32_16x16x32_bf16 v[84:87], v[166:169], v[198:201], v[84:87]
	v_mfma_f32_16x16x32_bf16 v[76:79], v[174:177], v[198:201], v[76:79]
	v_mfma_f32_16x16x32_bf16 v[68:71], v[166:169], v[206:209], v[68:71]
	v_mfma_f32_16x16x32_bf16 v[64:67], v[174:177], v[206:209], v[64:67]
	v_mfma_f32_16x16x32_bf16 v[116:119], v[170:173], v[186:189], v[116:119]
	v_mfma_f32_16x16x32_bf16 v[108:111], v[178:181], v[186:189], v[108:111]
	v_mfma_f32_16x16x32_bf16 v[100:103], v[170:173], v[194:197], v[100:103]
	v_mfma_f32_16x16x32_bf16 v[96:99], v[178:181], v[194:197], v[96:99]
	v_mfma_f32_16x16x32_bf16 v[84:87], v[170:173], v[202:205], v[84:87]
	v_mfma_f32_16x16x32_bf16 v[76:79], v[178:181], v[202:205], v[76:79]
	v_mfma_f32_16x16x32_bf16 v[68:71], v[170:173], v[210:213], v[68:71]
	v_mfma_f32_16x16x32_bf16 v[64:67], v[178:181], v[210:213], v[64:67]
	s_setprio 0
	s_barrier
; #define PG8_STAGE(bufoff, gbase, voff) do { _Pragma("unroll") for (int _i = 0; _i < 2; ++_i) \
;         __builtin_amdgcn_global_load_lds((const unsigned*)((const char*)(gbase) + (voff)[_i]), (PG8_LAS unsigned*)(lds + (bufoff) + ldsw + _i * 8192), 16, 0, 0); } while (0)
; #define PG8_LDA(dst, b, h) do { _Pragma("unroll") for (int m = 0; m < 4; ++m) _Pragma("unroll") for (int k = 0; k < 2; ++k) dst[m][k] = *(const PG8_LAS bf16x8*)(lds + PG8_SA(b, h) + aoff + m * 2048 + k * 1024); } while (0)
; #define PG8_MMA(ai, bj, At, Bt) do { __builtin_amdgcn_s_setprio(1); _Pragma("unroll") for (int m = 0; m < 4; ++m) _Pragma("unroll") for (int n = 0; n < 2; ++n) _Pragma("unroll") for (int k = 0; k < 2; ++k) \
;         acc[ai][bj][m][n] = __builtin_amdgcn_mfma_f32_16x16x32_bf16(Bt[n][k], At[m][k], acc[ai][bj][m][n], 0, 0, 0); __builtin_amdgcn_s_setprio(0); } while (0)
; #define PG8_WAIT_V(n) asm volatile("s_waitcnt vmcnt(" #n ")" ::: "memory")
; #define PG8_WAIT_L(n) asm volatile("s_waitcnt lgkmcnt(" #n ")" ::: "memory")
; #define PG8_BAR __builtin_amdgcn_s_barrier()
; #define PG8_SCHED __builtin_amdgcn_sched_barrier(0)
; template <class Epi, class Sched, bool ALIGN_EPI = false, bool SP2 = false>
; __device__ __forceinline__ void gemm_phase(PG8_LAS unsigned char* lds, const Gemm g, const Sched& S, const Epi& E) {
;     ...
;         for (int t = 0; t < nt; t += 2) {
;             const bool last = (t == nt - 2);
;     ...
;             PG8_LDA(At, 1, 1); PG8_STAGE(PG8_SB(1, 0), b3, voffB); PG8_STAGE(PG8_SB(1, 1), b3 + hstepB, voffB); PG8_STAGE(PG8_SA(1, 0), a3, voffA);
;             PG8_WAIT_V(8); PG8_WAIT_L(0); PG8_BAR; PG8_MMA(1, 0, At, B0); PG8_MMA(1, 1, At, B1); PG8_BAR; PG8_SCHED;
	s_add_i32 s18, s50, s33
	v_lshl_add_u64 v[214:215], v[214:215], 0, s[12:13]
	s_mov_b32 m0, s18
	ds_read_b128 v[182:185], v157 offset:49152
	ds_read_b128 v[186:189], v157 offset:50176
	ds_read_b128 v[190:193], v157 offset:51200
	ds_read_b128 v[194:197], v157 offset:52224
	ds_read_b128 v[198:201], v157 offset:53248
	ds_read_b128 v[202:205], v157 offset:54272
	ds_read_b128 v[206:209], v157 offset:55296
	ds_read_b128 v[210:213], v157 offset:56320
	global_load_lds_dwordx4 v[214:215], off
	s_add_i32 m0, s18, 0x2000
	s_add_u32 s18, s22, 0xb0080
	v_lshl_add_u64 v[214:215], v[216:217], 0, s[12:13]
	s_addc_u32 s19, s23, 0
	s_add_i32 s22, s51, s33
	global_load_lds_dwordx4 v[214:215], off
	v_lshl_add_u64 v[214:215], s[18:19], 0, v[130:131]
	s_mov_b32 m0, s22
	s_nop 0
	global_load_lds_dwordx4 v[214:215], off
	v_lshl_add_u64 v[214:215], s[18:19], 0, v[134:135]
	s_add_i32 m0, s22, 0x2000
	s_nop 0
	global_load_lds_dwordx4 v[214:215], off
	v_lshl_add_u64 v[214:215], v[218:219], 0, s[12:13]
	s_mov_b32 m0, s39
	s_nop 0
	global_load_lds_dwordx4 v[214:215], off
	v_lshl_add_u64 v[214:215], v[220:221], 0, s[12:13]
	s_mov_b32 m0, s40
	s_nop 0
	global_load_lds_dwordx4 v[214:215], off
	s_waitcnt vmcnt(8)
	s_waitcnt lgkmcnt(0)
	s_barrier
	s_setprio 1
	s_waitcnt lgkmcnt(0)
	v_mfma_f32_16x16x32_bf16 v[60:63], v[144:147], v[182:185], v[60:63]
	v_mfma_f32_16x16x32_bf16 v[56:59], v[158:161], v[182:185], v[56:59]
	v_mfma_f32_16x16x32_bf16 v[48:51], v[144:147], v[190:193], v[48:51]
	v_mfma_f32_16x16x32_bf16 v[40:43], v[158:161], v[190:193], v[40:43]
	v_mfma_f32_16x16x32_bf16 v[28:31], v[144:147], v[198:201], v[28:31]
	v_mfma_f32_16x16x32_bf16 v[24:27], v[158:161], v[198:201], v[24:27]
	v_mfma_f32_16x16x32_bf16 v[20:23], v[144:147], v[206:209], v[20:23]
	v_mfma_f32_16x16x32_bf16 v[12:15], v[158:161], v[206:209], v[12:15]
	v_mfma_f32_16x16x32_bf16 v[60:63], v[148:151], v[186:189], v[60:63]
	v_mfma_f32_16x16x32_bf16 v[56:59], v[162:165], v[186:189], v[56:59]
	v_mfma_f32_16x16x32_bf16 v[48:51], v[148:151], v[194:197], v[48:51]
	v_mfma_f32_16x16x32_bf16 v[40:43], v[162:165], v[194:197], v[40:43]
	v_mfma_f32_16x16x32_bf16 v[28:31], v[148:151], v[202:205], v[28:31]
	v_mfma_f32_16x16x32_bf16 v[24:27], v[162:165], v[202:205], v[24:27]
	v_mfma_f32_16x16x32_bf16 v[20:23], v[148:151], v[210:213], v[20:23]
	v_mfma_f32_16x16x32_bf16 v[12:15], v[162:165], v[210:213], v[12:15]
	s_setprio 0
	s_setprio 1
	v_mfma_f32_16x16x32_bf16 v[52:55], v[166:169], v[182:185], v[52:55]
	v_mfma_f32_16x16x32_bf16 v[44:47], v[174:177], v[182:185], v[44:47]
	v_mfma_f32_16x16x32_bf16 v[36:39], v[166:169], v[190:193], v[36:39]
	v_mfma_f32_16x16x32_bf16 v[32:35], v[174:177], v[190:193], v[32:35]
	v_mfma_f32_16x16x32_bf16 v[16:19], v[166:169], v[198:201], v[16:19]
	v_mfma_f32_16x16x32_bf16 v[8:11], v[174:177], v[198:201], v[8:11]
	v_mfma_f32_16x16x32_bf16 v[4:7], v[166:169], v[206:209], v[4:7]
	v_mfma_f32_16x16x32_bf16 v[0:3], v[174:177], v[206:209], v[0:3]
	v_mfma_f32_16x16x32_bf16 v[52:55], v[170:173], v[186:189], v[52:55]
	v_mfma_f32_16x16x32_bf16 v[44:47], v[178:181], v[186:189], v[44:47]
	v_mfma_f32_16x16x32_bf16 v[36:39], v[170:173], v[194:197], v[36:39]
	v_mfma_f32_16x16x32_bf16 v[32:35], v[178:181], v[194:197], v[32:35]
	v_mfma_f32_16x16x32_bf16 v[16:19], v[170:173], v[202:205], v[16:19]
	v_mfma_f32_16x16x32_bf16 v[8:11], v[178:181], v[202:205], v[8:11]
	v_mfma_f32_16x16x32_bf16 v[4:7], v[170:173], v[210:213], v[4:7]
	v_mfma_f32_16x16x32_bf16 v[0:3], v[178:181], v[210:213], v[0:3]
	s_setprio 0
	s_add_i32 s49, s49, 2
	s_add_u32 s47, s47, 0x100
	s_addc_u32 s48, s48, 0
	s_cmp_gt_u32 s49, 41
	s_mov_b64 s[18:19], s[20:21]
	s_barrier
	s_cbranch_scc0 .LBB0_1329
	s_and_b64 vcc, exec, s[14:15]
	s_cbranch_vccz .LBB0_1332
	s_barrier
